# div->rcp in combine/gdnprep gates; gdnprep GLA-gate LDS reads pipelined; combine sig loop unrolled with batched loads
# speedup vs baseline: 1.0417x; 1.0053x over previous
; __device__ __forceinline__ float bf2f(u16 v) { return __uint_as_float(((unsigned)v) << 16); }
; __device__ __forceinline__ float sigmoidf_(float x) { return 1.f / (1.f + __expf(-x)); }
; __device__ void phase_combine(const P& p, int l, int ntok, float* lds) {
;     ...
;     for (int e = tid; e < 16 * 96; e += NTHR) {
;       int i = e / 96, m = e % 96;
;       sig[e] = sigmoidf_(bf2f(p.projb[(size_t)(r0 + i) * PROJP + O_RG + m]));
;     }
.LBB0_92:
	s_mov_b32 s20, 0x2aaaaaab
	v_mul_hi_i32 v18, v0, s20
	v_lshrrev_b32_e32 v19, 31, v18
	v_ashrrev_i32_e32 v18, 4, v18
	v_add_u32_e32 v20, v18, v19
	s_movk_i32 s20, 0xffa0
	v_mov_b64_e32 v[2:3], s[94:95]
	v_mad_u64_u32 v[18:19], s[22:23], v20, s20, v[0:1]
	v_add_u32_e32 v20, s56, v20
	v_ashrrev_i32_e32 v19, 31, v18
	v_mad_i64_i32 v[2:3], s[22:23], v20, s33, v[2:3]
	v_lshl_add_u64 v[2:3], v[18:19], 1, v[2:3]
	v_add_co_u32_e32 v2, vcc, s75, v2
	s_nop 1
	v_addc_co_u32_e32 v3, vcc, 0, v3, vcc
	global_load_ushort v241, v[2:3], off offset:1216
	v_add_u32_e32 v0, 0x200, v0
	s_mov_b32 s20, 0x2aaaaaab
	v_mul_hi_i32 v18, v0, s20
	v_lshrrev_b32_e32 v19, 31, v18
	v_ashrrev_i32_e32 v18, 4, v18
	v_add_u32_e32 v20, v18, v19
	s_movk_i32 s20, 0xffa0
	v_mov_b64_e32 v[2:3], s[94:95]
	v_mad_u64_u32 v[18:19], s[22:23], v20, s20, v[0:1]
	v_add_u32_e32 v20, s56, v20
	v_ashrrev_i32_e32 v19, 31, v18
	v_mad_i64_i32 v[2:3], s[22:23], v20, s33, v[2:3]
	v_lshl_add_u64 v[2:3], v[18:19], 1, v[2:3]
	v_add_co_u32_e32 v2, vcc, s75, v2
	s_nop 1
	v_addc_co_u32_e32 v3, vcc, 0, v3, vcc
	global_load_ushort v242, v[2:3], off offset:1216
	v_add_u32_e32 v0, 0x200, v0
	s_mov_b32 s20, 0x2aaaaaab
	v_mul_hi_i32 v18, v0, s20
	v_lshrrev_b32_e32 v19, 31, v18
	v_ashrrev_i32_e32 v18, 4, v18
	v_add_u32_e32 v20, v18, v19
	s_movk_i32 s20, 0xffa0
	v_mov_b64_e32 v[2:3], s[94:95]
	v_mad_u64_u32 v[18:19], s[22:23], v20, s20, v[0:1]
	v_add_u32_e32 v20, s56, v20
	v_ashrrev_i32_e32 v19, 31, v18
	v_mad_i64_i32 v[2:3], s[22:23], v20, s33, v[2:3]
	v_lshl_add_u64 v[2:3], v[18:19], 1, v[2:3]
	v_add_co_u32_e32 v2, vcc, s75, v2
	s_nop 1
	v_addc_co_u32_e32 v3, vcc, 0, v3, vcc
	global_load_ushort v243, v[2:3], off offset:1216
	v_add_u32_e32 v0, 0x200, v0
	s_waitcnt vmcnt(0)
	v_lshlrev_b32_e32 v241, 16, v241
	v_mul_f32_e32 v241, 0xbfb8aa3b, v241
	v_exp_f32_e32 v241, v241
	v_lshlrev_b32_e32 v242, 16, v242
	v_mul_f32_e32 v242, 0xbfb8aa3b, v242
	v_exp_f32_e32 v242, v242
	v_lshlrev_b32_e32 v243, 16, v243
	v_mul_f32_e32 v243, 0xbfb8aa3b, v243
	v_exp_f32_e32 v243, v243
	v_add_f32_e32 v241, 1.0, v241
	v_add_f32_e32 v242, 1.0, v242
	v_add_f32_e32 v243, 1.0, v243
	v_rcp_f32_e32 v241, v241
	v_rcp_f32_e32 v242, v242
	v_rcp_f32_e32 v243, v243
	s_nop 0
	ds_write_b32 v1, v241
	v_add_u32_e32 v1, 0x800, v1
	ds_write_b32 v1, v242
	v_add_u32_e32 v1, 0x800, v1
	ds_write_b32 v1, v243
	v_add_u32_e32 v1, 0x800, v1

; __device__ void phase_combine(const P& p, int l, int ntok, float* lds) {
;     ...
;     for (int i0 = 0; i0 < 16; i0 += 4) {
;       float sf[4], sb[4];
;       unsigned y0[4], y1[4], a0[4], a1[4], a2[4], a3[4], vc[4], vp[4], vn[4], g0r[4], g1r[4], cbr[4], ucc[6], uch[6];
; #pragma unroll
;       for (int i = 0; i < 4; ++i) {
;         int row = r0 + i0 + i, t = tb + i0 + i;
;         y0[i] = or0[(size_t)row * 512 + tid]; y1[i] = or1[(size_t)row * 512 + tid];
;         const u16* pv = p.projb + (size_t)row * PROJP + O_RKV + 1024 + tid;
;         vc[i] = pv[0]; vp[i] = pv[t > 0 ? -PROJP : 0]; vn[i] = pv[t < T - 1 ? PROJP : 0];
;         sf[i] = p.sbon[(size_t)row * 8 + wv]; sb[i] = p.sbon[(size_t)NT * 8 + (size_t)row * 8 + wv];
;         size_t ob = (size_t)row * 512 + hh * 128 + lane;
;         a0[i] = om0[ob]; a1[i] = om1[ob]; a2[i] = om0[ob + 64]; a3[i] = om1[ob + 64];
;         const u16* pg = p.projb + (size_t)row * PROJP + gch;
;         g0r[i] = pg[0]; g1r[i] = pg[64];
;         cbr[i] = p.projb[(size_t)row * PROJP + O_CB + tid];
;       }
;       {
;         const u16* pc = p.projb + (size_t)(r0 + i0) * PROJP;
; #pragma unroll
;         for (int j = 0; j < 6; ++j) {
;           int t = tb + i0 + j - 1;
;           int off = (t < 0 ? 0 : (t > T - 1 ? T - 1 : t)) - (tb + i0);
;           const u16* pr = pc + (long)off * PROJP;
;           ucc[j] = pr[O_CC + tid]; uch[j] = pr[O_CH + tid];
;         }
;       }
.LBB0_94:
	s_or_b32 s46, s60, s56
	s_ashr_i32 s47, s46, 31
	s_lshl_b64 s[0:1], s[46:47], 9
	s_or_b32 s2, s60, s59
	v_lshl_add_u64 v[0:1], s[0:1], 0, v[4:5]
	s_mul_i32 s20, s46, 0x3600
	v_lshlrev_b64 v[0:1], 1, v[0:1]
	s_mul_hi_i32 s3, s46, 0x3600
	s_add_u32 s22, s94, s20
	v_lshl_add_u64 v[2:3], s[34:35], 0, v[0:1]
	v_lshl_add_u64 v[0:1], s[62:63], 0, v[0:1]
	s_addc_u32 s23, s95, s3
	v_lshlrev_b64 v[22:23], 1, v[4:5]
	v_sub_co_u32_e64 v139, s[52:53], s2, 1
	global_load_ushort v201, v[2:3], off
	global_load_ushort v202, v[0:1], off
	v_lshl_add_u64 v[0:1], s[22:23], 0, v[22:23]
	s_and_b64 s[24:25], s[52:53], exec
	v_add_co_u32_e32 v18, vcc, s75, v0
	s_cselect_b32 s25, 0, -1
	s_cselect_b32 s24, 0, 0xffffca00
	s_cmp_lt_u32 s2, s57
	v_lshl_add_u64 v[2:3], v[0:1], 0, s[68:69]
	v_addc_co_u32_e32 v19, vcc, 0, v1, vcc
	s_cselect_b64 s[44:45], -1, 0
	global_load_ushort v199, v[18:19], off offset:64
	v_lshl_add_u64 v[18:19], v[2:3], 0, s[24:25]
	s_and_b64 s[24:25], s[44:45], exec
	s_cselect_b32 s28, 0x3600, 0
	v_lshl_add_u64 v[2:3], v[2:3], 0, s[28:29]
	s_lshl_b64 s[24:25], s[46:47], 5
	global_load_ushort v208, v[18:19], off
	global_load_ushort v210, v[2:3], off
	s_add_u32 s24, s10, s24
	v_mov_b32_e32 v19, s1
	v_or_b32_e32 v18, s0, v10
	s_addc_u32 s25, s11, s25
	v_lshlrev_b64 v[18:19], 1, v[18:19]
	s_or_b32 s50, s46, 1
	v_lshl_add_u64 v[20:21], v[6:7], 0, v[18:19]
	v_lshl_add_u64 v[18:19], v[8:9], 0, v[18:19]
	s_ashr_i32 s51, s50, 31
	global_load_ushort v195, v[20:21], off
	global_load_ushort v193, v[18:19], off
	global_load_ushort v196, v[20:21], off offset:128
	global_load_ushort v194, v[18:19], off offset:128
	global_load_ushort v192, v134, s[22:23]
	global_load_ushort v191, v134, s[22:23] offset:128
	v_add_co_u32_e32 v18, vcc, s96, v0
	s_or_b32 s3, s2, 1
	s_lshl_b64 s[0:1], s[50:51], 9
	s_mul_i32 s22, s50, 0x3600
	v_addc_co_u32_e32 v19, vcc, 0, v1, vcc
	s_mul_hi_i32 s20, s50, 0x3600
	s_add_u32 s22, s94, s22
	global_load_ushort v138, v[18:19], off offset:3136
	v_lshl_add_u64 v[18:19], s[0:1], 0, v[4:5]
	s_addc_u32 s23, s95, s20
	v_lshlrev_b64 v[18:19], 1, v[18:19]
	s_cmp_lt_u32 s3, s57
	v_lshl_add_u64 v[20:21], s[34:35], 0, v[18:19]
	v_lshl_add_u64 v[18:19], s[62:63], 0, v[18:19]
	s_cselect_b64 s[42:43], -1, 0
	v_lshl_add_u64 v[2:3], s[24:25], 0, v[16:17]
	global_load_ushort v212, v[20:21], off
	global_load_ushort v213, v[18:19], off
	v_lshl_add_u64 v[20:21], s[22:23], 0, v[22:23]
	s_and_b64 s[24:25], s[42:43], exec
	v_lshl_add_u64 v[18:19], v[20:21], 0, s[68:69]
	v_add_co_u32_e32 v136, vcc, s75, v20
	s_cselect_b32 s28, 0x3600, 0
	s_nop 0
	v_addc_co_u32_e32 v137, vcc, 0, v21, vcc
	v_lshl_add_u64 v[18:19], v[18:19], 0, s[28:29]
	s_lshl_b64 s[24:25], s[50:51], 5
	global_load_ushort v198, v[136:137], off offset:64
	global_load_ushort v206, v[18:19], off
	s_add_u32 s24, s10, s24
	v_mov_b32_e32 v137, s1
	v_or_b32_e32 v136, s0, v10
	s_addc_u32 s25, s11, s25
	v_lshlrev_b64 v[136:137], 1, v[136:137]
	s_or_b32 s48, s46, 2
	v_lshl_add_u64 v[140:141], v[6:7], 0, v[136:137]
	v_lshl_add_u64 v[136:137], v[8:9], 0, v[136:137]
	s_ashr_i32 s49, s48, 31
	global_load_ushort v167, v[140:141], off
	global_load_ushort v165, v[136:137], off
	global_load_ushort v190, v[140:141], off offset:128
	global_load_ushort v166, v[136:137], off offset:128
	global_load_ushort v164, v134, s[22:23]
	global_load_ushort v163, v134, s[22:23] offset:128
	v_add_co_u32_e32 v20, vcc, s96, v20
	s_or_b32 s23, s2, 2
	s_lshl_b64 s[0:1], s[48:49], 9
	s_mul_i32 s22, s48, 0x3600
	v_lshl_add_u64 v[18:19], s[24:25], 0, v[16:17]
	v_addc_co_u32_e32 v21, vcc, 0, v21, vcc
	s_mul_hi_i32 s20, s48, 0x3600
	s_add_u32 s24, s94, s22
	global_load_ushort v137, v[20:21], off offset:3136
	v_lshl_add_u64 v[20:21], s[0:1], 0, v[4:5]
	s_addc_u32 s25, s95, s20
	v_lshlrev_b64 v[20:21], 1, v[20:21]
	s_cmp_lt_u32 s23, s57
	v_lshl_add_u64 v[140:141], s[34:35], 0, v[20:21]
	v_lshl_add_u64 v[20:21], s[62:63], 0, v[20:21]
	s_cselect_b64 s[40:41], -1, 0
	global_load_ushort v209, v[140:141], off
	global_load_ushort v211, v[20:21], off
	v_lshl_add_u64 v[140:141], s[24:25], 0, v[22:23]
	s_and_b64 s[26:27], s[40:41], exec
	v_lshl_add_u64 v[20:21], v[140:141], 0, s[68:69]
	v_add_co_u32_e32 v142, vcc, s75, v140
	s_cselect_b32 s28, 0x3600, 0
	s_lshl_b64 s[26:27], s[48:49], 5
	v_addc_co_u32_e32 v143, vcc, 0, v141, vcc
	v_lshl_add_u64 v[20:21], v[20:21], 0, s[28:29]
	s_add_u32 s26, s10, s26
	global_load_ushort v197, v[142:143], off offset:64
	global_load_ushort v204, v[20:21], off
	s_addc_u32 s27, s11, s27
	v_mov_b32_e32 v143, s1
	v_or_b32_e32 v142, s0, v10
	s_or_b32 s36, s46, 3
	v_lshlrev_b64 v[142:143], 1, v[142:143]
	v_add_co_u32_e32 v140, vcc, s96, v140
	s_ashr_i32 s37, s36, 31
	v_lshl_add_u64 v[144:145], v[6:7], 0, v[142:143]
	v_lshl_add_u64 v[142:143], v[8:9], 0, v[142:143]
	v_addc_co_u32_e32 v141, vcc, 0, v141, vcc
	s_lshl_b64 s[0:1], s[36:37], 9
	v_lshl_add_u64 v[20:21], s[26:27], 0, v[16:17]
	global_load_ushort v161, v[144:145], off
	global_load_ushort v159, v[142:143], off
	global_load_ushort v162, v[144:145], off offset:128
	global_load_ushort v160, v[142:143], off offset:128
	global_load_ushort v158, v134, s[24:25]
	global_load_ushort v157, v134, s[24:25] offset:128
	global_load_ushort v136, v[140:141], off offset:3136
	s_or_b32 s26, s2, 3
	v_lshl_add_u64 v[140:141], s[0:1], 0, v[4:5]
	s_mul_i32 s22, s36, 0x3600
	v_lshlrev_b64 v[140:141], 1, v[140:141]
	s_mul_hi_i32 s20, s36, 0x3600
	s_add_u32 s24, s94, s22
	v_lshl_add_u64 v[142:143], s[34:35], 0, v[140:141]
	v_lshl_add_u64 v[140:141], s[62:63], 0, v[140:141]
	s_addc_u32 s25, s95, s20
	global_load_ushort v205, v[142:143], off
	global_load_ushort v207, v[140:141], off
; #define PIN8(a, o) asm volatile("" : "+v"(a[o]), "+v"(a[o + 1]), "+v"(a[o + 2]), "+v"(a[o + 3]), "+v"(a[o + 4]), "+v"(a[o + 5]), "+v"(a[o + 6]), "+v"(a[o + 7]))
; #define PIN8(a) asm volatile("" : "+v"(a[0]), "+v"(a[1]), "+v"(a[2]), "+v"(a[3]))
; __device__ void phase_combine(const P& p, int l, int ntok, float* lds) {
;     ...
;         for (int j = 0; j < 6; ++j) {
;           int t = tb + i0 + j - 1;
;           int off = (t < 0 ? 0 : (t > T - 1 ? T - 1 : t)) - (tb + i0);
;           const u16* pr = pc + (long)off * PROJP;
;           ucc[j] = pr[O_CC + tid]; uch[j] = pr[O_CH + tid];
;         }
;       }
;       PIN8(y0); PIN8(y1); PIN8(sf); PIN8(sb); PIN8(a0); PIN8(a1); PIN8(a2); PIN8(a3);
;       PIN8(vc); PIN8(vp); PIN8(vn); PIN8(g0r); PIN8(g1r); PIN8(cbr); PIN8(ucc); PIN8(uch);
;       asm volatile("" : "+v"(ucc[4]), "+v"(ucc[5]), "+v"(uch[4]), "+v"(uch[5]));
;       {
;         float gate[4];
; #pragma unroll
;         for (int i = 0; i < 4; ++i) gate[i] = 0.f;
; #pragma unroll
;         for (int m = 0; m < 96; m += 4) {
; #pragma unroll
;           for (int i = 0; i < 4; ++i) {
;             float4 s = *reinterpret_cast<const float4*>(sig + (i0 + i) * 96 + m);
;             gate[i] += s.x * g2r[m] + s.y * g2r[m + 1] + s.z * g2r[m + 2] + s.w * g2r[m + 3];
;           }
;         }
	v_lshl_add_u64 v[140:141], s[24:25], 0, v[22:23]
	v_add_co_u32_e32 v142, vcc, s75, v140
	s_cmp_lt_u32 s26, s57
	s_nop 0
	v_addc_co_u32_e32 v143, vcc, 0, v141, vcc
	s_cselect_b64 vcc, -1, 0
	s_and_b64 s[30:31], vcc, exec
	v_lshl_add_u64 v[22:23], v[140:141], 0, s[68:69]
	s_cselect_b32 s28, 0x3600, 0
	v_lshl_add_u64 v[22:23], v[22:23], 0, s[28:29]
	global_load_ushort v200, v[142:143], off offset:64
	global_load_ushort v203, v[22:23], off
	v_mov_b32_e32 v143, s1
	v_or_b32_e32 v142, s0, v10
	v_min_i32_e32 v139, s57, v139
	v_lshlrev_b64 v[142:143], 1, v[142:143]
	v_add_co_u32_e64 v140, s[0:1], s96, v140
	v_cndmask_b32_e64 v139, v139, 0, s[52:53]
	v_lshl_add_u64 v[144:145], v[6:7], 0, v[142:143]
	v_lshl_add_u64 v[142:143], v[8:9], 0, v[142:143]
	v_addc_co_u32_e64 v141, s[0:1], 0, v141, s[0:1]
	v_subrev_u32_e32 v139, s2, v139
	global_load_ushort v155, v[144:145], off
	global_load_ushort v153, v[142:143], off
	global_load_ushort v156, v[144:145], off offset:128
	global_load_ushort v154, v[142:143], off offset:128
	global_load_ushort v152, v134, s[24:25]
	global_load_ushort v149, v134, s[24:25] offset:128
	global_load_ushort v135, v[140:141], off offset:3136
	v_mad_i64_i32 v[140:141], s[0:1], v139, s61, v[0:1]
	v_add_co_u32_e64 v140, s[0:1], s78, v140
	s_lshl_b64 s[30:31], s[36:37], 5
	s_nop 0
	v_addc_co_u32_e64 v141, s[0:1], 0, v141, s[0:1]
	global_load_ushort v139, v[140:141], off offset:64
	s_nop 0
	global_load_ushort v140, v[140:141], off offset:1088
	v_mov_b32_e32 v141, s57
	v_sub_u32_e64 v141, s2, v141 clamp
	v_sub_u32_e32 v141, 0, v141
	v_mad_i64_i32 v[142:143], s[0:1], v141, s61, v[0:1]
	v_add_co_u32_e64 v142, s[0:1], s78, v142
	s_add_u32 s30, s10, s30
	s_nop 0
	v_addc_co_u32_e64 v143, s[0:1], 0, v143, s[0:1]
	s_addc_u32 s31, s11, s31
	s_min_u32 s0, s3, s57
	s_sub_i32 s0, s0, s2
	global_load_ushort v147, v[142:143], off offset:64
	global_load_ushort v148, v[142:143], off offset:1088
	v_mad_i64_i32 v[142:143], s[0:1], s0, v179, v[0:1]
	v_add_co_u32_e64 v142, s[0:1], s78, v142
	v_lshl_add_u64 v[22:23], s[30:31], 0, v[16:17]
	s_nop 0
	v_addc_co_u32_e64 v143, s[0:1], 0, v143, s[0:1]
	s_min_u32 s0, s23, s57
	s_sub_i32 s0, s0, s2
	global_load_ushort v150, v[142:143], off offset:64
	global_load_ushort v151, v[142:143], off offset:1088
	v_mad_i64_i32 v[142:143], s[0:1], s0, v179, v[0:1]
	v_add_co_u32_e64 v142, s[0:1], s78, v142
	s_waitcnt vmcnt(25)
	v_mov_b32_e32 v216, v197
	v_addc_co_u32_e64 v143, s[0:1], 0, v143, s[0:1]
	s_min_u32 s0, s26, s57
	s_sub_i32 s0, s0, s2
	global_load_ushort v145, v[142:143], off offset:64
	global_load_ushort v146, v[142:143], off offset:1088
	v_mad_i64_i32 v[142:143], s[0:1], s0, v179, v[0:1]
	v_add_co_u32_e64 v214, s[0:1], s78, v142
	s_nop 1
	v_addc_co_u32_e64 v215, s[0:1], 0, v143, s[0:1]
	s_add_i32 s0, s2, 4
	s_min_u32 s0, s0, s57
	s_sub_i32 s0, s0, s2
	v_mad_i64_i32 v[0:1], s[0:1], s0, v179, v[0:1]
	v_add_co_u32_e64 v0, s[0:1], s78, v0
	global_load_ushort v143, v[214:215], off offset:64
	global_load_ushort v144, v[214:215], off offset:1088
	v_addc_co_u32_e64 v1, s[0:1], 0, v1, s[0:1]
	global_load_ushort v141, v[0:1], off offset:64
	global_load_ushort v142, v[0:1], off offset:1088
	global_load_dword v218, v[2:3], off
	global_load_dword v214, v[22:23], off
	global_load_dword v215, v[20:21], off
	global_load_dword v217, v[18:19], off
	v_add_co_u32_e64 v0, s[0:1], s66, v2
	s_lshl_b64 s[2:3], s[48:49], 12
	s_nop 0
	v_addc_co_u32_e64 v1, s[0:1], 0, v3, s[0:1]
	global_load_dword v219, v[0:1], off
	v_add_co_u32_e64 v0, s[0:1], s66, v22
	s_nop 1
	v_addc_co_u32_e64 v1, s[0:1], 0, v23, s[0:1]
	global_load_dword v22, v[0:1], off
	v_add_co_u32_e64 v0, s[0:1], s66, v20
	s_nop 1
	v_addc_co_u32_e64 v1, s[0:1], 0, v21, s[0:1]
	global_load_dword v23, v[0:1], off
	v_add_co_u32_e64 v0, s[0:1], s66, v18
	v_mov_b32_e32 v21, v198
	s_nop 0
	v_addc_co_u32_e64 v1, s[0:1], 0, v19, s[0:1]
	s_mul_i32 s0, s60, 0x180
	s_add_i32 s0, s0, 0
	global_load_dword v20, v[0:1], off
	v_mov_b32_e32 v18, v199
	v_mov_b32_e32 v19, s0
	s_waitcnt lgkmcnt(0)
	ds_read_b128 v[220:223], v19
	ds_read_b128 v[224:227], v19 offset:384
	ds_read_b128 v[228:231], v19 offset:768
	ds_read_b128 v[232:235], v19 offset:1152
	ds_read_b128 v[244:247], v19 offset:16
	ds_read_b128 v[248:251], v19 offset:400
	ds_read_b128 v[252:255], v19 offset:784
	ds_read_b128 v[0:3], v19 offset:1168
	s_waitcnt lgkmcnt(4)
	v_mul_f32_e32 v221, v91, v221
	v_mul_f32_e32 v225, v91, v225
	v_mul_f32_e32 v229, v91, v229
	v_mul_f32_e32 v233, v91, v233
	v_fmac_f32_e32 v221, v90, v220
	v_fmac_f32_e32 v225, v90, v224
	v_fmac_f32_e32 v229, v90, v228
	v_fmac_f32_e32 v233, v90, v232
	v_fmac_f32_e32 v221, v32, v222
	v_fmac_f32_e32 v225, v32, v226
	v_fmac_f32_e32 v229, v32, v230
	v_fmac_f32_e32 v233, v32, v234
	v_fmac_f32_e32 v221, v92, v223
	v_fmac_f32_e32 v225, v92, v227
	v_fmac_f32_e32 v229, v92, v231
	v_fmac_f32_e32 v233, v92, v235
	v_add_f32_e32 v241, 0, v221
	v_add_f32_e32 v242, 0, v225
	v_add_f32_e32 v243, 0, v229
	v_add_f32_e32 v236, 0, v233
	ds_read_b128 v[220:223], v19 offset:32
	ds_read_b128 v[224:227], v19 offset:416
	ds_read_b128 v[228:231], v19 offset:800
	ds_read_b128 v[232:235], v19 offset:1184
	s_waitcnt lgkmcnt(4)
	v_mul_f32_e32 v245, v78, v245
	v_mul_f32_e32 v249, v78, v249
	v_mul_f32_e32 v253, v78, v253
	v_mul_f32_e32 v1, v78, v1
	v_fmac_f32_e32 v245, v33, v244
	v_fmac_f32_e32 v249, v33, v248
	v_fmac_f32_e32 v253, v33, v252
	v_fmac_f32_e32 v1, v33, v0
	v_fmac_f32_e32 v245, v79, v246
	v_fmac_f32_e32 v249, v79, v250
	v_fmac_f32_e32 v253, v79, v254
	v_fmac_f32_e32 v1, v79, v2
	v_fmac_f32_e32 v245, v93, v247
	v_fmac_f32_e32 v249, v93, v251
	v_fmac_f32_e32 v253, v93, v255
	v_fmac_f32_e32 v1, v93, v3
	v_add_f32_e32 v241, v241, v245
	v_add_f32_e32 v242, v242, v249
	v_add_f32_e32 v243, v243, v253
	v_add_f32_e32 v236, v236, v1
	ds_read_b128 v[244:247], v19 offset:48
	ds_read_b128 v[248:251], v19 offset:432
	ds_read_b128 v[252:255], v19 offset:816
	ds_read_b128 v[0:3], v19 offset:1200
	s_waitcnt lgkmcnt(4)
; __device__ void phase_combine(const P& p, int l, int ntok, float* lds) {
;     ...
;         for (int m = 0; m < 96; m += 4) {
; #pragma unroll
;           for (int i = 0; i < 4; ++i) {
;             float4 s = *reinterpret_cast<const float4*>(sig + (i0 + i) * 96 + m);
;             gate[i] += s.x * g2r[m] + s.y * g2r[m + 1] + s.z * g2r[m + 2] + s.w * g2r[m + 3];
;           }
;         }
	v_mul_f32_e32 v221, v81, v221
	v_mul_f32_e32 v225, v81, v225
	v_mul_f32_e32 v229, v81, v229
	v_mul_f32_e32 v233, v81, v233
	v_fmac_f32_e32 v221, v80, v220
	v_fmac_f32_e32 v225, v80, v224
	v_fmac_f32_e32 v229, v80, v228
	v_fmac_f32_e32 v233, v80, v232
	v_fmac_f32_e32 v221, v82, v222
	v_fmac_f32_e32 v225, v82, v226
	v_fmac_f32_e32 v229, v82, v230
	v_fmac_f32_e32 v233, v82, v234
	v_fmac_f32_e32 v221, v11, v223
	v_fmac_f32_e32 v225, v11, v227
	v_fmac_f32_e32 v229, v11, v231
	v_fmac_f32_e32 v233, v11, v235
	v_add_f32_e32 v241, v241, v221
	v_add_f32_e32 v242, v242, v225
	v_add_f32_e32 v243, v243, v229
	v_add_f32_e32 v236, v236, v233
	ds_read_b128 v[220:223], v19 offset:64
	ds_read_b128 v[224:227], v19 offset:448
	ds_read_b128 v[228:231], v19 offset:832
	ds_read_b128 v[232:235], v19 offset:1216
	s_waitcnt lgkmcnt(4)
	v_mul_f32_e32 v245, v84, v245
	v_mul_f32_e32 v249, v84, v249
	v_mul_f32_e32 v253, v84, v253
	v_mul_f32_e32 v1, v84, v1
	v_fmac_f32_e32 v245, v83, v244
	v_fmac_f32_e32 v249, v83, v248
	v_fmac_f32_e32 v253, v83, v252
	v_fmac_f32_e32 v1, v83, v0
	v_fmac_f32_e32 v245, v85, v246
	v_fmac_f32_e32 v249, v85, v250
	v_fmac_f32_e32 v253, v85, v254
	v_fmac_f32_e32 v1, v85, v2
	v_fmac_f32_e32 v245, v94, v247
	v_fmac_f32_e32 v249, v94, v251
	v_fmac_f32_e32 v253, v94, v255
	v_fmac_f32_e32 v1, v94, v3
	v_add_f32_e32 v241, v241, v245
	v_add_f32_e32 v242, v242, v249
	v_add_f32_e32 v243, v243, v253
	v_add_f32_e32 v236, v236, v1
	ds_read_b128 v[244:247], v19 offset:80
	ds_read_b128 v[248:251], v19 offset:464
	ds_read_b128 v[252:255], v19 offset:848
	ds_read_b128 v[0:3], v19 offset:1232
	s_waitcnt lgkmcnt(4)
	v_mul_f32_e32 v221, v87, v221
	v_mul_f32_e32 v225, v87, v225
	v_mul_f32_e32 v229, v87, v229
	v_mul_f32_e32 v233, v87, v233
	v_fmac_f32_e32 v221, v86, v220
	v_fmac_f32_e32 v225, v86, v224
	v_fmac_f32_e32 v229, v86, v228
	v_fmac_f32_e32 v233, v86, v232
	v_fmac_f32_e32 v221, v88, v222
	v_fmac_f32_e32 v225, v88, v226
	v_fmac_f32_e32 v229, v88, v230
	v_fmac_f32_e32 v233, v88, v234
	v_fmac_f32_e32 v221, v95, v223
	v_fmac_f32_e32 v225, v95, v227
	v_fmac_f32_e32 v229, v95, v231
	v_fmac_f32_e32 v233, v95, v235
	v_add_f32_e32 v241, v241, v221
	v_add_f32_e32 v242, v242, v225
	v_add_f32_e32 v243, v243, v229
	v_add_f32_e32 v236, v236, v233
	ds_read_b128 v[220:223], v19 offset:96
	ds_read_b128 v[224:227], v19 offset:480
	ds_read_b128 v[228:231], v19 offset:864
	ds_read_b128 v[232:235], v19 offset:1248
	s_waitcnt lgkmcnt(4)
	v_mul_f32_e32 v245, v26, v245
	v_mul_f32_e32 v249, v26, v249
	v_mul_f32_e32 v253, v26, v253
	v_mul_f32_e32 v1, v26, v1
	v_fmac_f32_e32 v245, v89, v244
	v_fmac_f32_e32 v249, v89, v248
	v_fmac_f32_e32 v253, v89, v252
	v_fmac_f32_e32 v1, v89, v0
	v_fmac_f32_e32 v245, v27, v246
	v_fmac_f32_e32 v249, v27, v250
	v_fmac_f32_e32 v253, v27, v254
	v_fmac_f32_e32 v1, v27, v2
	v_fmac_f32_e32 v245, v24, v247
	v_fmac_f32_e32 v249, v24, v251
	v_fmac_f32_e32 v253, v24, v255
	v_fmac_f32_e32 v1, v24, v3
	v_add_f32_e32 v241, v241, v245
	v_add_f32_e32 v242, v242, v249
	v_add_f32_e32 v243, v243, v253
	v_add_f32_e32 v236, v236, v1
	ds_read_b128 v[244:247], v19 offset:112
	ds_read_b128 v[248:251], v19 offset:496
	ds_read_b128 v[252:255], v19 offset:880
	ds_read_b128 v[0:3], v19 offset:1264
	s_waitcnt lgkmcnt(4)
	v_mul_f32_e32 v221, v30, v221
	v_mul_f32_e32 v225, v30, v225
	v_mul_f32_e32 v229, v30, v229
	v_mul_f32_e32 v233, v30, v233
	v_fmac_f32_e32 v221, v25, v220
	v_fmac_f32_e32 v225, v25, v224
	v_fmac_f32_e32 v229, v25, v228
	v_fmac_f32_e32 v233, v25, v232
	v_fmac_f32_e32 v221, v31, v222
	v_fmac_f32_e32 v225, v31, v226
	v_fmac_f32_e32 v229, v31, v230
	v_fmac_f32_e32 v233, v31, v234
	v_fmac_f32_e32 v221, v103, v223
	v_fmac_f32_e32 v225, v103, v227
	v_fmac_f32_e32 v229, v103, v231
	v_fmac_f32_e32 v233, v103, v235
	v_add_f32_e32 v241, v241, v221
	v_add_f32_e32 v242, v242, v225
	v_add_f32_e32 v243, v243, v229
	v_add_f32_e32 v236, v236, v233
	ds_read_b128 v[220:223], v19 offset:128
	ds_read_b128 v[224:227], v19 offset:512
	ds_read_b128 v[228:231], v19 offset:896
	ds_read_b128 v[232:235], v19 offset:1280
	s_waitcnt lgkmcnt(4)
	v_mul_f32_e32 v245, v34, v245
	v_mul_f32_e32 v249, v34, v249
	v_mul_f32_e32 v253, v34, v253
	v_mul_f32_e32 v1, v34, v1
	v_fmac_f32_e32 v245, v96, v244
	v_fmac_f32_e32 v249, v96, v248
	v_fmac_f32_e32 v253, v96, v252
	v_fmac_f32_e32 v1, v96, v0
	v_fmac_f32_e32 v245, v35, v246
	v_fmac_f32_e32 v249, v35, v250
	v_fmac_f32_e32 v253, v35, v254
	v_fmac_f32_e32 v1, v35, v2
	v_fmac_f32_e32 v245, v28, v247
	v_fmac_f32_e32 v249, v28, v251
	v_fmac_f32_e32 v253, v28, v255
	v_fmac_f32_e32 v1, v28, v3
	v_add_f32_e32 v241, v241, v245
	v_add_f32_e32 v242, v242, v249
	v_add_f32_e32 v243, v243, v253
	v_add_f32_e32 v236, v236, v1
	ds_read_b128 v[244:247], v19 offset:144
	ds_read_b128 v[248:251], v19 offset:528
	ds_read_b128 v[252:255], v19 offset:912
	ds_read_b128 v[0:3], v19 offset:1296
	s_waitcnt lgkmcnt(4)
	v_mul_f32_e32 v221, v38, v221
	v_mul_f32_e32 v225, v38, v225
	v_mul_f32_e32 v229, v38, v229
	v_mul_f32_e32 v233, v38, v233
	v_fmac_f32_e32 v221, v97, v220
	v_fmac_f32_e32 v225, v97, v224
	v_fmac_f32_e32 v229, v97, v228
	v_fmac_f32_e32 v233, v97, v232
	v_fmac_f32_e32 v221, v39, v222
	v_fmac_f32_e32 v225, v39, v226
	v_fmac_f32_e32 v229, v39, v230
	v_fmac_f32_e32 v233, v39, v234
	v_fmac_f32_e32 v221, v29, v223
	v_fmac_f32_e32 v225, v29, v227
	v_fmac_f32_e32 v229, v29, v231
	v_fmac_f32_e32 v233, v29, v235
	v_add_f32_e32 v241, v241, v221
	v_add_f32_e32 v242, v242, v225
	v_add_f32_e32 v243, v243, v229
	v_add_f32_e32 v236, v236, v233
	ds_read_b128 v[220:223], v19 offset:160
	ds_read_b128 v[224:227], v19 offset:544
	ds_read_b128 v[228:231], v19 offset:928
	ds_read_b128 v[232:235], v19 offset:1312
	s_waitcnt lgkmcnt(4)
; __device__ void phase_combine(const P& p, int l, int ntok, float* lds) {
;     ...
;         for (int m = 0; m < 96; m += 4) {
; #pragma unroll
;           for (int i = 0; i < 4; ++i) {
;             float4 s = *reinterpret_cast<const float4*>(sig + (i0 + i) * 96 + m);
;             gate[i] += s.x * g2r[m] + s.y * g2r[m + 1] + s.z * g2r[m + 2] + s.w * g2r[m + 3];
;           }
;         }
	v_mul_f32_e32 v245, v42, v245
	v_mul_f32_e32 v249, v42, v249
	v_mul_f32_e32 v253, v42, v253
	v_mul_f32_e32 v1, v42, v1
	v_fmac_f32_e32 v245, v98, v244
	v_fmac_f32_e32 v249, v98, v248
	v_fmac_f32_e32 v253, v98, v252
	v_fmac_f32_e32 v1, v98, v0
	v_fmac_f32_e32 v245, v43, v246
	v_fmac_f32_e32 v249, v43, v250
	v_fmac_f32_e32 v253, v43, v254
	v_fmac_f32_e32 v1, v43, v2
	v_fmac_f32_e32 v245, v36, v247
	v_fmac_f32_e32 v249, v36, v251
	v_fmac_f32_e32 v253, v36, v255
	v_fmac_f32_e32 v1, v36, v3
	v_add_f32_e32 v241, v241, v245
	v_add_f32_e32 v242, v242, v249
	v_add_f32_e32 v243, v243, v253
	v_add_f32_e32 v236, v236, v1
	ds_read_b128 v[244:247], v19 offset:176
	ds_read_b128 v[248:251], v19 offset:560
	ds_read_b128 v[252:255], v19 offset:944
	ds_read_b128 v[0:3], v19 offset:1328
	s_waitcnt lgkmcnt(4)
	v_mul_f32_e32 v221, v46, v221
	v_mul_f32_e32 v225, v46, v225
	v_mul_f32_e32 v229, v46, v229
	v_mul_f32_e32 v233, v46, v233
	v_fmac_f32_e32 v221, v99, v220
	v_fmac_f32_e32 v225, v99, v224
	v_fmac_f32_e32 v229, v99, v228
	v_fmac_f32_e32 v233, v99, v232
	v_fmac_f32_e32 v221, v47, v222
	v_fmac_f32_e32 v225, v47, v226
	v_fmac_f32_e32 v229, v47, v230
	v_fmac_f32_e32 v233, v47, v234
	v_fmac_f32_e32 v221, v37, v223
	v_fmac_f32_e32 v225, v37, v227
	v_fmac_f32_e32 v229, v37, v231
	v_fmac_f32_e32 v233, v37, v235
	v_add_f32_e32 v241, v241, v221
	v_add_f32_e32 v242, v242, v225
	v_add_f32_e32 v243, v243, v229
	v_add_f32_e32 v236, v236, v233
	ds_read_b128 v[220:223], v19 offset:192
	ds_read_b128 v[224:227], v19 offset:576
	ds_read_b128 v[228:231], v19 offset:960
	ds_read_b128 v[232:235], v19 offset:1344
	s_waitcnt lgkmcnt(4)
	v_mul_f32_e32 v245, v50, v245
	v_mul_f32_e32 v249, v50, v249
	v_mul_f32_e32 v253, v50, v253
	v_mul_f32_e32 v1, v50, v1
	v_fmac_f32_e32 v245, v100, v244
	v_fmac_f32_e32 v249, v100, v248
	v_fmac_f32_e32 v253, v100, v252
	v_fmac_f32_e32 v1, v100, v0
	v_fmac_f32_e32 v245, v51, v246
	v_fmac_f32_e32 v249, v51, v250
	v_fmac_f32_e32 v253, v51, v254
	v_fmac_f32_e32 v1, v51, v2
	v_fmac_f32_e32 v245, v40, v247
	v_fmac_f32_e32 v249, v40, v251
	v_fmac_f32_e32 v253, v40, v255
	v_fmac_f32_e32 v1, v40, v3
	v_add_f32_e32 v241, v241, v245
	v_add_f32_e32 v242, v242, v249
	v_add_f32_e32 v243, v243, v253
	v_add_f32_e32 v236, v236, v1
	ds_read_b128 v[244:247], v19 offset:208
	ds_read_b128 v[248:251], v19 offset:592
	ds_read_b128 v[252:255], v19 offset:976
	ds_read_b128 v[0:3], v19 offset:1360
	s_waitcnt lgkmcnt(4)
	v_mul_f32_e32 v221, v56, v221
	v_mul_f32_e32 v225, v56, v225
	v_mul_f32_e32 v229, v56, v229
	v_mul_f32_e32 v233, v56, v233
	v_fmac_f32_e32 v221, v101, v220
	v_fmac_f32_e32 v225, v101, v224
	v_fmac_f32_e32 v229, v101, v228
	v_fmac_f32_e32 v233, v101, v232
	v_fmac_f32_e32 v221, v57, v222
	v_fmac_f32_e32 v225, v57, v226
	v_fmac_f32_e32 v229, v57, v230
	v_fmac_f32_e32 v233, v57, v234
	v_fmac_f32_e32 v221, v41, v223
	v_fmac_f32_e32 v225, v41, v227
	v_fmac_f32_e32 v229, v41, v231
	v_fmac_f32_e32 v233, v41, v235
	v_add_f32_e32 v241, v241, v221
	v_add_f32_e32 v242, v242, v225
	v_add_f32_e32 v243, v243, v229
	v_add_f32_e32 v236, v236, v233
	ds_read_b128 v[220:223], v19 offset:224
	ds_read_b128 v[224:227], v19 offset:608
	ds_read_b128 v[228:231], v19 offset:992
	ds_read_b128 v[232:235], v19 offset:1376
	s_waitcnt lgkmcnt(4)
	v_mul_f32_e32 v245, v60, v245
	v_mul_f32_e32 v249, v60, v249
	v_mul_f32_e32 v253, v60, v253
	v_mul_f32_e32 v1, v60, v1
	v_fmac_f32_e32 v245, v102, v244
	v_fmac_f32_e32 v249, v102, v248
	v_fmac_f32_e32 v253, v102, v252
	v_fmac_f32_e32 v1, v102, v0
	v_fmac_f32_e32 v245, v61, v246
	v_fmac_f32_e32 v249, v61, v250
	v_fmac_f32_e32 v253, v61, v254
	v_fmac_f32_e32 v1, v61, v2
	v_fmac_f32_e32 v245, v44, v247
	v_fmac_f32_e32 v249, v44, v251
	v_fmac_f32_e32 v253, v44, v255
	v_fmac_f32_e32 v1, v44, v3
	v_add_f32_e32 v241, v241, v245
	v_add_f32_e32 v242, v242, v249
	v_add_f32_e32 v243, v243, v253
	v_add_f32_e32 v236, v236, v1
	ds_read_b128 v[244:247], v19 offset:240
	ds_read_b128 v[248:251], v19 offset:624
	ds_read_b128 v[252:255], v19 offset:1008
	ds_read_b128 v[0:3], v19 offset:1392
	s_waitcnt lgkmcnt(4)
	v_mul_f32_e32 v221, v48, v221
	v_mul_f32_e32 v225, v48, v225
	v_mul_f32_e32 v229, v48, v229
	v_mul_f32_e32 v233, v48, v233
	v_fmac_f32_e32 v221, v45, v220
	v_fmac_f32_e32 v225, v45, v224
	v_fmac_f32_e32 v229, v45, v228
	v_fmac_f32_e32 v233, v45, v232
	v_fmac_f32_e32 v221, v49, v222
	v_fmac_f32_e32 v225, v49, v226
	v_fmac_f32_e32 v229, v49, v230
	v_fmac_f32_e32 v233, v49, v234
	v_fmac_f32_e32 v221, v54, v223
	v_fmac_f32_e32 v225, v54, v227
	v_fmac_f32_e32 v229, v54, v231
	v_fmac_f32_e32 v233, v54, v235
	v_add_f32_e32 v241, v241, v221
	v_add_f32_e32 v242, v242, v225
	v_add_f32_e32 v243, v243, v229
	v_add_f32_e32 v236, v236, v233
	ds_read_b128 v[220:223], v19 offset:256
	ds_read_b128 v[224:227], v19 offset:640
	ds_read_b128 v[228:231], v19 offset:1024
	ds_read_b128 v[232:235], v19 offset:1408
	s_waitcnt lgkmcnt(4)
	v_mul_f32_e32 v245, v53, v245
	v_mul_f32_e32 v249, v53, v249
	v_mul_f32_e32 v253, v53, v253
	v_mul_f32_e32 v1, v53, v1
	v_fmac_f32_e32 v245, v52, v244
	v_fmac_f32_e32 v249, v52, v248
	v_fmac_f32_e32 v253, v52, v252
	v_fmac_f32_e32 v1, v52, v0
	v_fmac_f32_e32 v245, v58, v246
	v_fmac_f32_e32 v249, v58, v250
	v_fmac_f32_e32 v253, v58, v254
	v_fmac_f32_e32 v1, v58, v2
	v_fmac_f32_e32 v245, v55, v247
	v_fmac_f32_e32 v249, v55, v251
	v_fmac_f32_e32 v253, v55, v255
	v_fmac_f32_e32 v1, v55, v3
	v_add_f32_e32 v241, v241, v245
	v_add_f32_e32 v242, v242, v249
	v_add_f32_e32 v243, v243, v253
	v_add_f32_e32 v236, v236, v1
	ds_read_b128 v[244:247], v19 offset:272
	ds_read_b128 v[248:251], v19 offset:656
	ds_read_b128 v[252:255], v19 offset:1040
	ds_read_b128 v[0:3], v19 offset:1424
	s_waitcnt lgkmcnt(4)
; __device__ void phase_combine(const P& p, int l, int ntok, float* lds) {
;     ...
;         for (int m = 0; m < 96; m += 4) {
; #pragma unroll
;           for (int i = 0; i < 4; ++i) {
;             float4 s = *reinterpret_cast<const float4*>(sig + (i0 + i) * 96 + m);
;             gate[i] += s.x * g2r[m] + s.y * g2r[m + 1] + s.z * g2r[m + 2] + s.w * g2r[m + 3];
;           }
;         }
	v_mul_f32_e32 v221, v64, v221
	v_mul_f32_e32 v225, v64, v225
	v_mul_f32_e32 v229, v64, v229
	v_mul_f32_e32 v233, v64, v233
	v_fmac_f32_e32 v221, v59, v220
	v_fmac_f32_e32 v225, v59, v224
	v_fmac_f32_e32 v229, v59, v228
	v_fmac_f32_e32 v233, v59, v232
	v_fmac_f32_e32 v221, v65, v222
	v_fmac_f32_e32 v225, v65, v226
	v_fmac_f32_e32 v229, v65, v230
	v_fmac_f32_e32 v233, v65, v234
	v_fmac_f32_e32 v221, v62, v223
	v_fmac_f32_e32 v225, v62, v227
	v_fmac_f32_e32 v229, v62, v231
	v_fmac_f32_e32 v233, v62, v235
	v_add_f32_e32 v241, v241, v221
	v_add_f32_e32 v242, v242, v225
	v_add_f32_e32 v243, v243, v229
	v_add_f32_e32 v236, v236, v233
	ds_read_b128 v[220:223], v19 offset:288
	ds_read_b128 v[224:227], v19 offset:672
	ds_read_b128 v[228:231], v19 offset:1056
	ds_read_b128 v[232:235], v19 offset:1440
	s_waitcnt lgkmcnt(4)
	v_mul_f32_e32 v245, v67, v245
	v_mul_f32_e32 v249, v67, v249
	v_mul_f32_e32 v253, v67, v253
	v_mul_f32_e32 v1, v67, v1
	v_fmac_f32_e32 v245, v66, v244
	v_fmac_f32_e32 v249, v66, v248
	v_fmac_f32_e32 v253, v66, v252
	v_fmac_f32_e32 v1, v66, v0
	v_fmac_f32_e32 v245, v70, v246
	v_fmac_f32_e32 v249, v70, v250
	v_fmac_f32_e32 v253, v70, v254
	v_fmac_f32_e32 v1, v70, v2
	v_fmac_f32_e32 v245, v63, v247
	v_fmac_f32_e32 v249, v63, v251
	v_fmac_f32_e32 v253, v63, v255
	v_fmac_f32_e32 v1, v63, v3
	v_add_f32_e32 v241, v241, v245
	v_add_f32_e32 v242, v242, v249
	v_add_f32_e32 v243, v243, v253
	v_add_f32_e32 v236, v236, v1
	ds_read_b128 v[244:247], v19 offset:304
	ds_read_b128 v[248:251], v19 offset:688
	ds_read_b128 v[252:255], v19 offset:1072
	ds_read_b128 v[0:3], v19 offset:1456
	s_waitcnt lgkmcnt(4)
	v_mul_f32_e32 v221, v74, v221
	v_mul_f32_e32 v225, v74, v225
	v_mul_f32_e32 v229, v74, v229
	v_mul_f32_e32 v233, v74, v233
	v_fmac_f32_e32 v221, v71, v220
	v_fmac_f32_e32 v225, v71, v224
	v_fmac_f32_e32 v229, v71, v228
	v_fmac_f32_e32 v233, v71, v232
	v_fmac_f32_e32 v221, v75, v222
	v_fmac_f32_e32 v225, v75, v226
	v_fmac_f32_e32 v229, v75, v230
	v_fmac_f32_e32 v233, v75, v234
	v_fmac_f32_e32 v221, v68, v223
	v_fmac_f32_e32 v225, v68, v227
	v_fmac_f32_e32 v229, v68, v231
	v_fmac_f32_e32 v233, v68, v235
	v_add_f32_e32 v241, v241, v221
	v_add_f32_e32 v242, v242, v225
	v_add_f32_e32 v243, v243, v229
	v_add_f32_e32 v236, v236, v233
	ds_read_b128 v[220:223], v19 offset:320
	ds_read_b128 v[224:227], v19 offset:704
	ds_read_b128 v[228:231], v19 offset:1088
	ds_read_b128 v[232:235], v19 offset:1472
	s_waitcnt lgkmcnt(4)
	v_mul_f32_e32 v245, v105, v245
	v_mul_f32_e32 v249, v105, v249
	v_mul_f32_e32 v253, v105, v253
	v_mul_f32_e32 v1, v105, v1
	v_fmac_f32_e32 v245, v104, v244
	v_fmac_f32_e32 v249, v104, v248
	v_fmac_f32_e32 v253, v104, v252
	v_fmac_f32_e32 v1, v104, v0
	v_fmac_f32_e32 v245, v106, v246
	v_fmac_f32_e32 v249, v106, v250
	v_fmac_f32_e32 v253, v106, v254
	v_fmac_f32_e32 v1, v106, v2
	v_fmac_f32_e32 v245, v69, v247
	v_fmac_f32_e32 v249, v69, v251
	v_fmac_f32_e32 v253, v69, v255
	v_fmac_f32_e32 v1, v69, v3
	v_add_f32_e32 v241, v241, v245
	v_add_f32_e32 v242, v242, v249
	v_add_f32_e32 v243, v243, v253
	v_add_f32_e32 v236, v236, v1
	ds_read_b128 v[244:247], v19 offset:336
	ds_read_b128 v[248:251], v19 offset:720
	ds_read_b128 v[252:255], v19 offset:1104
	ds_read_b128 v[0:3], v19 offset:1488
	s_waitcnt lgkmcnt(4)
	v_mul_f32_e32 v221, v108, v221
	v_mul_f32_e32 v225, v108, v225
	v_mul_f32_e32 v229, v108, v229
	v_mul_f32_e32 v233, v108, v233
	v_fmac_f32_e32 v221, v107, v220
	v_fmac_f32_e32 v225, v107, v224
	v_fmac_f32_e32 v229, v107, v228
	v_fmac_f32_e32 v233, v107, v232
	v_fmac_f32_e32 v221, v109, v222
	v_fmac_f32_e32 v225, v109, v226
	v_fmac_f32_e32 v229, v109, v230
	v_fmac_f32_e32 v233, v109, v234
	v_fmac_f32_e32 v221, v72, v223
	v_fmac_f32_e32 v225, v72, v227
	v_fmac_f32_e32 v229, v72, v231
	v_fmac_f32_e32 v233, v72, v235
	v_add_f32_e32 v241, v241, v221
	v_add_f32_e32 v242, v242, v225
	v_add_f32_e32 v243, v243, v229
	v_add_f32_e32 v236, v236, v233
	ds_read_b128 v[220:223], v19 offset:352
	ds_read_b128 v[224:227], v19 offset:736
	ds_read_b128 v[228:231], v19 offset:1120
	ds_read_b128 v[232:235], v19 offset:1504
	s_waitcnt lgkmcnt(4)
	v_mul_f32_e32 v245, v111, v245
	v_mul_f32_e32 v249, v111, v249
	v_mul_f32_e32 v253, v111, v253
	v_mul_f32_e32 v1, v111, v1
	v_fmac_f32_e32 v245, v110, v244
	v_fmac_f32_e32 v249, v110, v248
	v_fmac_f32_e32 v253, v110, v252
	v_fmac_f32_e32 v1, v110, v0
	v_fmac_f32_e32 v245, v112, v246
	v_fmac_f32_e32 v249, v112, v250
	v_fmac_f32_e32 v253, v112, v254
	v_fmac_f32_e32 v1, v112, v2
	v_fmac_f32_e32 v245, v73, v247
	v_fmac_f32_e32 v249, v73, v251
	v_fmac_f32_e32 v253, v73, v255
	v_fmac_f32_e32 v1, v73, v3
	v_add_f32_e32 v241, v241, v245
	v_add_f32_e32 v242, v242, v249
	v_add_f32_e32 v243, v243, v253
	v_add_f32_e32 v236, v236, v1
	ds_read_b128 v[244:247], v19 offset:368
	ds_read_b128 v[248:251], v19 offset:752
	ds_read_b128 v[252:255], v19 offset:1136
	ds_read_b128 v[0:3], v19 offset:1520
	s_waitcnt lgkmcnt(4)
	v_mul_f32_e32 v221, v77, v221
	v_mul_f32_e32 v225, v77, v225
	v_mul_f32_e32 v229, v77, v229
	v_mul_f32_e32 v233, v77, v233
	v_fmac_f32_e32 v221, v76, v220
	v_fmac_f32_e32 v225, v76, v224
	v_fmac_f32_e32 v229, v76, v228
	v_fmac_f32_e32 v233, v76, v232
	v_fmac_f32_e32 v221, v113, v222
	v_fmac_f32_e32 v225, v113, v226
	v_fmac_f32_e32 v229, v113, v230
	v_fmac_f32_e32 v233, v113, v234
	v_fmac_f32_e32 v221, v116, v223
	v_fmac_f32_e32 v225, v116, v227
	v_fmac_f32_e32 v229, v116, v231
	v_fmac_f32_e32 v233, v116, v235
	v_add_f32_e32 v241, v241, v221
	v_add_f32_e32 v242, v242, v225
	v_add_f32_e32 v243, v243, v229
	v_add_f32_e32 v236, v236, v233
	s_waitcnt lgkmcnt(0)
; __device__ __forceinline__ float bf2f(u16 v) { return __uint_as_float(((unsigned)v) << 16); }
; __device__ __forceinline__ float red16(float v) { v = red8(v); v += dpp_f<0x140>(v); return v; }
; __device__ __forceinline__ float wave_sum_b(float v) {
;   v = red16(v);
;   v += __int_as_float(__builtin_amdgcn_update_dpp(0, __float_as_int(v), 0x142, 0xa, 0xf, false));
;   v += __int_as_float(__builtin_amdgcn_update_dpp(0, __float_as_int(v), 0x143, 0xc, 0xf, false));
;   return rdlane(v, 63);
; }
; __device__ void phase_combine(const P& p, int l, int ntok, float* lds) {
;     ...
; #pragma unroll
;         for (int i = 0; i < 4; ++i) {
;           int row = r0 + i0 + i, t = tb + i0 + i;
;           float yv = bf2f((u16)y0[i]) + bf2f((u16)y1[i]);
;           float mean = wave_sum_b(yv) * (1.f / 64.f);
;           float d = yv - mean;
;           float var = wave_sum_b(d * d) * (1.f / 64.f);
;           float yn = d * rsqrtf(var + 64e-5f) * gnw + gnb;
;           float v_c = bf2f((u16)vc[i]), v_p = t > 0 ? bf2f((u16)vp[i]) : 0.f, v_n = t < T - 1 ? bf2f((u16)vn[i]) : 0.f;
;           float vf = v_c + (v_p - v_c) * muvf, vb = v_c + (v_n - v_c) * muvb;
;           float bonus = sf[i] * vf + sb[i] * vb;
;           p.nbuf[(size_t)row * D + 1536 + tid] = f2bf((yn + bonus) * gate[i]);
;         }
	v_mul_f32_e32 v245, v115, v245
	v_mul_f32_e32 v249, v115, v249
	v_mul_f32_e32 v253, v115, v253
	v_mul_f32_e32 v1, v115, v1
	v_fmac_f32_e32 v245, v114, v244
	v_fmac_f32_e32 v249, v114, v248
	v_fmac_f32_e32 v253, v114, v252
	v_fmac_f32_e32 v1, v114, v0
	v_fmac_f32_e32 v245, v117, v246
	v_fmac_f32_e32 v249, v117, v250
	v_fmac_f32_e32 v253, v117, v254
	v_fmac_f32_e32 v1, v117, v2
	v_fmac_f32_e32 v245, v118, v247
	v_fmac_f32_e32 v249, v118, v251
	v_fmac_f32_e32 v253, v118, v255
	v_fmac_f32_e32 v1, v118, v3
	v_add_f32_e32 v221, v241, v245
	v_add_f32_e32 v222, v242, v249
	v_add_f32_e32 v223, v243, v253
	v_add_f32_e32 v0, v236, v1
	s_waitcnt vmcnt(30)
	s_waitcnt vmcnt(29)
	s_waitcnt vmcnt(4)
	s_waitcnt vmcnt(0)
	v_lshlrev_b32_e32 v197, 16, v197
	v_lshlrev_b32_e32 v192, 16, v192
	v_lshlrev_b32_e32 v164, 16, v164
	v_lshlrev_b32_e32 v158, 16, v158
	v_lshlrev_b32_e32 v152, 16, v152
	v_lshlrev_b32_e32 v138, 16, v138
	v_lshlrev_b32_e32 v1, 16, v201
	v_lshlrev_b32_e32 v2, 16, v202
	v_add_f32_e32 v1, v2, v1
	v_mov_b32_e32 v3, v129
	s_nop 0
	v_add_f32_dpp v2, v1, v1 quad_perm:[1,0,3,2] row_mask:0xf bank_mask:0xf bound_ctrl:1
	s_nop 1
	v_add_f32_dpp v2, v2, v2 quad_perm:[2,3,0,1] row_mask:0xf bank_mask:0xf bound_ctrl:1
	s_nop 1
	v_add_f32_dpp v2, v2, v2 row_half_mirror row_mask:0xf bank_mask:0xf bound_ctrl:1
	s_nop 1
	v_add_f32_dpp v2, v2, v2 row_mirror row_mask:0xf bank_mask:0xf bound_ctrl:1
	s_nop 1
	v_mov_b32_dpp v3, v2 row_bcast:15 row_mask:0xa bank_mask:0xf
	v_add_f32_e32 v2, v2, v3
	v_mov_b32_e32 v3, v129
	s_nop 1
	v_mov_b32_dpp v3, v2 row_bcast:31 row_mask:0xc bank_mask:0xf
	v_add_f32_e32 v2, v2, v3
	v_mov_b32_e32 v3, v129
	v_readlane_b32 s0, v2, 63
	s_nop 1
	v_fmac_f32_e32 v1, s0, v180
	v_mul_f32_e32 v2, v1, v1
	s_nop 1
	v_mov_b32_dpp v2, v2 quad_perm:[1,0,3,2] row_mask:0xf bank_mask:0xf bound_ctrl:1
	v_fmac_f32_e32 v2, v1, v1
	s_nop 1
	v_add_f32_dpp v2, v2, v2 quad_perm:[2,3,0,1] row_mask:0xf bank_mask:0xf bound_ctrl:1
	s_nop 1
	v_add_f32_dpp v2, v2, v2 row_half_mirror row_mask:0xf bank_mask:0xf bound_ctrl:1
	s_nop 1
	v_add_f32_dpp v2, v2, v2 row_mirror row_mask:0xf bank_mask:0xf bound_ctrl:1
	s_nop 1
	v_mov_b32_dpp v3, v2 row_bcast:15 row_mask:0xa bank_mask:0xf
	v_add_f32_e32 v2, v2, v3
	v_mov_b32_e32 v3, v129
	s_nop 1
	v_mov_b32_dpp v3, v2 row_bcast:31 row_mask:0xc bank_mask:0xf
	v_add_f32_e32 v2, v2, v3
	s_nop 0
	v_readlane_b32 s0, v2, 63
	s_nop 1
	v_fma_f32 v2, s0, v181, v170
	v_cmp_gt_f32_e64 s[0:1], s33, v2
	v_mul_f32_e32 v3, 0x4b800000, v2
	s_nop 0
	v_cndmask_b32_e64 v2, v2, v3, s[0:1]
	v_rsq_f32_e32 v2, v2
	s_nop 0
	v_mul_f32_e32 v3, 0x45800000, v2
	v_cndmask_b32_e64 v2, v2, v3, s[0:1]
	v_mul_f32_e32 v1, v1, v2
	v_lshlrev_b32_e32 v2, 16, v18
	v_lshlrev_b32_e32 v3, 16, v208
	v_lshlrev_b32_e32 v18, 16, v210
	v_cndmask_b32_e64 v3, v3, 0, s[52:53]
	v_cndmask_b32_e64 v18, 0, v18, s[44:45]
	v_sub_f32_e32 v3, v3, v2
	v_sub_f32_e32 v18, v18, v2
	v_fma_f32 v3, v121, v3, v2
	v_fmac_f32_e32 v2, v122, v18
	v_mul_f32_e32 v2, v219, v2
	v_fma_f32 v1, v119, v1, v120
	v_fmac_f32_e32 v2, v218, v3
	v_add_f32_e32 v1, v2, v1
	v_mul_f32_e32 v1, v221, v1
	v_bfe_u32 v2, v1, 16, 1
	s_lshl_b64 s[44:45], s[46:47], 12
	v_add3_u32 v1, v1, v2, s21
	v_lshl_add_u64 v[18:19], v[14:15], 0, s[44:45]
	global_store_short_d16_hi v[18:19], v1, off offset:3072
	v_lshlrev_b32_e32 v1, 16, v212
	v_lshlrev_b32_e32 v2, 16, v213
	v_add_f32_e32 v1, v2, v1
	v_mov_b32_e32 v3, v129
	s_nop 0
	v_add_f32_dpp v2, v1, v1 quad_perm:[1,0,3,2] row_mask:0xf bank_mask:0xf bound_ctrl:1
	s_nop 1
	v_add_f32_dpp v2, v2, v2 quad_perm:[2,3,0,1] row_mask:0xf bank_mask:0xf bound_ctrl:1
	s_nop 1
	v_add_f32_dpp v2, v2, v2 row_half_mirror row_mask:0xf bank_mask:0xf bound_ctrl:1
	s_nop 1
	v_add_f32_dpp v2, v2, v2 row_mirror row_mask:0xf bank_mask:0xf bound_ctrl:1
	s_nop 1
	v_mov_b32_dpp v3, v2 row_bcast:15 row_mask:0xa bank_mask:0xf
	v_add_f32_e32 v2, v2, v3
	v_mov_b32_e32 v3, v129
	s_nop 1
	v_mov_b32_dpp v3, v2 row_bcast:31 row_mask:0xc bank_mask:0xf
	v_add_f32_e32 v2, v2, v3
	v_mov_b32_e32 v3, v129
	v_readlane_b32 s0, v2, 63
	s_nop 1
	v_fmac_f32_e32 v1, s0, v180
	v_mul_f32_e32 v2, v1, v1
	s_nop 1
	v_mov_b32_dpp v2, v2 quad_perm:[1,0,3,2] row_mask:0xf bank_mask:0xf bound_ctrl:1
	v_fmac_f32_e32 v2, v1, v1
	s_nop 1
	v_add_f32_dpp v2, v2, v2 quad_perm:[2,3,0,1] row_mask:0xf bank_mask:0xf bound_ctrl:1
	s_nop 1
	v_add_f32_dpp v2, v2, v2 row_half_mirror row_mask:0xf bank_mask:0xf bound_ctrl:1
	s_nop 1
	v_add_f32_dpp v2, v2, v2 row_mirror row_mask:0xf bank_mask:0xf bound_ctrl:1
	s_nop 1
	v_mov_b32_dpp v3, v2 row_bcast:15 row_mask:0xa bank_mask:0xf
	v_add_f32_e32 v2, v2, v3
	v_mov_b32_e32 v3, v129
	s_nop 1
	v_mov_b32_dpp v3, v2 row_bcast:31 row_mask:0xc bank_mask:0xf
	v_add_f32_e32 v2, v2, v3
	s_nop 0
	v_readlane_b32 s0, v2, 63
	s_nop 1
	v_fma_f32 v2, s0, v181, v170
	v_cmp_gt_f32_e64 s[0:1], s33, v2
	v_mul_f32_e32 v3, 0x4b800000, v2
	s_nop 0
	v_cndmask_b32_e64 v2, v2, v3, s[0:1]
	v_rsq_f32_e32 v2, v2
	s_nop 0
	v_mul_f32_e32 v3, 0x45800000, v2
	v_cndmask_b32_e64 v2, v2, v3, s[0:1]
	v_mul_f32_e32 v1, v1, v2
	v_lshlrev_b32_e32 v2, 16, v21
	v_lshlrev_b32_e32 v21, 16, v206
	v_lshlrev_b32_e32 v3, 16, v199
	v_cndmask_b32_e64 v21, 0, v21, s[42:43]
	v_sub_f32_e32 v3, v3, v2
	v_sub_f32_e32 v21, v21, v2
	v_fma_f32 v3, v121, v3, v2
	v_fmac_f32_e32 v2, v122, v21
	v_mul_f32_e32 v2, v20, v2
	v_fma_f32 v1, v119, v1, v120
	v_fmac_f32_e32 v2, v217, v3
	v_add_f32_e32 v1, v2, v1
	v_mul_f32_e32 v1, v222, v1
	v_bfe_u32 v2, v1, 16, 1
	s_lshl_b64 s[42:43], s[50:51], 12
	v_add3_u32 v1, v1, v2, s21
	v_lshl_add_u64 v[20:21], v[14:15], 0, s[42:43]
	global_store_short_d16_hi v[20:21], v1, off offset:3072
	v_lshlrev_b32_e32 v1, 16, v209
; __device__ __forceinline__ float bf2f(u16 v) { return __uint_as_float(((unsigned)v) << 16); }
; __device__ __forceinline__ float siluf_(float x) { return x / (1.f + __expf(-x)); }
; __device__ __forceinline__ float red16(float v) { v = red8(v); v += dpp_f<0x140>(v); return v; }
; __device__ __forceinline__ float wave_sum_b(float v) {
;   v = red16(v);
;   v += __int_as_float(__builtin_amdgcn_update_dpp(0, __float_as_int(v), 0x142, 0xa, 0xf, false));
;   v += __int_as_float(__builtin_amdgcn_update_dpp(0, __float_as_int(v), 0x143, 0xc, 0xf, false));
;   return rdlane(v, 63);
; }
; __device__ void phase_combine(const P& p, int l, int ntok, float* lds) {
;     ...
; #pragma unroll
;       for (int i = 0; i < 4; ++i) {
;         int row = r0 + i0 + i;
;         float o0 = bf2f((u16)a0[i]) + bf2f((u16)a1[i]), o1 = bf2f((u16)a2[i]) + bf2f((u16)a3[i]);
;         float ss = wave_sum_b(o0 * o0 + o1 * o1);
;         float rstd = rsqrtf(ss * (1.f / 128.f) + 1e-6f);
;         u16* dst = p.nbuf + (size_t)row * D + mixer * 512 + hh * 128 + lane;
;         dst[0] = f2bf(o0 * rstd * ng0 * siluf_(bf2f((u16)g0r[i])));
;         dst[64] = f2bf(o1 * rstd * ng1 * siluf_(bf2f((u16)g1r[i])));
	v_lshlrev_b32_e32 v2, 16, v211
	v_add_f32_e32 v1, v2, v1
	v_mov_b32_e32 v3, v129
	s_nop 0
	v_add_f32_dpp v2, v1, v1 quad_perm:[1,0,3,2] row_mask:0xf bank_mask:0xf bound_ctrl:1
	s_nop 1
	v_add_f32_dpp v2, v2, v2 quad_perm:[2,3,0,1] row_mask:0xf bank_mask:0xf bound_ctrl:1
	s_nop 1
	v_add_f32_dpp v2, v2, v2 row_half_mirror row_mask:0xf bank_mask:0xf bound_ctrl:1
	s_nop 1
	v_add_f32_dpp v2, v2, v2 row_mirror row_mask:0xf bank_mask:0xf bound_ctrl:1
	s_nop 1
	v_mov_b32_dpp v3, v2 row_bcast:15 row_mask:0xa bank_mask:0xf
	v_add_f32_e32 v2, v2, v3
	v_mov_b32_e32 v3, v129
	s_nop 1
	v_mov_b32_dpp v3, v2 row_bcast:31 row_mask:0xc bank_mask:0xf
	v_add_f32_e32 v2, v2, v3
	v_mov_b32_e32 v3, v129
	v_readlane_b32 s0, v2, 63
	s_nop 1
	v_fmac_f32_e32 v1, s0, v180
	v_mul_f32_e32 v2, v1, v1
	s_nop 1
	v_mov_b32_dpp v2, v2 quad_perm:[1,0,3,2] row_mask:0xf bank_mask:0xf bound_ctrl:1
	v_fmac_f32_e32 v2, v1, v1
	s_nop 1
	v_add_f32_dpp v2, v2, v2 quad_perm:[2,3,0,1] row_mask:0xf bank_mask:0xf bound_ctrl:1
	s_nop 1
	v_add_f32_dpp v2, v2, v2 row_half_mirror row_mask:0xf bank_mask:0xf bound_ctrl:1
	s_nop 1
	v_add_f32_dpp v2, v2, v2 row_mirror row_mask:0xf bank_mask:0xf bound_ctrl:1
	s_nop 1
	v_mov_b32_dpp v3, v2 row_bcast:15 row_mask:0xa bank_mask:0xf
	v_add_f32_e32 v2, v2, v3
	v_mov_b32_e32 v3, v129
	s_nop 1
	v_mov_b32_dpp v3, v2 row_bcast:31 row_mask:0xc bank_mask:0xf
	v_add_f32_e32 v2, v2, v3
	s_nop 0
	v_readlane_b32 s0, v2, 63
	s_nop 1
	v_fma_f32 v2, s0, v181, v170
	v_cmp_gt_f32_e64 s[0:1], s33, v2
	v_mul_f32_e32 v3, 0x4b800000, v2
	s_nop 0
	v_cndmask_b32_e64 v2, v2, v3, s[0:1]
	v_rsq_f32_e32 v2, v2
	s_nop 0
	v_mul_f32_e32 v3, 0x45800000, v2
	v_cndmask_b32_e64 v2, v2, v3, s[0:1]
	v_lshlrev_b32_e32 v3, 16, v198
	v_lshlrev_b32_e32 v198, 16, v204
	v_mul_f32_e32 v1, v1, v2
	v_lshlrev_b32_e32 v2, 16, v216
	v_cndmask_b32_e64 v198, 0, v198, s[40:41]
	v_sub_f32_e32 v3, v3, v2
	v_sub_f32_e32 v198, v198, v2
	v_fma_f32 v3, v121, v3, v2
	v_fmac_f32_e32 v2, v122, v198
	v_mul_f32_e32 v2, v23, v2
	v_fma_f32 v1, v119, v1, v120
	v_fmac_f32_e32 v2, v215, v3
	v_add_f32_e32 v1, v2, v1
	v_mul_f32_e32 v1, v223, v1
	v_bfe_u32 v2, v1, 16, 1
	v_add3_u32 v1, v1, v2, s21
	v_lshl_add_u64 v[2:3], v[14:15], 0, s[2:3]
	global_store_short_d16_hi v[2:3], v1, off offset:3072
	v_lshlrev_b32_e32 v1, 16, v205
	v_lshlrev_b32_e32 v23, 16, v207
	v_add_f32_e32 v1, v23, v1
	v_mov_b32_e32 v198, v129
	s_nop 0
	v_add_f32_dpp v23, v1, v1 quad_perm:[1,0,3,2] row_mask:0xf bank_mask:0xf bound_ctrl:1
	s_nop 1
	v_add_f32_dpp v23, v23, v23 quad_perm:[2,3,0,1] row_mask:0xf bank_mask:0xf bound_ctrl:1
	s_nop 1
	v_add_f32_dpp v23, v23, v23 row_half_mirror row_mask:0xf bank_mask:0xf bound_ctrl:1
	s_nop 1
	v_add_f32_dpp v23, v23, v23 row_mirror row_mask:0xf bank_mask:0xf bound_ctrl:1
	s_nop 1
	v_mov_b32_dpp v198, v23 row_bcast:15 row_mask:0xa bank_mask:0xf
	v_add_f32_e32 v23, v23, v198
	v_mov_b32_e32 v198, v129
	s_nop 1
	v_mov_b32_dpp v198, v23 row_bcast:31 row_mask:0xc bank_mask:0xf
	v_add_f32_e32 v23, v23, v198
	v_mov_b32_e32 v198, v129
	v_readlane_b32 s0, v23, 63
	s_nop 1
	v_fmac_f32_e32 v1, s0, v180
	v_mul_f32_e32 v23, v1, v1
	s_nop 1
	v_mov_b32_dpp v23, v23 quad_perm:[1,0,3,2] row_mask:0xf bank_mask:0xf bound_ctrl:1
	v_fmac_f32_e32 v23, v1, v1
	s_nop 1
	v_add_f32_dpp v23, v23, v23 quad_perm:[2,3,0,1] row_mask:0xf bank_mask:0xf bound_ctrl:1
	s_nop 1
	v_add_f32_dpp v23, v23, v23 row_half_mirror row_mask:0xf bank_mask:0xf bound_ctrl:1
	s_nop 1
	v_add_f32_dpp v23, v23, v23 row_mirror row_mask:0xf bank_mask:0xf bound_ctrl:1
	s_nop 1
	v_mov_b32_dpp v198, v23 row_bcast:15 row_mask:0xa bank_mask:0xf
	v_add_f32_e32 v23, v23, v198
	v_mov_b32_e32 v198, v129
	s_nop 1
	v_mov_b32_dpp v198, v23 row_bcast:31 row_mask:0xc bank_mask:0xf
	v_add_f32_e32 v23, v23, v198
	s_nop 0
	v_readlane_b32 s0, v23, 63
	s_nop 1
	v_fma_f32 v23, s0, v181, v170
	v_cmp_gt_f32_e64 s[0:1], s33, v23
	v_mul_f32_e32 v198, 0x4b800000, v23
	s_nop 0
	v_cndmask_b32_e64 v23, v23, v198, s[0:1]
	v_rsq_f32_e32 v23, v23
	s_nop 0
	v_mul_f32_e32 v198, 0x45800000, v23
	v_cndmask_b32_e64 v23, v23, v198, s[0:1]
	v_lshlrev_b32_e32 v198, 16, v203
	v_mul_f32_e32 v1, v1, v23
	v_lshlrev_b32_e32 v23, 16, v200
	v_cndmask_b32_e32 v198, 0, v198, vcc
	v_sub_f32_e32 v197, v197, v23
	v_sub_f32_e32 v198, v198, v23
	v_fma_f32 v197, v121, v197, v23
	v_fmac_f32_e32 v23, v122, v198
	v_mul_f32_e32 v22, v22, v23
	v_fma_f32 v1, v119, v1, v120
	v_fmac_f32_e32 v22, v214, v197
	v_add_f32_e32 v1, v22, v1
	v_mul_f32_e32 v0, v0, v1
	v_bfe_u32 v1, v0, 16, 1
	s_lshl_b64 s[0:1], s[36:37], 12
	v_add3_u32 v22, v0, v1, s21
	v_lshl_add_u64 v[0:1], v[14:15], 0, s[0:1]
	global_store_short_d16_hi v[0:1], v22, off offset:3072
	v_lshlrev_b32_e32 v22, 16, v195
	v_lshlrev_b32_e32 v23, 16, v196
	v_lshlrev_b32_e32 v196, 16, v193
	v_lshlrev_b32_e32 v197, 16, v194
	v_pk_add_f32 v[22:23], v[22:23], v[196:197]
	v_mul_f32_e32 v196, 0xbfb8aa3b, v192
	v_pk_mul_f32 v[194:195], v[22:23], v[22:23]
	v_exp_f32_e32 v196, v196
	v_add_f32_e32 v193, v194, v195
	v_mov_b32_e32 v194, v129
	v_add_f32_e32 v196, 1.0, v196
	v_add_f32_dpp v193, v193, v193 quad_perm:[1,0,3,2] row_mask:0xf bank_mask:0xf bound_ctrl:1
	s_nop 0
	s_nop 0
	v_add_f32_dpp v193, v193, v193 quad_perm:[2,3,0,1] row_mask:0xf bank_mask:0xf bound_ctrl:1
	s_nop 0
	s_nop 0
	v_add_f32_dpp v193, v193, v193 row_half_mirror row_mask:0xf bank_mask:0xf bound_ctrl:1
	s_nop 0
	s_nop 0
	v_add_f32_dpp v193, v193, v193 row_mirror row_mask:0xf bank_mask:0xf bound_ctrl:1
	s_nop 0
	s_nop 0
	v_mov_b32_dpp v194, v193 row_bcast:15 row_mask:0xa bank_mask:0xf
	v_add_f32_e32 v193, v193, v194
	v_mov_b32_e32 v194, v129
	s_nop 1
	v_mov_b32_dpp v194, v193 row_bcast:31 row_mask:0xc bank_mask:0xf
; __device__ __forceinline__ float bf2f(u16 v) { return __uint_as_float(((unsigned)v) << 16); }
; __device__ __forceinline__ float siluf_(float x) { return x / (1.f + __expf(-x)); }
; __device__ void phase_combine(const P& p, int l, int ntok, float* lds) {
;     ...
; #pragma unroll
;       for (int i = 0; i < 4; ++i) {
;         int row = r0 + i0 + i;
;         float o0 = bf2f((u16)a0[i]) + bf2f((u16)a1[i]), o1 = bf2f((u16)a2[i]) + bf2f((u16)a3[i]);
;         float ss = wave_sum_b(o0 * o0 + o1 * o1);
;         float rstd = rsqrtf(ss * (1.f / 128.f) + 1e-6f);
;         u16* dst = p.nbuf + (size_t)row * D + mixer * 512 + hh * 128 + lane;
;         dst[0] = f2bf(o0 * rstd * ng0 * siluf_(bf2f((u16)g0r[i])));
;         dst[64] = f2bf(o1 * rstd * ng1 * siluf_(bf2f((u16)g1r[i])));
;       }
	v_add_f32_e32 v193, v193, v194
	s_nop 0
	v_readlane_b32 s20, v193, 63
	s_nop 1
	v_fma_f32 v193, s20, v182, v169
	v_cmp_gt_f32_e32 vcc, s33, v193
	v_mul_f32_e32 v194, 0x4b800000, v193
	s_nop 0
	v_cndmask_b32_e32 v193, v193, v194, vcc
	v_rsq_f32_e32 v193, v193
	s_nop 0
	v_mul_f32_e32 v194, 0x45800000, v193
	v_cndmask_b32_e32 v193, v193, v194, vcc
	v_mul_f32_e32 v22, v22, v193
	v_mul_f32_e32 v22, v126, v22
	v_rcp_f32_e32 v197, v196
	s_nop 0
	v_mul_f32_e32 v192, v192, v197
	v_mul_f32_e32 v22, v192, v22
	v_bfe_u32 v192, v22, 16, 1
	v_lshl_add_u64 v[194:195], v[12:13], 0, s[44:45]
	v_add3_u32 v22, v22, v192, s21
	global_store_short_d16_hi v[194:195], v22, off
	v_mul_f32_e32 v22, v23, v193
	v_lshlrev_b32_e32 v23, 16, v191
	v_mul_f32_e32 v191, 0xbfb8aa3b, v23
	v_exp_f32_e32 v191, v191
	v_mul_f32_e32 v22, v127, v22
	v_add_f32_e32 v191, 1.0, v191
	s_nop 0
	v_rcp_f32_e32 v192, v191
	s_nop 0
	v_mul_f32_e32 v23, v23, v192
	v_mul_f32_e32 v22, v23, v22
	v_bfe_u32 v23, v22, 16, 1
	v_add3_u32 v22, v22, v23, s21
	global_store_short_d16_hi v[194:195], v22, off offset:128
	v_lshlrev_b32_e32 v22, 16, v167
	v_lshlrev_b32_e32 v23, 16, v190
	v_lshlrev_b32_e32 v190, 16, v165
	v_lshlrev_b32_e32 v191, 16, v166
	v_pk_add_f32 v[22:23], v[22:23], v[190:191]
	v_mul_f32_e32 v190, 0xbfb8aa3b, v164
	v_pk_mul_f32 v[166:167], v[22:23], v[22:23]
	v_exp_f32_e32 v190, v190
	v_add_f32_e32 v165, v166, v167
	v_mov_b32_e32 v166, v129
	v_add_f32_e32 v190, 1.0, v190
	v_add_f32_dpp v165, v165, v165 quad_perm:[1,0,3,2] row_mask:0xf bank_mask:0xf bound_ctrl:1
	s_nop 0
	s_nop 0
	v_add_f32_dpp v165, v165, v165 quad_perm:[2,3,0,1] row_mask:0xf bank_mask:0xf bound_ctrl:1
	s_nop 0
	s_nop 0
	v_add_f32_dpp v165, v165, v165 row_half_mirror row_mask:0xf bank_mask:0xf bound_ctrl:1
	s_nop 0
	s_nop 0
	v_add_f32_dpp v165, v165, v165 row_mirror row_mask:0xf bank_mask:0xf bound_ctrl:1
	s_nop 0
	s_nop 0
	v_mov_b32_dpp v166, v165 row_bcast:15 row_mask:0xa bank_mask:0xf
	v_add_f32_e32 v165, v165, v166
	v_mov_b32_e32 v166, v129
	s_nop 1
	v_mov_b32_dpp v166, v165 row_bcast:31 row_mask:0xc bank_mask:0xf
	v_add_f32_e32 v165, v165, v166
	s_nop 0
	v_readlane_b32 s20, v165, 63
	s_nop 1
	v_fma_f32 v165, s20, v182, v169
	v_cmp_gt_f32_e32 vcc, s33, v165
	v_mul_f32_e32 v166, 0x4b800000, v165
	s_nop 0
	v_cndmask_b32_e32 v165, v165, v166, vcc
	v_rsq_f32_e32 v165, v165
	s_nop 0
	v_mul_f32_e32 v166, 0x45800000, v165
	v_cndmask_b32_e32 v165, v165, v166, vcc
	v_mul_f32_e32 v22, v22, v165
	v_mul_f32_e32 v22, v126, v22
	v_rcp_f32_e32 v191, v190
	s_nop 0
	v_mul_f32_e32 v164, v164, v191
	v_mul_f32_e32 v22, v164, v22
	v_bfe_u32 v164, v22, 16, 1
	v_lshl_add_u64 v[166:167], v[12:13], 0, s[42:43]
	v_add3_u32 v22, v22, v164, s21
	global_store_short_d16_hi v[166:167], v22, off
	v_mul_f32_e32 v22, v23, v165
	v_lshlrev_b32_e32 v23, 16, v163
	v_mul_f32_e32 v163, 0xbfb8aa3b, v23
	v_exp_f32_e32 v163, v163
	v_mul_f32_e32 v22, v127, v22
	v_add_f32_e32 v163, 1.0, v163
	s_nop 0
	v_rcp_f32_e32 v164, v163
	s_nop 0
	v_mul_f32_e32 v23, v23, v164
	v_mul_f32_e32 v22, v23, v22
	v_bfe_u32 v23, v22, 16, 1
	v_add3_u32 v22, v22, v23, s21
	global_store_short_d16_hi v[166:167], v22, off offset:128
	v_lshlrev_b32_e32 v22, 16, v161
	v_lshlrev_b32_e32 v23, 16, v162
	v_lshlrev_b32_e32 v162, 16, v159
	v_lshlrev_b32_e32 v163, 16, v160
	v_pk_add_f32 v[22:23], v[22:23], v[162:163]
	v_mul_f32_e32 v162, 0xbfb8aa3b, v158
	v_pk_mul_f32 v[160:161], v[22:23], v[22:23]
	v_exp_f32_e32 v162, v162
	v_add_f32_e32 v159, v160, v161
	v_mov_b32_e32 v160, v129
	v_add_f32_e32 v162, 1.0, v162
	v_add_f32_dpp v159, v159, v159 quad_perm:[1,0,3,2] row_mask:0xf bank_mask:0xf bound_ctrl:1
	s_nop 1
	v_add_f32_dpp v159, v159, v159 quad_perm:[2,3,0,1] row_mask:0xf bank_mask:0xf bound_ctrl:1
	s_nop 1
	v_add_f32_dpp v159, v159, v159 row_half_mirror row_mask:0xf bank_mask:0xf bound_ctrl:1
	s_nop 1
	v_add_f32_dpp v159, v159, v159 row_mirror row_mask:0xf bank_mask:0xf bound_ctrl:1
	s_nop 1
	v_mov_b32_dpp v160, v159 row_bcast:15 row_mask:0xa bank_mask:0xf
	v_add_f32_e32 v159, v159, v160
	v_mov_b32_e32 v160, v129
	s_nop 1
	v_mov_b32_dpp v160, v159 row_bcast:31 row_mask:0xc bank_mask:0xf
	v_add_f32_e32 v159, v159, v160
	s_nop 0
	v_readlane_b32 s20, v159, 63
	s_nop 1
	v_fma_f32 v159, s20, v182, v169
	v_cmp_gt_f32_e32 vcc, s33, v159
	v_mul_f32_e32 v160, 0x4b800000, v159
	s_nop 0
	v_cndmask_b32_e32 v159, v159, v160, vcc
	v_rsq_f32_e32 v159, v159
	s_nop 0
	v_mul_f32_e32 v160, 0x45800000, v159
	v_cndmask_b32_e32 v159, v159, v160, vcc
	v_lshl_add_u64 v[160:161], v[12:13], 0, s[2:3]
	v_mul_f32_e32 v22, v22, v159
	v_mul_f32_e32 v22, v126, v22
	v_rcp_f32_e32 v163, v162
	s_nop 0
	v_mul_f32_e32 v158, v158, v163
	v_mul_f32_e32 v22, v158, v22
; __device__ __forceinline__ float bf2f(u16 v) { return __uint_as_float(((unsigned)v) << 16); }
; __device__ __forceinline__ float siluf_(float x) { return x / (1.f + __expf(-x)); }
; __device__ void phase_combine(const P& p, int l, int ntok, float* lds) {
;     ...
; #pragma unroll
;       for (int i = 0; i < 4; ++i) {
;         int row = r0 + i0 + i;
;         float o0 = bf2f((u16)a0[i]) + bf2f((u16)a1[i]), o1 = bf2f((u16)a2[i]) + bf2f((u16)a3[i]);
;         float ss = wave_sum_b(o0 * o0 + o1 * o1);
;         float rstd = rsqrtf(ss * (1.f / 128.f) + 1e-6f);
;         u16* dst = p.nbuf + (size_t)row * D + mixer * 512 + hh * 128 + lane;
;         dst[0] = f2bf(o0 * rstd * ng0 * siluf_(bf2f((u16)g0r[i])));
;         dst[64] = f2bf(o1 * rstd * ng1 * siluf_(bf2f((u16)g1r[i])));
;       }
; #pragma unroll
;       for (int i = 0; i < 4; ++i) {
;         int tr = (tb + i0 + i) & (RL - 1);
;         float up = tr != 0 ? bf2f((u16)ucc[i]) * bf2f((u16)uch[i]) : 0.f;
;         float uc = bf2f((u16)ucc[i + 1]) * bf2f((u16)uch[i + 1]);
;         float un = tr != RL - 1 ? bf2f((u16)ucc[i + 2]) * bf2f((u16)uch[i + 2]) : 0.f;
;         float cv = scw0 * up + scw1 * uc + scw2 * un;
;         p.nbuf[(size_t)(r0 + i0 + i) * D + 1024 + tid] = f2bf(bf2f((u16)cbr[i]) * cv);
;       }
	v_bfe_u32 v158, v22, 16, 1
	v_add3_u32 v22, v22, v158, s21
	global_store_short_d16_hi v[160:161], v22, off
	v_mul_f32_e32 v22, v23, v159
	v_lshlrev_b32_e32 v23, 16, v157
	v_mul_f32_e32 v157, 0xbfb8aa3b, v23
	v_exp_f32_e32 v157, v157
	v_mul_f32_e32 v22, v127, v22
	v_add_f32_e32 v157, 1.0, v157
	s_nop 0
	v_rcp_f32_e32 v158, v157
	s_nop 0
	v_mul_f32_e32 v23, v23, v158
	v_mul_f32_e32 v22, v23, v22
	v_bfe_u32 v23, v22, 16, 1
	v_add3_u32 v22, v22, v23, s21
	global_store_short_d16_hi v[160:161], v22, off offset:128
	v_lshlrev_b32_e32 v22, 16, v155
	v_lshlrev_b32_e32 v23, 16, v156
	v_lshlrev_b32_e32 v156, 16, v153
	v_lshlrev_b32_e32 v157, 16, v154
	v_pk_add_f32 v[22:23], v[22:23], v[156:157]
	v_mul_f32_e32 v156, 0xbfb8aa3b, v152
	v_pk_mul_f32 v[154:155], v[22:23], v[22:23]
	v_exp_f32_e32 v156, v156
	v_add_f32_e32 v153, v154, v155
	v_mov_b32_e32 v154, v129
	v_add_f32_e32 v156, 1.0, v156
	v_add_f32_dpp v153, v153, v153 quad_perm:[1,0,3,2] row_mask:0xf bank_mask:0xf bound_ctrl:1
	s_nop 1
	v_add_f32_dpp v153, v153, v153 quad_perm:[2,3,0,1] row_mask:0xf bank_mask:0xf bound_ctrl:1
	s_nop 1
	v_add_f32_dpp v153, v153, v153 row_half_mirror row_mask:0xf bank_mask:0xf bound_ctrl:1
	s_nop 1
	v_add_f32_dpp v153, v153, v153 row_mirror row_mask:0xf bank_mask:0xf bound_ctrl:1
	s_nop 1
	v_mov_b32_dpp v154, v153 row_bcast:15 row_mask:0xa bank_mask:0xf
	v_add_f32_e32 v153, v153, v154
	v_mov_b32_e32 v154, v129
	s_nop 1
	v_mov_b32_dpp v154, v153 row_bcast:31 row_mask:0xc bank_mask:0xf
	v_add_f32_e32 v153, v153, v154
	s_nop 0
	v_readlane_b32 s2, v153, 63
	s_nop 1
	v_fma_f32 v153, s2, v182, v169
	v_cmp_gt_f32_e32 vcc, s33, v153
	v_mul_f32_e32 v154, 0x4b800000, v153
	s_nop 0
	v_cndmask_b32_e32 v153, v153, v154, vcc
	v_rsq_f32_e32 v153, v153
	s_nop 0
	v_mul_f32_e32 v154, 0x45800000, v153
	v_cndmask_b32_e32 v153, v153, v154, vcc
	v_lshl_add_u64 v[154:155], v[12:13], 0, s[0:1]
	v_mul_f32_e32 v22, v22, v153
	v_mul_f32_e32 v22, v126, v22
	v_rcp_f32_e32 v157, v156
	s_nop 0
	v_mul_f32_e32 v152, v152, v157
	v_mul_f32_e32 v22, v152, v22
	v_bfe_u32 v152, v22, 16, 1
	v_add3_u32 v22, v22, v152, s21
	global_store_short_d16_hi v[154:155], v22, off
	v_mul_f32_e32 v22, v23, v153
	v_lshlrev_b32_e32 v23, 16, v149
	v_mul_f32_e32 v149, 0xbfb8aa3b, v23
	v_exp_f32_e32 v149, v149
	v_mul_f32_e32 v22, v127, v22
	v_add_f32_e32 v149, 1.0, v149
	s_and_b32 s0, s46, s58
	s_cmp_lg_u32 s0, 0
	v_rcp_f32_e32 v152, v149
	s_nop 0
	v_mul_f32_e32 v23, v23, v152
	v_mul_f32_e32 v22, v23, v22
	v_bfe_u32 v23, v22, 16, 1
	v_add3_u32 v22, v22, v23, s21
	global_store_short_d16_hi v[154:155], v22, off offset:128
	v_lshlrev_b32_e32 v22, 16, v139
	v_lshlrev_b32_e32 v23, 16, v140
	v_mul_f32_e32 v22, v22, v23
	s_cselect_b64 vcc, -1, 0
	v_cndmask_b32_e32 v22, 0, v22, vcc
	v_lshlrev_b32_e32 v23, 16, v147
	v_lshlrev_b32_e32 v139, 16, v148
	v_mul_f32_e32 v23, v23, v139
	v_lshlrev_b32_e32 v139, 16, v150
	v_lshlrev_b32_e32 v140, 16, v151
	v_mul_f32_e32 v22, v123, v22
	v_mul_f32_e32 v139, v139, v140
	v_fmac_f32_e32 v22, v124, v23
	v_fmac_f32_e32 v22, v125, v139
	v_mul_f32_e32 v22, v22, v138
	v_bfe_u32 v138, v22, 16, 1
	v_add3_u32 v22, v22, v138, s21
	global_store_short_d16_hi v[18:19], v22, off offset:2048
	v_lshlrev_b32_e32 v18, 16, v145
	v_lshlrev_b32_e32 v19, 16, v146
	v_mul_f32_e32 v18, v18, v19
	v_mul_f32_e32 v19, v124, v139
	v_fmac_f32_e32 v19, v123, v23
	v_fmac_f32_e32 v19, v125, v18
	v_lshlrev_b32_e32 v22, 16, v137
	v_mul_f32_e32 v19, v19, v22
	v_bfe_u32 v22, v19, 16, 1
	v_add3_u32 v19, v19, v22, s21
	global_store_short_d16_hi v[20:21], v19, off offset:2048
	v_lshlrev_b32_e32 v19, 16, v143
	v_lshlrev_b32_e32 v20, 16, v144
	v_mul_f32_e32 v19, v19, v20
	v_mul_f32_e32 v20, v124, v18
	v_fmac_f32_e32 v20, v123, v139
	v_fmac_f32_e32 v20, v125, v19
	v_lshlrev_b32_e32 v21, 16, v136
	v_mul_f32_e32 v20, v20, v21
	v_bfe_u32 v21, v20, 16, 1
	v_add3_u32 v20, v20, v21, s21
	s_and_b32 s0, s36, s58
	global_store_short_d16_hi v[2:3], v20, off offset:2048
	v_lshlrev_b32_e32 v2, 16, v141
	v_lshlrev_b32_e32 v3, 16, v142
	s_cmp_lg_u32 s0, s58
	v_mul_f32_e32 v2, v2, v3
	s_cselect_b64 vcc, -1, 0
	v_mul_f32_e32 v3, v124, v19
	v_cndmask_b32_e32 v2, 0, v2, vcc
	v_fmac_f32_e32 v3, v123, v18
	v_fmac_f32_e32 v3, v125, v2
	v_lshlrev_b32_e32 v2, 16, v135
	v_mul_f32_e32 v2, v3, v2
	v_bfe_u32 v3, v2, 16, 1
	s_add_i32 s0, s60, 4
	v_add3_u32 v2, v2, v3, s21
	s_cmp_gt_u32 s60, 11
	s_mov_b32 s60, s0
	global_store_short_d16_hi v[0:1], v2, off offset:2048
	s_cbranch_scc0 .LBB0_94
	v_readlane_b32 s0, v240, 4
	v_readlane_b32 s1, v240, 5
	s_load_dword s0, s[0:1], 0x0
	s_movk_i32 s33, 0x3600
	s_waitcnt lgkmcnt(0)
	s_add_i32 s55, s0, s55
	s_cmp_ge_i32 s55, s72
	s_cbranch_scc0 .LBB0_90

; __device__ __forceinline__ float bf2f(u16 v) { return __uint_as_float(((unsigned)v) << 16); }
; __device__ __forceinline__ float tanhf_(float x) { return 1.f - 2.f / (1.f + __expf(2.f * x)); }
; __device__ void phase_gdnprep(const P& p, int l, float* lds) {
;     ...
;           const int tk = wv + 8 * q, t = tq0 + tk, tp = dir ? t + 1 : t - 1;
;           const bool hp = tp >= 0 && tp < T;
;           float wc = bf2f((u16)nwc[q]);
;           float wp = hp ? bf2f((u16)nwp[q]) : 0.f;
;           float xwa = wc + (wp - wc) * mu_wa;
;           tw_s[tk * 68 + lane] = lane < 32 ? tanhf_(xwa) : xwa;
;         }
.LBB0_122:
	s_add_i32 s2, s22, 0xffffc000
	s_cmpk_lt_i32 s47, 0x400
	s_cselect_b32 s20, s96, 0x100
	s_cselect_b32 s2, s22, s2
	s_add_i32 s3, s20, -1
	s_and_b32 s23, s2, s3
	s_add_i32 s23, s23, s28
	v_add_u32_e32 v9, s23, v35
	s_waitcnt vmcnt(2)
	v_lshlrev_b32_e32 v10, 16, v79
	v_cmp_gt_u32_e32 vcc, s20, v9
	v_lshlrev_b32_e32 v8, 16, v80
	s_nop 0
	v_cndmask_b32_e32 v9, 0, v10, vcc
	v_sub_f32_e32 v9, v9, v8
	s_waitcnt vmcnt(0)
	v_fmac_f32_e32 v8, v161, v9
	s_and_saveexec_b64 s[2:3], s[38:39]
	s_cbranch_execz .LBB0_124
	v_add_f32_e32 v8, v8, v8
	v_mul_f32_e32 v8, 0x3fb8aa3b, v8
	v_exp_f32_e32 v8, v8
	s_nop 0
	v_add_f32_e32 v8, 1.0, v8
	v_rcp_f32_e32 v9, v8
	s_nop 0
	v_mul_f32_e32 v8, 2.0, v9
	v_sub_f32_e32 v8, 1.0, v8
.LBB0_124:
	s_or_b64 exec, exec, s[2:3]
	v_add_u32_e32 v9, s23, v77
	v_lshlrev_b32_e32 v10, 16, v83
	v_cmp_gt_u32_e32 vcc, s20, v9
	ds_write_b32 v78, v8 offset:51200
	v_lshlrev_b32_e32 v8, 16, v84
	v_cndmask_b32_e32 v9, 0, v10, vcc
	v_sub_f32_e32 v9, v9, v8
	v_fmac_f32_e32 v8, v161, v9
	s_and_saveexec_b64 s[2:3], s[38:39]
	s_cbranch_execz .LBB0_126
	v_add_f32_e32 v8, v8, v8
	v_mul_f32_e32 v8, 0x3fb8aa3b, v8
	v_exp_f32_e32 v8, v8
	s_nop 0
	v_add_f32_e32 v8, 1.0, v8
	v_rcp_f32_e32 v9, v8
	s_nop 0
	v_mul_f32_e32 v8, 2.0, v9
	v_sub_f32_e32 v8, 1.0, v8

; __device__ __forceinline__ float sigmoidf_(float x) { return 1.f / (1.f + __expf(-x)); }
; __device__ void phase_gdnprep(const P& p, int l, float* lds) {
;     ...
;         float aw[8], aa[8];
; #pragma unroll
;         for (int k4 = 0; k4 < 8; ++k4) { aw[k4] = tw_s[fr * 68 + k4 * 4 + fq]; aa[k4] = tw_s[fr * 68 + 32 + k4 * 4 + fq]; }
; #pragma unroll
;         for (int nt = 0; nt < 4; ++nt) {
;           f32x4 cw = (f32x4){0.f, 0.f, 0.f, 0.f}, ca = cw;
; #pragma unroll
;           for (int k4 = 0; k4 < 8; ++k4) {
;             cw = __builtin_amdgcn_mfma_f32_16x16x4f32(aw[k4], bw[k4][nt], cw, 0, 0, 0);
;             ca = __builtin_amdgcn_mfma_f32_16x16x4f32(aa[k4], ba[k4][nt], ca, 0, 0, 0);
;           }
; #pragma unroll
;           for (int j = 0; j < 4; ++j) {
;             const size_t o = (size_t)(R0 + fq * 4 + j) * 512 + wv * 64 + nt * 16 + fr;
;             dD[o] = __expf(-0.6065306597126334f * sigmoidf_(w0v[nt] + cw[j]));
;             dA[o] = sigmoidf_(a0v[nt] + ca[j]);
;           }
;         }
.LBB0_130:
	s_waitcnt lgkmcnt(0)
	s_barrier
	v_add_u32_e32 v8, 0xc800, v75
	ds_read2_b32 v[72:73], v8 offset1:4
	ds_read2_b32 v[68:69], v8 offset0:8 offset1:12
	v_add_u32_e32 v9, 0xc800, v76
	ds_read2_b32 v[70:71], v9 offset0:32 offset1:36
	ds_read2_b32 v[66:67], v9 offset0:40 offset1:44
	ds_read2_b32 v[54:55], v8 offset0:16 offset1:20
	ds_read2_b32 v[50:51], v9 offset0:48 offset1:52
	ds_read2_b32 v[44:45], v8 offset0:24 offset1:28
	ds_read2_b32 v[46:47], v9 offset0:56 offset1:60
	s_waitcnt lgkmcnt(7)
	v_mfma_f32_16x16x4_f32 v[8:11], v72, v117, 0
	v_add_u32_e32 v42, s22, v74
	v_ashrrev_i32_e32 v43, 31, v42
	v_lshlrev_b64 v[48:49], 9, v[42:43]
	v_lshl_add_u64 v[48:49], v[48:49], 0, v[26:27]
	v_lshlrev_b64 v[48:49], 2, v[48:49]
	v_lshl_add_u64 v[62:63], s[42:43], 0, v[48:49]
	s_waitcnt lgkmcnt(5)
	v_mfma_f32_16x16x4_f32 v[12:15], v70, v120, 0
	v_mfma_f32_16x16x4_f32 v[8:11], v73, v81, v[8:11]
	v_mfma_f32_16x16x4_f32 v[12:15], v71, v82, v[12:15]
	v_mfma_f32_16x16x4_f32 v[8:11], v68, v85, v[8:11]
	s_waitcnt lgkmcnt(4)
	v_mfma_f32_16x16x4_f32 v[12:15], v66, v86, v[12:15]
	v_mfma_f32_16x16x4_f32 v[8:11], v69, v87, v[8:11]
	v_mfma_f32_16x16x4_f32 v[12:15], v67, v88, v[12:15]
	s_waitcnt lgkmcnt(3)
	v_mfma_f32_16x16x4_f32 v[8:11], v54, v89, v[8:11]
	s_waitcnt lgkmcnt(2)
	v_mfma_f32_16x16x4_f32 v[12:15], v50, v90, v[12:15]
	v_mfma_f32_16x16x4_f32 v[8:11], v55, v91, v[8:11]
	v_mfma_f32_16x16x4_f32 v[12:15], v51, v92, v[12:15]
	s_waitcnt lgkmcnt(1)
	v_mfma_f32_16x16x4_f32 v[8:11], v44, v93, v[8:11]
	s_waitcnt lgkmcnt(0)
	v_mfma_f32_16x16x4_f32 v[56:59], v46, v94, v[12:15]
	v_mfma_f32_16x16x4_f32 v[12:15], v45, v95, v[8:11]
	v_mfma_f32_16x16x4_f32 v[8:11], v47, v96, v[56:59]
	s_nop 8
	v_add_f32_e32 v12, v111, v12
	v_mul_f32_e32 v12, 0xbfb8aa3b, v12
	v_exp_f32_e32 v12, v12
	s_nop 0
	v_add_f32_e32 v12, 1.0, v12
	v_add_f32_e32 v8, v114, v8
	v_mul_f32_e32 v8, 0xbfb8aa3b, v8
	v_exp_f32_e32 v8, v8
	v_rcp_f32_e32 v43, v12
	s_nop 0
	v_mul_f32_e32 v12, 1.0, v43
	v_mul_f32_e32 v12, 0xbf1b4598, v12
	v_mul_f32_e32 v12, 0x3fb8aa3b, v12
	v_exp_f32_e32 v12, v12
	v_lshl_add_u64 v[56:57], s[0:1], 0, v[48:49]
	v_add_f32_e32 v8, 1.0, v8
	v_add_u32_e32 v48, 1, v42
	global_store_dword v[56:57], v12, off
	v_ashrrev_i32_e32 v49, 31, v48
	v_lshlrev_b64 v[48:49], 9, v[48:49]
	v_lshl_add_u64 v[48:49], v[48:49], 0, v[26:27]
	v_rcp_f32_e32 v12, v8
	s_nop 0
	v_mul_f32_e32 v8, 1.0, v12
	global_store_dword v[62:63], v8, off
	v_add_f32_e32 v8, v111, v13
	v_mul_f32_e32 v8, 0xbfb8aa3b, v8
	v_exp_f32_e32 v8, v8
	v_add_f32_e32 v10, v114, v10
	v_mul_f32_e32 v10, 0xbfb8aa3b, v10
	v_exp_f32_e32 v10, v10
	v_add_f32_e32 v8, 1.0, v8
	v_add_f32_e32 v10, 1.0, v10
	v_rcp_f32_e32 v12, v8
	s_nop 0
	v_mul_f32_e32 v8, 1.0, v12
	v_mul_f32_e32 v8, 0xbf1b4598, v8
	v_mul_f32_e32 v8, 0x3fb8aa3b, v8
	v_exp_f32_e32 v8, v8
	v_lshlrev_b64 v[12:13], 2, v[48:49]
	v_lshl_add_u64 v[60:61], s[0:1], 0, v[12:13]
	v_lshl_add_u64 v[64:65], s[42:43], 0, v[12:13]
	global_store_dword v[60:61], v8, off
	v_add_f32_e32 v8, v114, v9
	v_mul_f32_e32 v8, 0xbfb8aa3b, v8
	v_exp_f32_e32 v8, v8
	v_add_f32_e32 v12, v111, v14
	v_mul_f32_e32 v12, 0xbfb8aa3b, v12
	v_exp_f32_e32 v12, v12
	v_add_f32_e32 v8, 1.0, v8
	v_add_f32_e32 v12, 1.0, v12
	v_rcp_f32_e32 v9, v8
	s_nop 0
	v_mul_f32_e32 v8, 1.0, v9
	v_rcp_f32_e32 v13, v12
	s_nop 0
	v_mul_f32_e32 v12, 1.0, v13
	global_store_dword v[64:65], v8, off
	v_add_u32_e32 v8, 2, v42
	v_mul_f32_e32 v12, 0xbf1b4598, v12
	v_ashrrev_i32_e32 v9, 31, v8
	v_mul_f32_e32 v12, 0x3fb8aa3b, v12
	v_lshlrev_b64 v[8:9], 9, v[8:9]
	v_exp_f32_e32 v12, v12
	v_lshl_add_u64 v[8:9], v[8:9], 0, v[26:27]
	v_lshlrev_b64 v[8:9], 2, v[8:9]
	v_lshl_add_u64 v[58:59], s[0:1], 0, v[8:9]
	global_store_dword v[58:59], v12, off
	v_lshl_add_u64 v[52:53], s[42:43], 0, v[8:9]
	v_add_u32_e32 v8, 3, v42
	v_ashrrev_i32_e32 v9, 31, v8
	v_rcp_f32_e32 v12, v10
	s_nop 0
	v_mul_f32_e32 v10, 1.0, v12
	global_store_dword v[52:53], v10, off
	v_add_f32_e32 v10, v111, v15
	v_mul_f32_e32 v10, 0xbfb8aa3b, v10
	v_exp_f32_e32 v10, v10
	v_lshlrev_b64 v[8:9], 9, v[8:9]
	v_lshl_add_u64 v[8:9], v[8:9], 0, v[26:27]
	v_lshlrev_b64 v[8:9], 2, v[8:9]
	v_add_f32_e32 v10, 1.0, v10
	v_lshl_add_u64 v[48:49], s[0:1], 0, v[8:9]
	v_rcp_f32_e32 v12, v10
	s_nop 0
	v_mul_f32_e32 v10, 1.0, v12
	v_mul_f32_e32 v10, 0xbf1b4598, v10
	v_mul_f32_e32 v10, 0x3fb8aa3b, v10
	v_exp_f32_e32 v10, v10
	v_lshl_add_u64 v[42:43], s[42:43], 0, v[8:9]
	global_store_dword v[48:49], v10, off
	v_add_f32_e32 v10, v114, v11
	v_mul_f32_e32 v10, 0xbfb8aa3b, v10
	v_exp_f32_e32 v10, v10
	s_nop 0
	v_add_f32_e32 v10, 1.0, v10
	s_nop 0
	v_rcp_f32_e32 v11, v10
	s_nop 0
	v_mul_f32_e32 v10, 1.0, v11
	global_store_dword v[42:43], v10, off
	v_mfma_f32_16x16x4_f32 v[8:11], v72, v118, 0
	v_mfma_f32_16x16x4_f32 v[12:15], v70, v121, 0
	v_mfma_f32_16x16x4_f32 v[8:11], v73, v97, v[8:11]
	v_mfma_f32_16x16x4_f32 v[12:15], v71, v98, v[12:15]
	v_mfma_f32_16x16x4_f32 v[8:11], v68, v99, v[8:11]
	v_mfma_f32_16x16x4_f32 v[12:15], v66, v100, v[12:15]
	v_mfma_f32_16x16x4_f32 v[8:11], v69, v101, v[8:11]
	v_mfma_f32_16x16x4_f32 v[12:15], v67, v102, v[12:15]
	v_mfma_f32_16x16x4_f32 v[8:11], v54, v103, v[8:11]
	v_mfma_f32_16x16x4_f32 v[12:15], v50, v104, v[12:15]
	v_mfma_f32_16x16x4_f32 v[8:11], v55, v105, v[8:11]
	v_mfma_f32_16x16x4_f32 v[12:15], v51, v106, v[12:15]
	v_mfma_f32_16x16x4_f32 v[8:11], v44, v107, v[8:11]
	v_mfma_f32_16x16x4_f32 v[162:165], v46, v108, v[12:15]
	v_mfma_f32_16x16x4_f32 v[12:15], v45, v109, v[8:11]
	v_mfma_f32_16x16x4_f32 v[8:11], v47, v110, v[162:165]
	s_nop 8
	v_add_f32_e32 v12, v112, v12
	v_mul_f32_e32 v12, 0xbfb8aa3b, v12
	v_exp_f32_e32 v12, v12
	s_nop 0
	v_add_f32_e32 v12, 1.0, v12
; __device__ __forceinline__ float sigmoidf_(float x) { return 1.f / (1.f + __expf(-x)); }
; __device__ void phase_gdnprep(const P& p, int l, float* lds) {
;     ...
; #pragma unroll
;         for (int nt = 0; nt < 4; ++nt) {
;           f32x4 cw = (f32x4){0.f, 0.f, 0.f, 0.f}, ca = cw;
; #pragma unroll
;           for (int k4 = 0; k4 < 8; ++k4) {
;             cw = __builtin_amdgcn_mfma_f32_16x16x4f32(aw[k4], bw[k4][nt], cw, 0, 0, 0);
;             ca = __builtin_amdgcn_mfma_f32_16x16x4f32(aa[k4], ba[k4][nt], ca, 0, 0, 0);
;           }
; #pragma unroll
;           for (int j = 0; j < 4; ++j) {
;             const size_t o = (size_t)(R0 + fq * 4 + j) * 512 + wv * 64 + nt * 16 + fr;
;             dD[o] = __expf(-0.6065306597126334f * sigmoidf_(w0v[nt] + cw[j]));
;             dA[o] = sigmoidf_(a0v[nt] + ca[j]);
;           }
;         }
	v_add_f32_e32 v8, v115, v8
	v_mul_f32_e32 v8, 0xbfb8aa3b, v8
	v_exp_f32_e32 v8, v8
	v_rcp_f32_e32 v128, v12
	s_nop 0
	v_mul_f32_e32 v12, 1.0, v128
	v_mul_f32_e32 v12, 0xbf1b4598, v12
	v_mul_f32_e32 v12, 0x3fb8aa3b, v12
	v_exp_f32_e32 v12, v12
	v_add_f32_e32 v8, 1.0, v8
	global_store_dword v[56:57], v12, off offset:64
	s_nop 0
	v_rcp_f32_e32 v12, v8
	s_nop 0
	v_mul_f32_e32 v8, 1.0, v12
	global_store_dword v[62:63], v8, off offset:64
	v_add_f32_e32 v8, v112, v13
	v_mul_f32_e32 v8, 0xbfb8aa3b, v8
	v_exp_f32_e32 v8, v8
	s_nop 0
	v_add_f32_e32 v8, 1.0, v8
	s_nop 0
	v_rcp_f32_e32 v12, v8
	s_nop 0
	v_mul_f32_e32 v8, 1.0, v12
	v_mul_f32_e32 v8, 0xbf1b4598, v8
	v_mul_f32_e32 v8, 0x3fb8aa3b, v8
	v_exp_f32_e32 v8, v8
	global_store_dword v[60:61], v8, off offset:64
	v_add_f32_e32 v8, v115, v9
	v_mul_f32_e32 v8, 0xbfb8aa3b, v8
	v_exp_f32_e32 v8, v8
	s_nop 0
	v_add_f32_e32 v8, 1.0, v8
	s_nop 0
	v_rcp_f32_e32 v9, v8
	s_nop 0
	v_mul_f32_e32 v8, 1.0, v9
	global_store_dword v[64:65], v8, off offset:64
	v_add_f32_e32 v8, v112, v14
	v_mul_f32_e32 v8, 0xbfb8aa3b, v8
	v_exp_f32_e32 v8, v8
	s_nop 0
	v_add_f32_e32 v8, 1.0, v8
	s_nop 0
	v_rcp_f32_e32 v9, v8
	s_nop 0
	v_mul_f32_e32 v8, 1.0, v9
	v_mul_f32_e32 v8, 0xbf1b4598, v8
	v_mul_f32_e32 v8, 0x3fb8aa3b, v8
	v_exp_f32_e32 v8, v8
	global_store_dword v[58:59], v8, off offset:64
	v_add_f32_e32 v8, v115, v10
	v_mul_f32_e32 v8, 0xbfb8aa3b, v8
	v_exp_f32_e32 v8, v8
	s_nop 0
	v_add_f32_e32 v8, 1.0, v8
	s_nop 0
	v_rcp_f32_e32 v9, v8
	s_nop 0
	v_mul_f32_e32 v8, 1.0, v9
	global_store_dword v[52:53], v8, off offset:64
	v_add_f32_e32 v8, v112, v15
	v_mul_f32_e32 v8, 0xbfb8aa3b, v8
	v_exp_f32_e32 v8, v8
	s_nop 0
	v_add_f32_e32 v8, 1.0, v8
	s_nop 0
	v_rcp_f32_e32 v9, v8
	s_nop 0
	v_mul_f32_e32 v8, 1.0, v9
	v_mul_f32_e32 v8, 0xbf1b4598, v8
	v_mul_f32_e32 v8, 0x3fb8aa3b, v8
	v_exp_f32_e32 v8, v8
	global_store_dword v[48:49], v8, off offset:64
	v_add_f32_e32 v8, v115, v11
	v_mul_f32_e32 v8, 0xbfb8aa3b, v8
	v_exp_f32_e32 v8, v8
	s_nop 0
	v_add_f32_e32 v8, 1.0, v8
	s_nop 0
	v_rcp_f32_e32 v9, v8
	s_nop 0
	v_mul_f32_e32 v8, 1.0, v9
	global_store_dword v[42:43], v8, off offset:64
	v_mfma_f32_16x16x4_f32 v[8:11], v72, v119, 0
	v_mfma_f32_16x16x4_f32 v[12:15], v70, v122, 0
	v_mfma_f32_16x16x4_f32 v[8:11], v73, v123, v[8:11]
	v_mfma_f32_16x16x4_f32 v[12:15], v71, v124, v[12:15]
	v_mfma_f32_16x16x4_f32 v[8:11], v68, v125, v[8:11]
	v_mfma_f32_16x16x4_f32 v[12:15], v66, v126, v[12:15]
	v_mfma_f32_16x16x4_f32 v[8:11], v69, v127, v[8:11]
	v_mfma_f32_16x16x4_f32 v[12:15], v67, v134, v[12:15]
	v_mfma_f32_16x16x4_f32 v[8:11], v54, v135, v[8:11]
	v_mfma_f32_16x16x4_f32 v[12:15], v50, v136, v[12:15]
	v_mfma_f32_16x16x4_f32 v[8:11], v55, v137, v[8:11]
	v_mfma_f32_16x16x4_f32 v[12:15], v51, v138, v[12:15]
	v_mfma_f32_16x16x4_f32 v[8:11], v44, v139, v[8:11]
	v_mfma_f32_16x16x4_f32 v[162:165], v46, v140, v[12:15]
	v_mfma_f32_16x16x4_f32 v[12:15], v45, v141, v[8:11]
	v_mfma_f32_16x16x4_f32 v[8:11], v47, v142, v[162:165]
	s_nop 8
	v_add_f32_e32 v12, v113, v12
	v_mul_f32_e32 v12, 0xbfb8aa3b, v12
	v_exp_f32_e32 v12, v12
	s_nop 0
	v_add_f32_e32 v12, 1.0, v12
	v_add_f32_e32 v8, v116, v8
	v_mul_f32_e32 v8, 0xbfb8aa3b, v8
	v_exp_f32_e32 v8, v8
	v_rcp_f32_e32 v128, v12
	s_nop 0
	v_mul_f32_e32 v12, 1.0, v128
	v_mul_f32_e32 v12, 0xbf1b4598, v12
	v_mul_f32_e32 v12, 0x3fb8aa3b, v12
	v_exp_f32_e32 v12, v12
	v_add_f32_e32 v8, 1.0, v8
	global_store_dword v[56:57], v12, off offset:128
	s_nop 0
	v_rcp_f32_e32 v12, v8
	s_nop 0
	v_mul_f32_e32 v8, 1.0, v12
	global_store_dword v[62:63], v8, off offset:128
	v_add_f32_e32 v8, v113, v13
	v_mul_f32_e32 v8, 0xbfb8aa3b, v8
	v_exp_f32_e32 v8, v8
	s_nop 0
	v_add_f32_e32 v8, 1.0, v8
	s_nop 0
	v_rcp_f32_e32 v12, v8
	s_nop 0
	v_mul_f32_e32 v8, 1.0, v12
	v_mul_f32_e32 v8, 0xbf1b4598, v8
	v_mul_f32_e32 v8, 0x3fb8aa3b, v8
	v_exp_f32_e32 v8, v8
	global_store_dword v[60:61], v8, off offset:128
	v_add_f32_e32 v8, v116, v9
	v_mul_f32_e32 v8, 0xbfb8aa3b, v8
	v_exp_f32_e32 v8, v8
	s_nop 0
	v_add_f32_e32 v8, 1.0, v8
	s_nop 0
	v_rcp_f32_e32 v9, v8
	s_nop 0
	v_mul_f32_e32 v8, 1.0, v9
	global_store_dword v[64:65], v8, off offset:128
	v_add_f32_e32 v8, v113, v14
	v_mul_f32_e32 v8, 0xbfb8aa3b, v8
	v_exp_f32_e32 v8, v8
	s_nop 0
	v_add_f32_e32 v8, 1.0, v8
	s_nop 0
; __device__ __forceinline__ float sigmoidf_(float x) { return 1.f / (1.f + __expf(-x)); }
; #define LBAR() do { asm volatile("s_waitcnt lgkmcnt(0)" ::: "memory"); __builtin_amdgcn_s_barrier(); asm volatile("" ::: "memory"); } while (0)
; __device__ void phase_gdnprep(const P& p, int l, float* lds) {
;     ...
; #pragma unroll
;         for (int nt = 0; nt < 4; ++nt) {
;           f32x4 cw = (f32x4){0.f, 0.f, 0.f, 0.f}, ca = cw;
; #pragma unroll
;           for (int k4 = 0; k4 < 8; ++k4) {
;             cw = __builtin_amdgcn_mfma_f32_16x16x4f32(aw[k4], bw[k4][nt], cw, 0, 0, 0);
;             ca = __builtin_amdgcn_mfma_f32_16x16x4f32(aa[k4], ba[k4][nt], ca, 0, 0, 0);
;           }
; #pragma unroll
;           for (int j = 0; j < 4; ++j) {
;             const size_t o = (size_t)(R0 + fq * 4 + j) * 512 + wv * 64 + nt * 16 + fr;
;             dD[o] = __expf(-0.6065306597126334f * sigmoidf_(w0v[nt] + cw[j]));
;             dA[o] = sigmoidf_(a0v[nt] + ca[j]);
;           }
;         }
;         LBAR();
;       }
	v_rcp_f32_e32 v9, v8
	s_nop 0
	v_mul_f32_e32 v8, 1.0, v9
	v_mul_f32_e32 v8, 0xbf1b4598, v8
	v_mul_f32_e32 v8, 0x3fb8aa3b, v8
	v_exp_f32_e32 v8, v8
	global_store_dword v[58:59], v8, off offset:128
	v_add_f32_e32 v8, v116, v10
	v_mul_f32_e32 v8, 0xbfb8aa3b, v8
	v_exp_f32_e32 v8, v8
	s_nop 0
	v_add_f32_e32 v8, 1.0, v8
	s_nop 0
	v_rcp_f32_e32 v9, v8
	s_nop 0
	v_mul_f32_e32 v8, 1.0, v9
	global_store_dword v[52:53], v8, off offset:128
	v_add_f32_e32 v8, v113, v15
	v_mul_f32_e32 v8, 0xbfb8aa3b, v8
	v_exp_f32_e32 v8, v8
	s_nop 0
	v_add_f32_e32 v8, 1.0, v8
	s_nop 0
	v_rcp_f32_e32 v9, v8
	s_nop 0
	v_mul_f32_e32 v8, 1.0, v9
	v_mul_f32_e32 v8, 0xbf1b4598, v8
	v_mul_f32_e32 v8, 0x3fb8aa3b, v8
	v_exp_f32_e32 v8, v8
	global_store_dword v[48:49], v8, off offset:128
	v_add_f32_e32 v8, v116, v11
	v_mul_f32_e32 v8, 0xbfb8aa3b, v8
	v_exp_f32_e32 v8, v8
	s_nop 0
	v_add_f32_e32 v8, 1.0, v8
	s_nop 0
	v_rcp_f32_e32 v9, v8
	s_nop 0
	v_mul_f32_e32 v8, 1.0, v9
	global_store_dword v[42:43], v8, off offset:128
	v_mfma_f32_16x16x4_f32 v[8:11], v72, v145, 0
	v_mfma_f32_16x16x4_f32 v[12:15], v70, v146, 0
	v_mfma_f32_16x16x4_f32 v[8:11], v73, v147, v[8:11]
	v_mfma_f32_16x16x4_f32 v[12:15], v71, v148, v[12:15]
	v_mfma_f32_16x16x4_f32 v[8:11], v68, v149, v[8:11]
	v_mfma_f32_16x16x4_f32 v[12:15], v66, v150, v[12:15]
	v_mfma_f32_16x16x4_f32 v[8:11], v69, v151, v[8:11]
	v_mfma_f32_16x16x4_f32 v[12:15], v67, v152, v[12:15]
	v_mfma_f32_16x16x4_f32 v[8:11], v54, v153, v[8:11]
	v_mfma_f32_16x16x4_f32 v[12:15], v50, v154, v[12:15]
	v_mfma_f32_16x16x4_f32 v[8:11], v55, v155, v[8:11]
	v_mfma_f32_16x16x4_f32 v[12:15], v51, v156, v[12:15]
	v_mfma_f32_16x16x4_f32 v[8:11], v44, v157, v[8:11]
	v_mfma_f32_16x16x4_f32 v[66:69], v46, v158, v[12:15]
	v_mfma_f32_16x16x4_f32 v[12:15], v45, v159, v[8:11]
	v_mfma_f32_16x16x4_f32 v[8:11], v47, v160, v[66:69]
	s_nop 8
	v_add_f32_e32 v12, v143, v12
	v_mul_f32_e32 v12, 0xbfb8aa3b, v12
	v_exp_f32_e32 v12, v12
	s_nop 0
	v_add_f32_e32 v12, 1.0, v12
	v_add_f32_e32 v8, v144, v8
	v_mul_f32_e32 v8, 0xbfb8aa3b, v8
	v_exp_f32_e32 v8, v8
	v_rcp_f32_e32 v44, v12
	s_nop 0
	v_mul_f32_e32 v12, 1.0, v44
	v_mul_f32_e32 v12, 0xbf1b4598, v12
	v_mul_f32_e32 v12, 0x3fb8aa3b, v12
	v_exp_f32_e32 v12, v12
	v_add_f32_e32 v8, 1.0, v8
	global_store_dword v[56:57], v12, off offset:192
	s_nop 0
	v_rcp_f32_e32 v12, v8
	s_nop 0
	v_mul_f32_e32 v8, 1.0, v12
	global_store_dword v[62:63], v8, off offset:192
	v_add_f32_e32 v8, v143, v13
	v_mul_f32_e32 v8, 0xbfb8aa3b, v8
	v_exp_f32_e32 v8, v8
	s_nop 0
	v_add_f32_e32 v8, 1.0, v8
	s_nop 0
	v_rcp_f32_e32 v12, v8
	s_nop 0
	v_mul_f32_e32 v8, 1.0, v12
	v_mul_f32_e32 v8, 0xbf1b4598, v8
	v_mul_f32_e32 v8, 0x3fb8aa3b, v8
	v_exp_f32_e32 v8, v8
	global_store_dword v[60:61], v8, off offset:192
	v_add_f32_e32 v8, v144, v9
	v_mul_f32_e32 v8, 0xbfb8aa3b, v8
	v_exp_f32_e32 v8, v8
	s_nop 0
	v_add_f32_e32 v8, 1.0, v8
	s_nop 0
	v_rcp_f32_e32 v9, v8
	s_nop 0
	v_mul_f32_e32 v8, 1.0, v9
	global_store_dword v[64:65], v8, off offset:192
	v_add_f32_e32 v8, v143, v14
	v_mul_f32_e32 v8, 0xbfb8aa3b, v8
	v_exp_f32_e32 v8, v8
	s_nop 0
	v_add_f32_e32 v8, 1.0, v8
	s_nop 0
	v_rcp_f32_e32 v9, v8
	s_nop 0
	v_mul_f32_e32 v8, 1.0, v9
	v_mul_f32_e32 v8, 0xbf1b4598, v8
	v_mul_f32_e32 v8, 0x3fb8aa3b, v8
	v_exp_f32_e32 v8, v8
	global_store_dword v[58:59], v8, off offset:192
	v_add_f32_e32 v8, v144, v10
	v_mul_f32_e32 v8, 0xbfb8aa3b, v8
	v_exp_f32_e32 v8, v8
	s_nop 0
	v_add_f32_e32 v8, 1.0, v8
	s_nop 0
	v_rcp_f32_e32 v9, v8
	s_nop 0
	v_mul_f32_e32 v8, 1.0, v9
	global_store_dword v[52:53], v8, off offset:192
	v_add_f32_e32 v8, v143, v15
	v_mul_f32_e32 v8, 0xbfb8aa3b, v8
	v_exp_f32_e32 v8, v8
	s_nop 0
	v_add_f32_e32 v8, 1.0, v8
	s_nop 0
	v_rcp_f32_e32 v9, v8
	s_nop 0
	v_mul_f32_e32 v8, 1.0, v9
	v_mul_f32_e32 v8, 0xbf1b4598, v8
	v_mul_f32_e32 v8, 0x3fb8aa3b, v8
	v_exp_f32_e32 v8, v8
	global_store_dword v[48:49], v8, off offset:192
	v_add_f32_e32 v8, v144, v11
	v_mul_f32_e32 v8, 0xbfb8aa3b, v8
	v_exp_f32_e32 v8, v8
	s_nop 0
	v_add_f32_e32 v8, 1.0, v8
	s_nop 0
	v_rcp_f32_e32 v9, v8
	s_nop 0
	v_mul_f32_e32 v8, 1.0, v9
	global_store_dword v[42:43], v8, off offset:192
	s_waitcnt lgkmcnt(0)
	s_barrier
	s_and_b64 vcc, exec, s[44:45]
	s_cbranch_vccnz .LBB0_117
	s_mov_b32 s22, s48
	s_branch .LBB0_122

; __device__ __forceinline__ float bf2f(u16 v) { return __uint_as_float(((unsigned)v) << 16); }
; __device__ __forceinline__ float siluf_(float x) { return x / (1.f + __expf(-x)); }
; __device__ void phase_gdnprep(const P& p, int l, float* lds) {
;     ...
;   for (int row = blockIdx.x * 8 + wv; row < NT; row += nw) {
;     const int seq = row < NX ? 1 : 0;
;     const int RL = seq ? 64 : 256;
;     const int t = (seq ? row : row - NX) & (RL - 1);
;     const float ml = t != 0 ? 1.f : 0.f, mr = t != RL - 1 ? 1.f : 0.f;
;     const u16* pc = p.projb + (size_t)row * PROJP + O_DQKV;
;     const u16* pl = pc - (t != 0 ? PROJP : 0);
;     const u16* pn = pc + (t != RL - 1 ? PROJP : 0);
;     float x[24];
;     unsigned rc[24], rl[24], rr[24];
; #pragma unroll
;     for (int j = 0; j < 24; ++j) { const int c = j * 64 + lane; rc[j] = pc[c]; rl[j] = pl[c]; rr[j] = pn[c]; }
;     unsigned glo_raw = p.projb[(size_t)row * PROJP + O_GLO + (lane & 15)], dab_raw = p.projb[(size_t)row * PROJP + O_DA + (lane & 15)];
;     unsigned glq[4], glk[4];
; #pragma unroll
;     for (int j = 0; j < 4; ++j) { glq[j] = p.projb[(size_t)row * PROJP + O_GQ + j * 64 + lane]; glk[j] = p.projb[(size_t)row * PROJP + O_GK + j * 64 + lane]; }
;     ...
;       for (int j = 0; j < 8; ++j) {
;         float xc = bf2f((u16)rc[g8 * 8 + j]), xl = bf2f((u16)rl[g8 * 8 + j]) * ml, xr = bf2f((u16)rr[g8 * 8 + j]) * mr;
;         x[g8 * 8 + j] = siluf_(xl * w0[j] + xc * w1[j] + xr * w2[j]);
.LBB0_344:
	s_or_b64 exec, exec, s[0:1]
	v_lshlrev_b32_e32 v36, 16, v88
	v_lshlrev_b32_e32 v37, 16, v89
	v_mul_f32_e32 v37, v10, v37
	v_lshlrev_b32_e32 v38, 16, v87
	v_mul_f32_e32 v36, v113, v36
	v_mul_f32_e32 v38, v8, v38
	v_fmac_f32_e32 v36, v37, v111
	v_fmac_f32_e32 v36, v38, v114
	v_mul_f32_e32 v37, 0xbfb8aa3b, v36
	v_exp_f32_e32 v37, v37
	v_lshlrev_b32_e32 v13, 16, v13
	v_mul_f32_e32 v8, v8, v13
	global_store_short_d16_hi v[58:59], v9, off offset:768
	global_store_short_d16_hi v[58:59], v11, off offset:896
	global_store_short_d16_hi v[58:59], v34, off offset:1792
	global_store_short_d16_hi v[58:59], v35, off offset:1920
	v_add_f32_e32 v37, 1.0, v37
	v_add_u32_e32 v12, s46, v12
	s_add_u32 s60, s60, s52
	s_addc_u32 s61, s61, s53
	v_rcp_f32_e32 v38, v37
	s_nop 0
	v_mul_f32_e32 v36, v36, v38
	v_lshlrev_b32_e32 v37, 16, v85
	v_lshlrev_b32_e32 v38, 16, v86
	v_mul_f32_e32 v10, v10, v38
	v_mul_f32_e32 v13, v110, v37
	v_fmac_f32_e32 v13, v10, v33
	v_fmac_f32_e32 v13, v8, v112
	v_mul_f32_e32 v8, 0xbfb8aa3b, v13
	v_exp_f32_e32 v8, v8
	v_bfe_u32 v9, v36, 16, 1
	v_add3_u32 v9, v36, v9, s21
	global_store_short_d16_hi v[58:59], v9, off offset:2816
	v_add_f32_e32 v8, 1.0, v8
	s_movk_i32 s0, 0x43ff
	v_lshl_add_u64 v[18:19], v[18:19], 0, s[50:51]
	v_lshl_add_u64 v[22:23], v[22:23], 0, s[52:53]
	v_rcp_f32_e32 v10, v8
	s_nop 0
	v_mul_f32_e32 v8, v13, v10
	v_bfe_u32 v9, v8, 16, 1
	v_cmp_lt_i32_e32 vcc, s0, v12
	v_add3_u32 v8, v8, v9, s21
	v_lshl_add_u64 v[28:29], v[28:29], 0, s[54:55]
	v_lshl_add_u64 v[30:31], v[30:31], 0, s[56:57]
	s_or_b64 s[58:59], vcc, s[58:59]
	global_store_short_d16_hi v[58:59], v8, off offset:2944
	s_andn2_b64 exec, exec, s[58:59]
	s_cbranch_execz .LBB0_355
.LBB0_345:
	s_movk_i32 s2, 0x4000
	v_cmp_gt_i32_e32 vcc, s2, v12
	s_mov_b64 s[0:1], s[48:49]
	v_mov_b32_e32 v33, v129
	v_cndmask_b32_e64 v8, v184, 63, vcc
	v_and_b32_e32 v9, v8, v12
	v_cmp_eq_u32_e64 s[42:43], 0, v9
	v_cmp_eq_u32_e64 s[44:45], v9, v8
	v_lshl_add_u64 v[8:9], v[18:19], 0, v[26:27]
	v_cndmask_b32_e64 v11, -1, 0, s[42:43]
	v_cndmask_b32_e64 v10, v185, 0, s[42:43]
	v_cndmask_b32_e64 v128, v179, 0, s[44:45]
	v_add_co_u32_e32 v36, vcc, s96, v8
	v_lshl_add_u64 v[10:11], v[8:9], 0, v[10:11]
	v_lshl_add_u64 v[34:35], v[8:9], 0, v[128:129]
	v_addc_co_u32_e32 v37, vcc, 0, v9, vcc
	global_load_ushort v194, v[8:9], off offset:3104
	global_load_ushort v196, v[10:11], off offset:3104
	global_load_ushort v195, v[34:35], off offset:3104
	global_load_ushort v199, v[8:9], off offset:3232
	global_load_ushort v198, v[10:11], off offset:3232
	global_load_ushort v197, v[34:35], off offset:3232
	global_load_ushort v162, v[8:9], off offset:3360
	global_load_ushort v160, v[10:11], off offset:3360
	global_load_ushort v159, v[34:35], off offset:3360
	global_load_ushort v165, v[8:9], off offset:3488
	global_load_ushort v164, v[10:11], off offset:3488
	global_load_ushort v163, v[34:35], off offset:3488
	global_load_ushort v136, v[8:9], off offset:3616
	global_load_ushort v135, v[10:11], off offset:3616
	global_load_ushort v134, v[34:35], off offset:3616
	global_load_ushort v139, v[8:9], off offset:3744
	global_load_ushort v138, v[10:11], off offset:3744
	global_load_ushort v137, v[34:35], off offset:3744
	global_load_ushort v100, v[8:9], off offset:3872
	global_load_ushort v99, v[10:11], off offset:3872
	global_load_ushort v98, v[34:35], off offset:3872
	global_load_ushort v101, v[8:9], off offset:4000
	global_load_ushort v106, v[10:11], off offset:4000
	global_load_ushort v107, v[34:35], off offset:4000
	v_add_co_u32_e32 v10, vcc, s96, v10
	global_load_ushort v200, v[36:37], off offset:32
	s_nop 0
	v_addc_co_u32_e32 v11, vcc, 0, v11, vcc
	v_add_co_u32_e32 v34, vcc, s96, v34
	global_load_ushort v201, v[10:11], off offset:32
	s_nop 0
	v_addc_co_u32_e32 v35, vcc, 0, v35, vcc
	global_load_ushort v202, v[34:35], off offset:32
	global_load_ushort v205, v[36:37], off offset:160
	global_load_ushort v204, v[10:11], off offset:160
	global_load_ushort v203, v[34:35], off offset:160
	global_load_ushort v190, v[36:37], off offset:288
	global_load_ushort v167, v[10:11], off offset:288
	global_load_ushort v166, v[34:35], off offset:288
	global_load_ushort v193, v[36:37], off offset:416
	global_load_ushort v192, v[10:11], off offset:416
	global_load_ushort v191, v[34:35], off offset:416
	global_load_ushort v142, v[36:37], off offset:544
	global_load_ushort v141, v[10:11], off offset:544
	global_load_ushort v140, v[34:35], off offset:544
	global_load_ushort v145, v[36:37], off offset:672
	global_load_ushort v144, v[10:11], off offset:672
	global_load_ushort v143, v[34:35], off offset:672
	global_load_ushort v104, v[36:37], off offset:800
	global_load_ushort v103, v[10:11], off offset:800
	global_load_ushort v102, v[34:35], off offset:800
	global_load_ushort v105, v[36:37], off offset:928
	global_load_ushort v108, v[10:11], off offset:928
	global_load_ushort v109, v[34:35], off offset:928
	global_load_ushort v157, v[36:37], off offset:1056
	global_load_ushort v158, v[10:11], off offset:1056
	global_load_ushort v156, v[34:35], off offset:1056
	global_load_ushort v152, v[36:37], off offset:1184
	global_load_ushort v153, v[10:11], off offset:1184
	global_load_ushort v151, v[34:35], off offset:1184
	global_load_ushort v126, v[36:37], off offset:1312
	global_load_ushort v127, v[10:11], off offset:1312
	global_load_ushort v125, v[34:35], off offset:1312
	global_load_ushort v122, v[36:37], off offset:1440
	global_load_ushort v123, v[10:11], off offset:1440
	global_load_ushort v121, v[34:35], off offset:1440
	global_load_ushort v96, v[36:37], off offset:1568
	global_load_ushort v97, v[10:11], off offset:1568
	global_load_ushort v95, v[34:35], off offset:1568
	global_load_ushort v93, v[36:37], off offset:1696
	global_load_ushort v94, v[10:11], off offset:1696
	global_load_ushort v92, v[34:35], off offset:1696
	global_load_ushort v88, v[36:37], off offset:1824
	global_load_ushort v89, v[10:11], off offset:1824
	global_load_ushort v87, v[34:35], off offset:1824
	global_load_ushort v85, v[36:37], off offset:1952
	global_load_ushort v86, v[10:11], off offset:1952
	global_load_ushort v13, v[34:35], off offset:1952
	v_lshl_add_u64 v[34:35], v[18:19], 0, v[14:15]
	global_load_ushort v10, v[34:35], off offset:3072
	v_add_co_u32_e32 v34, vcc, s96, v34
	v_lshlrev_b32_e32 v128, 2, v16
	s_nop 0
	v_addc_co_u32_e32 v35, vcc, 0, v35, vcc
	global_load_ushort v11, v[34:35], off offset:3104
	global_load_ushort v207, v[8:9], off
	global_load_ushort v206, v[8:9], off offset:512
	global_load_ushort v147, v[8:9], off offset:128
	global_load_ushort v146, v[8:9], off offset:640
	global_load_ushort v116, v[8:9], off offset:256
	global_load_ushort v115, v[8:9], off offset:768
	global_load_ushort v90, v[8:9], off offset:384
	global_load_ushort v91, v[8:9], off offset:896
	s_mov_b32 s22, 0xbfb8aa3b
	s_mov_b32 s20, 0x800000
	s_mov_b32 s24, 0x3f317217
	s_mov_b32 s25, 0x7f800000
	s_waitcnt vmcnt(0)
; __device__ __forceinline__ float bf2f(u16 v) { return __uint_as_float(((unsigned)v) << 16); }
; __device__ __forceinline__ float siluf_(float x) { return x / (1.f + __expf(-x)); }
; #define PIN8(a, o) asm volatile("" : "+v"(a[o]), "+v"(a[o + 1]), "+v"(a[o + 2]), "+v"(a[o + 3]), "+v"(a[o + 4]), "+v"(a[o + 5]), "+v"(a[o + 6]), "+v"(a[o + 7]))
; #define PIN8(a) asm volatile("" : "+v"(a[0]), "+v"(a[1]), "+v"(a[2]), "+v"(a[3]))
; __device__ void phase_gdnprep(const P& p, int l, float* lds) {
;     ...
;     for (int g8 = 0; g8 < 3; ++g8) {
;       float w0[8], w1[8], w2[8];
;       const float* cwl = cw; asm volatile("" : "+s"(cwl));
; #pragma unroll
;       for (int j = 0; j < 8; ++j) { const int c = (g8 * 8 + j) * 64 + lane; w0[j] = cwl[c]; w1[j] = cwl[1536 + c]; w2[j] = cwl[3072 + c]; }
;       PIN8(w0, 0); PIN8(w1, 0); PIN8(w2, 0);
; #pragma unroll
;       for (int j = 0; j < 8; ++j) {
;         float xc = bf2f((u16)rc[g8 * 8 + j]), xl = bf2f((u16)rl[g8 * 8 + j]) * ml, xr = bf2f((u16)rr[g8 * 8 + j]) * mr;
;         x[g8 * 8 + j] = siluf_(xl * w0[j] + xc * w1[j] + xr * w2[j]);
;       }
;     }
;     ...
;     {
;       float glo = bf2f((u16)glo_raw);
;       float dab = bf2f((u16)dab_raw);
; #pragma unroll
;       for (int dir = 0; dir < 2; ++dir) {
;         float4 acc = abias[dir];
; #pragma unroll
;         for (int m = 0; m < 16; ++m) {
;           float g = rdlane(glo, m);
;           float4 w = *reinterpret_cast<const float4*>(aup_s + (dir * 16 + m) * 256 + lane * 4);
;           acc.x += g * w.x; acc.y += g * w.y; acc.z += g * w.z; acc.w += g * w.w;
;         }
	s_nop 0
	v_lshl_add_u64 v[8:9], s[0:1], 0, v[128:129]
	v_add_co_u32_e32 v34, vcc, s96, v8
	flat_load_dword v41, v[8:9] offset:1792
	flat_load_dword v40, v[8:9] offset:1536
	flat_load_dword v53, v[8:9] offset:1280
	flat_load_dword v52, v[8:9] offset:1024
	flat_load_dword v65, v[8:9] offset:768
	flat_load_dword v64, v[8:9] offset:512
	flat_load_dword v71, v[8:9] offset:256
	flat_load_dword v70, v[8:9]
	v_addc_co_u32_e32 v35, vcc, 0, v9, vcc
	v_add_co_u32_e32 v8, vcc, s75, v8
	flat_load_dword v43, v[34:35] offset:3840
	flat_load_dword v42, v[34:35] offset:3584
	flat_load_dword v55, v[34:35] offset:3328
	flat_load_dword v54, v[34:35] offset:3072
	flat_load_dword v67, v[34:35] offset:2816
	flat_load_dword v66, v[34:35] offset:2560
	flat_load_dword v73, v[34:35] offset:2304
	flat_load_dword v72, v[34:35] offset:2048
	v_addc_co_u32_e32 v9, vcc, 0, v9, vcc
	flat_load_dword v45, v[8:9] offset:1792
	flat_load_dword v44, v[8:9] offset:1536
	flat_load_dword v57, v[8:9] offset:1280
	flat_load_dword v56, v[8:9] offset:1024
	flat_load_dword v69, v[8:9] offset:768
	flat_load_dword v68, v[8:9] offset:512
	flat_load_dword v75, v[8:9] offset:256
	flat_load_dword v74, v[8:9]
	s_mov_b64 s[0:1], s[48:49]
	s_waitcnt vmcnt(0) lgkmcnt(0)
	s_nop 0
	v_lshl_add_u64 v[8:9], s[0:1], 0, v[128:129]
	v_add_co_u32_e32 v38, vcc, s78, v8
	flat_load_dword v35, v[8:9] offset:3840
	flat_load_dword v34, v[8:9] offset:3584
	flat_load_dword v47, v[8:9] offset:3328
	flat_load_dword v46, v[8:9] offset:3072
	flat_load_dword v59, v[8:9] offset:2816
	flat_load_dword v58, v[8:9] offset:2560
	flat_load_dword v77, v[8:9] offset:2304
	flat_load_dword v76, v[8:9] offset:2048
	v_addc_co_u32_e32 v39, vcc, 0, v9, vcc
	v_add_co_u32_e32 v8, vcc, s75, v8
	flat_load_dword v37, v[38:39] offset:1792
	flat_load_dword v36, v[38:39] offset:1536
	flat_load_dword v49, v[38:39] offset:1280
	flat_load_dword v48, v[38:39] offset:1024
	flat_load_dword v61, v[38:39] offset:768
	flat_load_dword v60, v[38:39] offset:512
	flat_load_dword v79, v[38:39] offset:256
	flat_load_dword v78, v[38:39]
	v_addc_co_u32_e32 v9, vcc, 0, v9, vcc
	flat_load_dword v39, v[8:9] offset:3840
	flat_load_dword v38, v[8:9] offset:3584
	flat_load_dword v51, v[8:9] offset:3328
	flat_load_dword v50, v[8:9] offset:3072
	flat_load_dword v63, v[8:9] offset:2816
	flat_load_dword v62, v[8:9] offset:2560
	flat_load_dword v81, v[8:9] offset:2304
	flat_load_dword v80, v[8:9] offset:2048
	s_mov_b64 s[0:1], s[48:49]
	s_waitcnt vmcnt(0) lgkmcnt(0)
	s_nop 0
	v_lshl_add_u64 v[214:215], s[0:1], 0, v[128:129]
	v_add_co_u32_e32 v112, vcc, s96, v214
	v_lshl_add_u64 v[8:9], s[0:1], 0, v[32:33]
	s_nop 0
	v_addc_co_u32_e32 v113, vcc, 0, v215, vcc
	v_add_co_u32_e32 v212, vcc, s78, v214
	flat_load_dword v33, v[112:113] offset:1792
	flat_load_dword v111, v[112:113] offset:1536
	flat_load_dword v117, v[112:113] offset:1280
	flat_load_dword v119, v[112:113] offset:1024
	flat_load_dword v148, v[112:113] offset:768
	flat_load_dword v150, v[112:113] offset:512
	flat_load_dword v208, v[112:113] offset:256
	flat_load_dword v210, v[8:9]
	v_addc_co_u32_e32 v213, vcc, 0, v215, vcc
	flat_load_dword v110, v[212:213] offset:3840
	flat_load_dword v113, v[212:213] offset:3584
	flat_load_dword v118, v[212:213] offset:3328
	flat_load_dword v124, v[212:213] offset:3072
	flat_load_dword v149, v[212:213] offset:2816
	flat_load_dword v155, v[212:213] offset:2560
	flat_load_dword v209, v[212:213] offset:2304
	v_add_co_u32_e32 v212, vcc, s96, v8
	s_nop 1
	v_addc_co_u32_e32 v213, vcc, 0, v9, vcc
	v_add_co_u32_e32 v214, vcc, s2, v214
	flat_load_dword v212, v[212:213] offset:2048
	s_nop 0
	v_addc_co_u32_e32 v215, vcc, 0, v215, vcc
	flat_load_dword v112, v[214:215] offset:1792
	flat_load_dword v114, v[214:215] offset:1536
	flat_load_dword v120, v[214:215] offset:1280
	flat_load_dword v128, v[214:215] offset:1024
	flat_load_dword v154, v[214:215] offset:768
	flat_load_dword v161, v[214:215] offset:512
	flat_load_dword v211, v[214:215] offset:256
	v_add_co_u32_e32 v8, vcc, s75, v8
	v_lshlrev_b32_e32 v215, 16, v10
	s_nop 0
	v_addc_co_u32_e32 v9, vcc, 0, v9, vcc
	flat_load_dword v213, v[8:9]
	s_waitcnt vmcnt(0) lgkmcnt(0)
	v_lshlrev_b32_e32 v214, 16, v11
	v_readlane_b32 s67, v215, 0
	v_readlane_b32 s65, v215, 1
	v_readlane_b32 s66, v215, 2
	v_readlane_b32 s63, v215, 3
	v_readlane_b32 s64, v215, 4
	v_readlane_b32 s47, v215, 5
	v_readlane_b32 s62, v215, 6
	v_readlane_b32 s31, v215, 7
	v_readlane_b32 s33, v215, 8
	v_readlane_b32 s28, v215, 9
	v_readlane_b32 s30, v215, 10
	v_readlane_b32 s26, v215, 11
	v_readlane_b32 s27, v215, 12
	v_readlane_b32 s3, v215, 13
	v_readlane_b32 s23, v215, 14
	v_readlane_b32 s2, v215, 15
	s_nop 1
	ds_read_b128 v[216:219], v83 offset:0
	ds_read_b128 v[244:247], v83 offset:1024
	ds_read_b128 v[248:251], v83 offset:2048
	ds_read_b128 v[252:255], v83 offset:3072
	s_waitcnt lgkmcnt(3)
	v_fma_f32 v8, s67, v216, v0
	v_fma_f32 v9, s67, v217, v1
	v_fma_f32 v10, s67, v218, v2
	v_fma_f32 v11, s67, v219, v3
	ds_read_b128 v[216:219], v83 offset:4096
	s_waitcnt lgkmcnt(3)
	v_fmac_f32_e32 v8, s65, v244
	v_fmac_f32_e32 v9, s65, v245
	v_fmac_f32_e32 v10, s65, v246
	v_fmac_f32_e32 v11, s65, v247
	ds_read_b128 v[244:247], v83 offset:5120
	s_waitcnt lgkmcnt(3)
	v_fmac_f32_e32 v8, s66, v248
	v_fmac_f32_e32 v9, s66, v249
	v_fmac_f32_e32 v10, s66, v250
	v_fmac_f32_e32 v11, s66, v251
	ds_read_b128 v[248:251], v83 offset:6144
	s_waitcnt lgkmcnt(3)
	v_fmac_f32_e32 v8, s63, v252
	v_fmac_f32_e32 v9, s63, v253
	v_fmac_f32_e32 v10, s63, v254
	v_fmac_f32_e32 v11, s63, v255
	ds_read_b128 v[252:255], v83 offset:7168
	s_waitcnt lgkmcnt(3)
; __device__ void phase_gdnprep(const P& p, int l, float* lds) {
;     ...
;       for (int dir = 0; dir < 2; ++dir) {
;         float4 acc = abias[dir];
; #pragma unroll
;         for (int m = 0; m < 16; ++m) {
;           float g = rdlane(glo, m);
;           float4 w = *reinterpret_cast<const float4*>(aup_s + (dir * 16 + m) * 256 + lane * 4);
;           acc.x += g * w.x; acc.y += g * w.y; acc.z += g * w.z; acc.w += g * w.w;
;         }
;         float4 f;
;         f.x = __expf((fminf(acc.x, 0.f) - __logf(1.f + __expf(-fabsf(acc.x)))) * (1.f / 16.f));
;         f.y = __expf((fminf(acc.y, 0.f) - __logf(1.f + __expf(-fabsf(acc.y)))) * (1.f / 16.f));
;         f.z = __expf((fminf(acc.z, 0.f) - __logf(1.f + __expf(-fabsf(acc.z)))) * (1.f / 16.f));
;         f.w = __expf((fminf(acc.w, 0.f) - __logf(1.f + __expf(-fabsf(acc.w)))) * (1.f / 16.f));
;         *reinterpret_cast<float4*>(p.glf + ((size_t)dir * NT + row) * 256 + lane * 4) = f;
	v_fmac_f32_e32 v8, s64, v216
	v_fmac_f32_e32 v9, s64, v217
	v_fmac_f32_e32 v10, s64, v218
	v_fmac_f32_e32 v11, s64, v219
	ds_read_b128 v[216:219], v83 offset:8192
	s_waitcnt lgkmcnt(3)
	v_fmac_f32_e32 v8, s47, v244
	v_fmac_f32_e32 v9, s47, v245
	v_fmac_f32_e32 v10, s47, v246
	v_fmac_f32_e32 v11, s47, v247
	ds_read_b128 v[244:247], v83 offset:9216
	s_waitcnt lgkmcnt(3)
	v_fmac_f32_e32 v8, s62, v248
	v_fmac_f32_e32 v9, s62, v249
	v_fmac_f32_e32 v10, s62, v250
	v_fmac_f32_e32 v11, s62, v251
	ds_read_b128 v[248:251], v83 offset:10240
	s_waitcnt lgkmcnt(3)
	v_fmac_f32_e32 v8, s31, v252
	v_fmac_f32_e32 v9, s31, v253
	v_fmac_f32_e32 v10, s31, v254
	v_fmac_f32_e32 v11, s31, v255
	ds_read_b128 v[252:255], v83 offset:11264
	s_waitcnt lgkmcnt(3)
	v_fmac_f32_e32 v8, s33, v216
	v_fmac_f32_e32 v9, s33, v217
	v_fmac_f32_e32 v10, s33, v218
	v_fmac_f32_e32 v11, s33, v219
	ds_read_b128 v[216:219], v83 offset:12288
	s_waitcnt lgkmcnt(3)
	v_fmac_f32_e32 v8, s28, v244
	v_fmac_f32_e32 v9, s28, v245
	v_fmac_f32_e32 v10, s28, v246
	v_fmac_f32_e32 v11, s28, v247
	ds_read_b128 v[244:247], v83 offset:13312
	s_waitcnt lgkmcnt(3)
	v_fmac_f32_e32 v8, s30, v248
	v_fmac_f32_e32 v9, s30, v249
	v_fmac_f32_e32 v10, s30, v250
	v_fmac_f32_e32 v11, s30, v251
	ds_read_b128 v[248:251], v83 offset:14336
	s_waitcnt lgkmcnt(3)
	v_fmac_f32_e32 v8, s26, v252
	v_fmac_f32_e32 v9, s26, v253
	v_fmac_f32_e32 v10, s26, v254
	v_fmac_f32_e32 v11, s26, v255
	ds_read_b128 v[252:255], v83 offset:15360
	s_waitcnt lgkmcnt(3)
	v_fmac_f32_e32 v8, s27, v216
	v_fmac_f32_e32 v9, s27, v217
	v_fmac_f32_e32 v10, s27, v218
	v_fmac_f32_e32 v11, s27, v219
	s_waitcnt lgkmcnt(2)
	v_fmac_f32_e32 v8, s3, v244
	v_fmac_f32_e32 v9, s3, v245
	v_fmac_f32_e32 v10, s3, v246
	v_fmac_f32_e32 v11, s3, v247
	s_waitcnt lgkmcnt(1)
	v_fmac_f32_e32 v8, s23, v248
	v_fmac_f32_e32 v9, s23, v249
	v_fmac_f32_e32 v10, s23, v250
	v_fmac_f32_e32 v11, s23, v251
	s_waitcnt lgkmcnt(0)
	v_fmac_f32_e32 v8, s2, v252
	v_fmac_f32_e32 v9, s2, v253
	v_fmac_f32_e32 v10, s2, v254
	v_fmac_f32_e32 v11, s2, v255
	v_min_f32_e32 v215, 0, v8
	v_mul_f32_e64 v8, |v8|, s22
	v_exp_f32_e32 v8, v8
	s_nop 0
	v_add_f32_e32 v8, 1.0, v8
	v_cmp_gt_f32_e32 vcc, s20, v8
	s_nop 1
	v_cndmask_b32_e64 v216, 0, 32, vcc
	v_ldexp_f32 v8, v8, v216
	v_log_f32_e32 v8, v8
	s_nop 0
	v_mul_f32_e32 v216, 0x3f317217, v8
	v_fma_f32 v216, v8, s24, -v216
	v_fmac_f32_e32 v216, 0x3377d1cf, v8
	v_fmac_f32_e32 v216, 0x3f317217, v8
	v_cmp_lt_f32_e64 s[0:1], |v8|, s25
	s_nop 1
	v_cndmask_b32_e64 v8, v8, v216, s[0:1]
	v_cndmask_b32_e32 v216, 0, v186, vcc
	v_sub_f32_e32 v8, v8, v216
	v_sub_f32_e32 v8, v215, v8
	v_min_f32_e32 v215, 0, v9
	v_mul_f32_e64 v9, |v9|, s22
	v_exp_f32_e32 v9, v9
	v_mul_f32_e32 v8, 0x3d800000, v8
	v_mul_f32_e32 v8, 0x3fb8aa3b, v8
	v_exp_f32_e32 v8, v8
	v_add_f32_e32 v9, 1.0, v9
	v_cmp_gt_f32_e32 vcc, s20, v9
	s_nop 1
	v_cndmask_b32_e64 v216, 0, 32, vcc
	v_ldexp_f32 v9, v9, v216
	v_log_f32_e32 v9, v9
	s_nop 0
	v_mul_f32_e32 v216, 0x3f317217, v9
	v_fma_f32 v216, v9, s24, -v216
	v_fmac_f32_e32 v216, 0x3377d1cf, v9
	v_fmac_f32_e32 v216, 0x3f317217, v9
	v_cmp_lt_f32_e64 s[0:1], |v9|, s25
	s_nop 1
	v_cndmask_b32_e64 v9, v9, v216, s[0:1]
	v_cndmask_b32_e32 v216, 0, v186, vcc
	v_sub_f32_e32 v9, v9, v216
	v_sub_f32_e32 v9, v215, v9
	v_min_f32_e32 v215, 0, v10
	v_mul_f32_e64 v10, |v10|, s22
	v_exp_f32_e32 v10, v10
	v_mul_f32_e32 v9, 0x3d800000, v9
	v_mul_f32_e32 v9, 0x3fb8aa3b, v9
	v_exp_f32_e32 v9, v9
	v_add_f32_e32 v10, 1.0, v10
	v_cmp_gt_f32_e32 vcc, s20, v10
	s_nop 1
	v_cndmask_b32_e64 v216, 0, 32, vcc
	v_ldexp_f32 v10, v10, v216
	v_log_f32_e32 v10, v10
	s_nop 0
	v_mul_f32_e32 v216, 0x3f317217, v10
	v_fma_f32 v216, v10, s24, -v216
	v_fmac_f32_e32 v216, 0x3377d1cf, v10
	v_fmac_f32_e32 v216, 0x3f317217, v10
	v_cmp_lt_f32_e64 s[0:1], |v10|, s25
	s_nop 1
	v_cndmask_b32_e64 v10, v10, v216, s[0:1]
	v_cndmask_b32_e32 v216, 0, v186, vcc
	v_sub_f32_e32 v10, v10, v216
	v_sub_f32_e32 v10, v215, v10
	v_min_f32_e32 v215, 0, v11
	v_mul_f32_e64 v11, |v11|, s22
	v_exp_f32_e32 v11, v11
	v_mul_f32_e32 v10, 0x3d800000, v10
	v_mul_f32_e32 v10, 0x3fb8aa3b, v10
	v_exp_f32_e32 v10, v10
	v_add_f32_e32 v11, 1.0, v11
	v_cmp_gt_f32_e32 vcc, s20, v11
	s_nop 1
	v_cndmask_b32_e64 v216, 0, 32, vcc
	v_ldexp_f32 v11, v11, v216
	v_log_f32_e32 v11, v11
	s_nop 0
	v_mul_f32_e32 v216, 0x3f317217, v11
	v_fma_f32 v216, v11, s24, -v216
	v_fmac_f32_e32 v216, 0x3377d1cf, v11
	v_fmac_f32_e32 v216, 0x3f317217, v11
	v_cmp_lt_f32_e64 s[0:1], |v11|, s25
	s_nop 1
	v_cndmask_b32_e64 v11, v11, v216, s[0:1]
	v_cndmask_b32_e32 v216, 0, v186, vcc
	v_sub_f32_e32 v11, v11, v216
	v_sub_f32_e32 v11, v215, v11
	v_mul_f32_e32 v11, 0x3d800000, v11
	v_mul_f32_e32 v11, 0x3fb8aa3b, v11
	v_exp_f32_e32 v11, v11
	global_store_dwordx4 v[30:31], v[8:11], off
	s_nop 0
	s_nop 1
	ds_read_b128 v[216:219], v83 offset:16384
	ds_read_b128 v[244:247], v83 offset:17408
	ds_read_b128 v[248:251], v83 offset:18432
	ds_read_b128 v[252:255], v83 offset:19456
	s_waitcnt lgkmcnt(3)
	v_fma_f32 v11, s67, v216, v4
	v_fma_f32 v10, s67, v217, v5
	v_fma_f32 v9, s67, v218, v6
	v_fma_f32 v8, s67, v219, v7
	ds_read_b128 v[216:219], v83 offset:20480
	s_waitcnt lgkmcnt(3)
	v_fmac_f32_e32 v11, s65, v244
	v_fmac_f32_e32 v10, s65, v245
	v_fmac_f32_e32 v9, s65, v246
	v_fmac_f32_e32 v8, s65, v247
	ds_read_b128 v[244:247], v83 offset:21504
	s_waitcnt lgkmcnt(3)
	v_fmac_f32_e32 v11, s66, v248
	v_fmac_f32_e32 v10, s66, v249
	v_fmac_f32_e32 v9, s66, v250
	v_fmac_f32_e32 v8, s66, v251
	ds_read_b128 v[248:251], v83 offset:22528
	s_waitcnt lgkmcnt(3)
	v_fmac_f32_e32 v11, s63, v252
	v_fmac_f32_e32 v10, s63, v253
	v_fmac_f32_e32 v9, s63, v254
	v_fmac_f32_e32 v8, s63, v255
	ds_read_b128 v[252:255], v83 offset:23552
	s_waitcnt lgkmcnt(3)
; __device__ void phase_gdnprep(const P& p, int l, float* lds) {
;     ...
;       for (int dir = 0; dir < 2; ++dir) {
;         float4 acc = abias[dir];
; #pragma unroll
;         for (int m = 0; m < 16; ++m) {
;           float g = rdlane(glo, m);
;           float4 w = *reinterpret_cast<const float4*>(aup_s + (dir * 16 + m) * 256 + lane * 4);
;           acc.x += g * w.x; acc.y += g * w.y; acc.z += g * w.z; acc.w += g * w.w;
;         }
;         float4 f;
;         f.x = __expf((fminf(acc.x, 0.f) - __logf(1.f + __expf(-fabsf(acc.x)))) * (1.f / 16.f));
;         f.y = __expf((fminf(acc.y, 0.f) - __logf(1.f + __expf(-fabsf(acc.y)))) * (1.f / 16.f));
;         f.z = __expf((fminf(acc.z, 0.f) - __logf(1.f + __expf(-fabsf(acc.z)))) * (1.f / 16.f));
;         f.w = __expf((fminf(acc.w, 0.f) - __logf(1.f + __expf(-fabsf(acc.w)))) * (1.f / 16.f));
;         *reinterpret_cast<float4*>(p.glf + ((size_t)dir * NT + row) * 256 + lane * 4) = f;
;       }
;       float db_v = __shfl(dab, (lane & 7) + 8);
	v_fmac_f32_e32 v11, s64, v216
	v_fmac_f32_e32 v10, s64, v217
	v_fmac_f32_e32 v9, s64, v218
	v_fmac_f32_e32 v8, s64, v219
	ds_read_b128 v[216:219], v83 offset:24576
	s_waitcnt lgkmcnt(3)
	v_fmac_f32_e32 v11, s47, v244
	v_fmac_f32_e32 v10, s47, v245
	v_fmac_f32_e32 v9, s47, v246
	v_fmac_f32_e32 v8, s47, v247
	ds_read_b128 v[244:247], v83 offset:25600
	s_waitcnt lgkmcnt(3)
	v_fmac_f32_e32 v11, s62, v248
	v_fmac_f32_e32 v10, s62, v249
	v_fmac_f32_e32 v9, s62, v250
	v_fmac_f32_e32 v8, s62, v251
	ds_read_b128 v[248:251], v83 offset:26624
	s_waitcnt lgkmcnt(3)
	v_fmac_f32_e32 v11, s31, v252
	v_fmac_f32_e32 v10, s31, v253
	v_fmac_f32_e32 v9, s31, v254
	v_fmac_f32_e32 v8, s31, v255
	ds_read_b128 v[252:255], v83 offset:27648
	s_waitcnt lgkmcnt(3)
	v_fmac_f32_e32 v11, s33, v216
	v_fmac_f32_e32 v10, s33, v217
	v_fmac_f32_e32 v9, s33, v218
	v_fmac_f32_e32 v8, s33, v219
	ds_read_b128 v[216:219], v83 offset:28672
	s_waitcnt lgkmcnt(3)
	v_fmac_f32_e32 v11, s28, v244
	v_fmac_f32_e32 v10, s28, v245
	v_fmac_f32_e32 v9, s28, v246
	v_fmac_f32_e32 v8, s28, v247
	ds_read_b128 v[244:247], v83 offset:29696
	s_waitcnt lgkmcnt(3)
	v_fmac_f32_e32 v11, s30, v248
	v_fmac_f32_e32 v10, s30, v249
	v_fmac_f32_e32 v9, s30, v250
	v_fmac_f32_e32 v8, s30, v251
	ds_read_b128 v[248:251], v83 offset:30720
	s_waitcnt lgkmcnt(3)
	v_fmac_f32_e32 v11, s26, v252
	v_fmac_f32_e32 v10, s26, v253
	v_fmac_f32_e32 v9, s26, v254
	v_fmac_f32_e32 v8, s26, v255
	ds_read_b128 v[252:255], v83 offset:31744
	s_waitcnt lgkmcnt(3)
	v_fmac_f32_e32 v11, s27, v216
	v_fmac_f32_e32 v10, s27, v217
	v_fmac_f32_e32 v9, s27, v218
	v_fmac_f32_e32 v8, s27, v219
	s_waitcnt lgkmcnt(2)
	v_fmac_f32_e32 v11, s3, v244
	v_fmac_f32_e32 v10, s3, v245
	v_fmac_f32_e32 v9, s3, v246
	v_fmac_f32_e32 v8, s3, v247
	s_waitcnt lgkmcnt(1)
	v_fmac_f32_e32 v11, s23, v248
	v_fmac_f32_e32 v10, s23, v249
	v_fmac_f32_e32 v9, s23, v250
	v_fmac_f32_e32 v8, s23, v251
	s_waitcnt lgkmcnt(0)
	v_fmac_f32_e32 v11, s2, v252
	v_fmac_f32_e32 v10, s2, v253
	v_fmac_f32_e32 v9, s2, v254
	v_fmac_f32_e32 v8, s2, v255
	s_mov_b32 s23, 0xbfb8aa3b
	v_min_f32_e32 v215, 0, v11
	v_mul_f32_e64 v11, |v11|, s22
	v_exp_f32_e32 v11, v11
	s_nop 0
	v_add_f32_e32 v11, 1.0, v11
	v_cmp_gt_f32_e32 vcc, s20, v11
	s_nop 1
	v_cndmask_b32_e64 v216, 0, 32, vcc
	v_ldexp_f32 v11, v11, v216
	v_log_f32_e32 v11, v11
	s_nop 0
	v_mul_f32_e32 v216, 0x3f317217, v11
	v_fma_f32 v216, v11, s24, -v216
	v_fmac_f32_e32 v216, 0x3377d1cf, v11
	v_fmac_f32_e32 v216, 0x3f317217, v11
	v_cmp_lt_f32_e64 s[0:1], |v11|, s25
	s_nop 1
	v_cndmask_b32_e64 v11, v11, v216, s[0:1]
	v_cndmask_b32_e32 v216, 0, v186, vcc
	v_sub_f32_e32 v11, v11, v216
	v_sub_f32_e32 v11, v215, v11
	v_mul_f32_e32 v11, 0x3d800000, v11
	v_mul_f32_e32 v11, 0x3fb8aa3b, v11
	v_exp_f32_e32 v216, v11
	v_min_f32_e32 v11, 0, v10
	v_mul_f32_e64 v10, |v10|, s22
	v_exp_f32_e32 v10, v10
	s_nop 0
	v_add_f32_e32 v10, 1.0, v10
	v_cmp_gt_f32_e32 vcc, s20, v10
	s_nop 1
	v_cndmask_b32_e64 v215, 0, 32, vcc
	v_ldexp_f32 v10, v10, v215
	v_log_f32_e32 v10, v10
	s_nop 0
	v_mul_f32_e32 v215, 0x3f317217, v10
	v_fma_f32 v215, v10, s24, -v215
	v_fmac_f32_e32 v215, 0x3377d1cf, v10
	v_fmac_f32_e32 v215, 0x3f317217, v10
	v_cmp_lt_f32_e64 s[0:1], |v10|, s25
	s_nop 1
	v_cndmask_b32_e64 v10, v10, v215, s[0:1]
	v_cndmask_b32_e32 v215, 0, v186, vcc
	v_sub_f32_e32 v10, v10, v215
	v_sub_f32_e32 v10, v11, v10
	v_mul_f32_e32 v10, 0x3d800000, v10
	v_mul_f32_e32 v10, 0x3fb8aa3b, v10
	v_exp_f32_e32 v217, v10
	v_min_f32_e32 v10, 0, v9
	v_mul_f32_e64 v9, |v9|, s22
	v_exp_f32_e32 v9, v9
	s_nop 0
	v_add_f32_e32 v9, 1.0, v9
	v_cmp_gt_f32_e32 vcc, s20, v9
	s_nop 1
	v_cndmask_b32_e64 v11, 0, 32, vcc
	v_ldexp_f32 v9, v9, v11
	v_log_f32_e32 v9, v9
	s_nop 0
	v_mul_f32_e32 v11, 0x3f317217, v9
	v_fma_f32 v11, v9, s24, -v11
	v_fmac_f32_e32 v11, 0x3377d1cf, v9
	v_fmac_f32_e32 v11, 0x3f317217, v9
	v_cmp_lt_f32_e64 s[0:1], |v9|, s25
	s_nop 1
	v_cndmask_b32_e64 v9, v9, v11, s[0:1]
	v_cndmask_b32_e32 v11, 0, v186, vcc
	v_sub_f32_e32 v9, v9, v11
	v_sub_f32_e32 v9, v10, v9
	v_mul_f32_e32 v9, 0x3d800000, v9
	v_mul_f32_e32 v9, 0x3fb8aa3b, v9
	v_exp_f32_e32 v218, v9
	v_min_f32_e32 v9, 0, v8
	v_mul_f32_e64 v8, |v8|, s22
	v_exp_f32_e32 v8, v8
	s_nop 0
	v_add_f32_e32 v8, 1.0, v8
	v_cmp_gt_f32_e32 vcc, s20, v8
	s_mov_b32 s20, 0x7f800000
	s_nop 0
	v_cndmask_b32_e64 v10, 0, 32, vcc
	v_ldexp_f32 v8, v8, v10
	v_log_f32_e32 v8, v8
	s_nop 0
	v_mul_f32_e32 v10, 0x3f317217, v8
	v_fma_f32 v10, v8, s24, -v10
	v_fmac_f32_e32 v10, 0x3377d1cf, v8
	v_fmac_f32_e32 v10, 0x3f317217, v8
	v_cmp_lt_f32_e64 s[0:1], |v8|, s25
	s_nop 1
	v_cndmask_b32_e64 v8, v8, v10, s[0:1]
	v_cndmask_b32_e32 v10, 0, v186, vcc
	v_sub_f32_e32 v8, v8, v10
	v_sub_f32_e32 v8, v9, v8
	v_mul_f32_e32 v8, 0x3d800000, v8
	v_mul_f32_e32 v8, 0x3fb8aa3b, v8
	v_exp_f32_e32 v219, v8
	v_add_co_u32_e32 v8, vcc, 0x1100000, v30
	s_nop 1
	v_addc_co_u32_e32 v9, vcc, 0, v31, vcc
	global_store_dwordx4 v[8:9], v[216:219], off
	v_and_or_b32 v8, v173, 64, v84
	v_lshlrev_b32_e32 v8, 2, v8
	ds_bpermute_b32 v8, v8, v214
	s_and_saveexec_b64 s[2:3], s[38:39]
	s_cbranch_execz .LBB0_347
; __device__ __forceinline__ float sigmoidf_(float x) { return 1.f / (1.f + __expf(-x)); }
; __device__ __forceinline__ float softplusf_(float x) { return fmaxf(x, 0.f) + log1pf(__expf(-fabsf(x))); }
; __device__ void phase_gdnprep(const P& p, int l, float* lds) {
;     ...
;       float db_v = __shfl(dab, (lane & 7) + 8);
;       float a_v = fmaxf(__expf(-gA * softplusf_(dab + gdt)), 1e-9f);
;       float b_v = sigmoidf_(db_v);
;       if (lane < 8) *reinterpret_cast<float2*>(p.gab + (((size_t)(lane >> 2) * NT + row) * 4 + (lane & 3)) * 2) = make_float2(a_v, b_v);
	s_waitcnt lgkmcnt(0)
	v_mul_f32_e32 v8, 0xbfb8aa3b, v8
	v_exp_f32_e32 v8, v8
	s_nop 0
	v_add_f32_e32 v8, 1.0, v8
	s_mov_b32 s0, 0x33800000
	v_rcp_f32_e32 v9, v8
	s_nop 0
	v_mul_f32_e32 v9, 1.0, v9
	v_add_f32_e32 v8, v17, v214
	v_max_f32_e32 v214, 0, v8
	v_mul_f32_e64 v8, |v8|, s23
	v_exp_f32_e32 v8, v8
	s_nop 0
	v_add_f32_e32 v215, 1.0, v8
	v_cvt_f64_f32_e32 v[10:11], v215
	v_cmp_lt_f32_e64 vcc, |v8|, s0
	v_frexp_exp_i32_f64_e32 v10, v[10:11]
	v_frexp_mant_f32_e32 v11, v215
	s_mov_b32 s0, 0x3f2aaaab
	v_cmp_gt_f32_e64 s[0:1], s0, v11
	v_add_f32_e32 v220, -1.0, v215
	v_sub_f32_e32 v221, v8, v220
	v_subbrev_co_u32_e64 v10, s[0:1], 0, v10, s[0:1]
	v_cvt_f32_i32_e32 v11, v10
	v_sub_u32_e32 v10, 0, v10
	v_ldexp_f32 v218, v215, v10
	v_sub_f32_e32 v215, v220, v215
	v_add_f32_e32 v215, 1.0, v215
	v_add_f32_e32 v219, -1.0, v218
	v_add_f32_e32 v215, v221, v215
	v_add_f32_e32 v221, 1.0, v218
	v_ldexp_f32 v10, v215, v10
	v_add_f32_e32 v215, 1.0, v219
	v_add_f32_e32 v222, -1.0, v221
	v_sub_f32_e32 v215, v218, v215
	v_sub_f32_e32 v218, v218, v222
	v_add_f32_e32 v215, v10, v215
	v_add_f32_e32 v10, v10, v218
	v_add_f32_e32 v218, v221, v10
	v_rcp_f32_e32 v222, v218
	v_add_f32_e32 v220, v219, v215
	v_sub_f32_e32 v221, v218, v221
	v_sub_f32_e32 v10, v10, v221
	v_mul_f32_e32 v223, v220, v222
	v_mul_f32_e32 v224, v218, v223
	v_fma_f32 v221, v223, v218, -v224
	v_fmac_f32_e32 v221, v223, v10
	v_add_f32_e32 v225, v224, v221
	v_sub_f32_e32 v226, v220, v225
	v_sub_f32_e32 v219, v220, v219
	v_sub_f32_e32 v215, v215, v219
	v_sub_f32_e32 v219, v220, v226
	v_sub_f32_e32 v224, v225, v224
	v_sub_f32_e32 v219, v219, v225
	v_sub_f32_e32 v221, v224, v221
	v_add_f32_e32 v215, v215, v219
	v_add_f32_e32 v215, v221, v215
	v_add_f32_e32 v219, v226, v215
	v_mul_f32_e32 v220, v222, v219
	v_mul_f32_e32 v224, v218, v220
	v_fma_f32 v218, v220, v218, -v224
	v_add_f32_e32 v221, v223, v220
	v_fmac_f32_e32 v218, v220, v10
	v_sub_f32_e32 v223, v221, v223
	v_add_f32_e32 v10, v224, v218
	v_sub_f32_e32 v223, v220, v223
	v_sub_f32_e32 v220, v219, v10
	v_sub_f32_e32 v224, v10, v224
	v_sub_f32_e32 v218, v224, v218
	v_sub_f32_e32 v224, v226, v219
	v_sub_f32_e32 v219, v219, v220
	v_add_f32_e32 v215, v215, v224
	v_sub_f32_e32 v10, v219, v10
	v_add_f32_e32 v10, v215, v10
	v_add_f32_e32 v10, v218, v10
	v_add_f32_e32 v10, v220, v10
	v_mul_f32_e32 v10, v222, v10
	v_add_f32_e32 v10, v223, v10
	v_add_f32_e32 v215, v221, v10
	v_mul_f32_e32 v219, v215, v215
	v_fmamk_f32 v222, v219, 0x3e9b6dac, v171
	v_mul_f32_e32 v220, v215, v219
	v_fmaak_f32 v219, v219, v222, 0x3f2aaada
	v_ldexp_f32 v218, v215, 1
	v_mul_f32_e32 v219, v220, v219
	v_add_f32_e32 v220, v218, v219
	v_sub_f32_e32 v215, v215, v221
	v_mul_f32_e32 v216, 0x3f317218, v11
	s_mov_b32 s0, 0x3f317218
	v_sub_f32_e32 v10, v10, v215
	v_sub_f32_e32 v215, v220, v218
	v_fma_f32 v217, v11, s0, -v216
	v_ldexp_f32 v10, v10, 1
	v_sub_f32_e32 v215, v219, v215
	v_fmac_f32_e32 v217, 0xb102e308, v11
	v_add_f32_e32 v10, v10, v215
	v_add_f32_e32 v11, v216, v217
	v_add_f32_e32 v215, v220, v10
	v_add_f32_e32 v218, v11, v215
	v_sub_f32_e32 v216, v11, v216
	v_sub_f32_e32 v216, v217, v216
	v_sub_f32_e32 v217, v215, v220
	v_sub_f32_e32 v219, v218, v11
	v_sub_f32_e32 v10, v10, v217
	v_sub_f32_e32 v215, v215, v219
	v_sub_f32_e32 v219, v218, v219
	v_add_f32_e32 v217, v216, v10
	v_sub_f32_e32 v11, v11, v219
	v_add_f32_e32 v11, v215, v11
	v_sub_f32_e32 v219, v217, v216
	v_add_f32_e32 v11, v217, v11
	v_sub_f32_e32 v217, v217, v219
	v_add_f32_e32 v215, v218, v11
	v_sub_f32_e32 v10, v10, v219
	v_sub_f32_e32 v216, v216, v217
	v_add_f32_e32 v10, v10, v216
	v_sub_f32_e32 v216, v215, v218
	v_sub_f32_e32 v11, v11, v216
	v_add_f32_e32 v10, v10, v11
	v_add_f32_e32 v10, v215, v10
	v_cmp_neq_f32_e64 s[0:1], s20, v8
	s_nop 1
	v_cndmask_b32_e64 v10, v187, v10, s[0:1]
	v_cmp_ngt_f32_e64 s[0:1], -1.0, v8
	s_nop 1
	v_cndmask_b32_e64 v10, v188, v10, s[0:1]
	v_cmp_neq_f32_e64 s[0:1], -1.0, v8
	s_nop 1
	v_cndmask_b32_e64 v10, v189, v10, s[0:1]
	v_cndmask_b32_e32 v8, v10, v8, vcc
	v_add_f32_e32 v8, v214, v8
	v_mul_f32_e32 v8, v8, v82
	v_mul_f32_e32 v8, 0xbfb8aa3b, v8
	v_exp_f32_e32 v8, v8
	v_lshl_add_u64 v[10:11], v[22:23], 0, v[24:25]
	v_max_f32_e32 v8, 0x3089705f, v8
	global_store_dwordx2 v[10:11], v[8:9], off offset:-4
; __device__ __forceinline__ float bf2f(u16 v) { return __uint_as_float(((unsigned)v) << 16); }
; __device__ __forceinline__ float siluf_(float x) { return x / (1.f + __expf(-x)); }
; __device__ void phase_gdnprep(const P& p, int l, float* lds) {
;     ...
; #pragma unroll
;       for (int j = 0; j < 8; ++j) {
;         float xc = bf2f((u16)rc[g8 * 8 + j]), xl = bf2f((u16)rl[g8 * 8 + j]) * ml, xr = bf2f((u16)rr[g8 * 8 + j]) * mr;
;         x[g8 * 8 + j] = siluf_(xl * w0[j] + xc * w1[j] + xr * w2[j]);
;       }
;     }
;     ...
;     for (int hh = 0; hh < 4; ++hh) {
;       float qs = wave_sum_b(x[2 * hh] * x[2 * hh] + x[2 * hh + 1] * x[2 * hh + 1]);
;       float ks = wave_sum_b(x[8 + 2 * hh] * x[8 + 2 * hh] + x[8 + 2 * hh + 1] * x[8 + 2 * hh + 1]);
;       float qn = rsqrtf(qs + 1e-6f) * 0.08838834764831845f, kn = rsqrtf(ks + 1e-6f);
;       u16 q0b = f2bf(x[2 * hh] * qn), q1b = f2bf(x[2 * hh + 1] * qn), k0b = f2bf(x[8 + 2 * hh] * kn), k1b = f2bf(x[8 + 2 * hh + 1] * kn);
;       float kqd = wave_sum_b(bf2f(k0b) * bf2f(q0b) + bf2f(k1b) * bf2f(q1b));
;       float kql = wave_sum_b(bf2f((u16)glq[hh]) * 0.125f * bf2f((u16)glk[hh]));
;       if (lane == 0) { p.kqa[(size_t)row * 8 + hh] = kqd; p.kqa[(size_t)row * 8 + 4 + hh] = kql; }
.LBB0_347:
	s_or_b64 exec, exec, s[2:3]
	v_cndmask_b32_e64 v10, 1.0, 0, s[42:43]
	v_lshlrev_b32_e32 v214, 16, v194
	v_lshlrev_b32_e32 v215, 16, v199
	v_lshlrev_b32_e32 v216, 16, v196
	v_lshlrev_b32_e32 v217, 16, v198
	s_waitcnt lgkmcnt(0)
	v_cndmask_b32_e64 v8, 1.0, 0, s[44:45]
	v_pk_mul_f32 v[198:199], v[10:11], v[216:217] op_sel_hi:[0,1]
	v_lshlrev_b32_e32 v194, 16, v195
	v_lshlrev_b32_e32 v195, 16, v197
	v_pk_mul_f32 v[72:73], v[72:73], v[214:215]
	v_pk_mul_f32 v[194:195], v[8:9], v[194:195] op_sel_hi:[0,1]
	v_pk_fma_f32 v[70:71], v[198:199], v[70:71], v[72:73]
	v_lshlrev_b32_e32 v196, 16, v202
	v_pk_fma_f32 v[70:71], v[194:195], v[74:75], v[70:71]
	v_lshlrev_b32_e32 v195, 16, v204
	v_mul_f32_e32 v9, 0xbfb8aa3b, v70
	v_exp_f32_e32 v72, v9
	v_mul_f32_e32 v9, 0xbfb8aa3b, v71
	v_exp_f32_e32 v73, v9
	v_lshlrev_b32_e32 v197, 16, v203
	v_pk_add_f32 v[72:73], v[72:73], 1.0 op_sel_hi:[1,0]
	s_nop 0
	v_div_scale_f32 v198, s[0:1], v72, v72, v70
	v_rcp_f32_e32 v199, v198
	v_rcp_f32_e32 v9, v73
	s_nop 0
	v_mul_f32_e32 v73, v71, v9
	v_fma_f32 v9, -v198, v199, 1.0
	v_fmac_f32_e32 v199, v9, v199
	v_div_scale_f32 v9, vcc, v70, v72, v70
	v_mul_f32_e32 v11, v9, v199
	v_lshlrev_b32_e32 v74, 16, v200
	v_lshlrev_b32_e32 v75, 16, v205
	v_lshlrev_b32_e32 v194, 16, v201
	v_pk_mul_f32 v[194:195], v[10:11], v[194:195] op_sel_hi:[0,1]
	v_pk_mul_f32 v[74:75], v[78:79], v[74:75]
	v_pk_mul_f32 v[196:197], v[8:9], v[196:197] op_sel_hi:[0,1]
	v_pk_fma_f32 v[74:75], v[194:195], v[76:77], v[74:75]
	s_nop 0
	v_pk_fma_f32 v[74:75], v[196:197], v[80:81], v[74:75]
	s_nop 0
	v_mul_f32_e32 v71, 0xbfb8aa3b, v74
	v_exp_f32_e32 v76, v71
	v_mul_f32_e32 v71, 0xbfb8aa3b, v75
	v_exp_f32_e32 v77, v71
	v_fma_f32 v71, -v198, v11, v9
	v_fmac_f32_e32 v11, v71, v199
	v_fma_f32 v9, -v198, v11, v9
	v_pk_add_f32 v[76:77], v[76:77], 1.0 op_sel_hi:[1,0]
	v_div_fmas_f32 v9, v9, v199, v11
	v_div_fixup_f32 v72, v9, v72, v70
	v_rcp_f32_e32 v9, v77
	s_nop 0
	v_mul_f32_e32 v75, v75, v9
	v_rcp_f32_e32 v9, v76
	s_nop 0
	v_mul_f32_e32 v74, v74, v9
	v_pk_mul_f32 v[76:77], v[72:73], v[72:73]
	v_mov_b32_e32 v11, v129
	v_add_f32_e32 v9, v76, v77
	v_pk_mul_f32 v[76:77], v[74:75], v[74:75]
	v_lshl_add_u64 v[70:71], s[60:61], 0, v[20:21]
	v_add_f32_dpp v9, v9, v9 quad_perm:[1,0,3,2] row_mask:0xf bank_mask:0xf bound_ctrl:1
	s_nop 1
	v_add_f32_dpp v9, v9, v9 quad_perm:[2,3,0,1] row_mask:0xf bank_mask:0xf bound_ctrl:1
	s_nop 1
	v_add_f32_dpp v9, v9, v9 row_half_mirror row_mask:0xf bank_mask:0xf bound_ctrl:1
	s_nop 1
	v_add_f32_dpp v9, v9, v9 row_mirror row_mask:0xf bank_mask:0xf bound_ctrl:1
	s_nop 1
	v_mov_b32_dpp v11, v9 row_bcast:15 row_mask:0xa bank_mask:0xf
	v_add_f32_e32 v9, v9, v11
	v_mov_b32_e32 v11, v129
	s_nop 1
	v_mov_b32_dpp v11, v9 row_bcast:31 row_mask:0xc bank_mask:0xf
	v_add_f32_e32 v9, v9, v11
	v_mov_b32_e32 v11, v129
	v_readlane_b32 s0, v9, 63
	v_add_f32_e32 v9, v76, v77
	s_nop 1
	v_add_f32_dpp v9, v9, v9 quad_perm:[1,0,3,2] row_mask:0xf bank_mask:0xf bound_ctrl:1
	s_nop 1
	v_add_f32_dpp v9, v9, v9 quad_perm:[2,3,0,1] row_mask:0xf bank_mask:0xf bound_ctrl:1
	s_nop 1
	v_add_f32_dpp v9, v9, v9 row_half_mirror row_mask:0xf bank_mask:0xf bound_ctrl:1
	s_nop 1
	v_add_f32_dpp v9, v9, v9 row_mirror row_mask:0xf bank_mask:0xf bound_ctrl:1
	s_nop 1
	v_mov_b32_dpp v11, v9 row_bcast:15 row_mask:0xa bank_mask:0xf
	v_add_f32_e32 v9, v9, v11
	v_mov_b32_e32 v11, v129
	s_nop 1
	v_mov_b32_dpp v11, v9 row_bcast:31 row_mask:0xc bank_mask:0xf
	v_add_f32_e32 v9, v9, v11
	s_nop 0
	v_readlane_b32 s1, v9, 63
	v_add_f32_e32 v9, s0, v169
	s_mov_b32 s0, 0x800000
	v_mul_f32_e32 v11, 0x4b800000, v9
	v_cmp_gt_f32_e32 vcc, s0, v9
	s_nop 1
	v_cndmask_b32_e32 v9, v9, v11, vcc
	v_rsq_f32_e32 v9, v9
	v_add_f32_e32 v11, s1, v169
	v_mul_f32_e32 v76, 0x4b800000, v11
	v_cmp_gt_f32_e64 s[0:1], s0, v11
	s_nop 1
	v_cndmask_b32_e64 v11, v11, v76, s[0:1]
	v_rsq_f32_e32 v11, v11
	v_mul_f32_e32 v76, 0x45800000, v9
	v_cndmask_b32_e32 v9, v9, v76, vcc
	v_mul_f32_e32 v9, 0x3db504f3, v9
	v_mul_f32_e32 v76, 0x45800000, v11
	v_mul_f32_e32 v72, v72, v9
	v_mul_f32_e32 v9, v73, v9
	v_cndmask_b32_e64 v11, v11, v76, s[0:1]
	v_bfe_u32 v73, v9, 16, 1
	v_add3_u32 v73, v9, v73, s21
	v_mul_f32_e32 v9, v74, v11
	v_bfe_u32 v74, v9, 16, 1
	v_add3_u32 v74, v9, v74, s21
	v_mul_f32_e32 v9, v75, v11
	v_bfe_u32 v11, v9, 16, 1
	v_bfe_u32 v76, v72, 16, 1
	v_add3_u32 v75, v9, v11, s21
	v_add3_u32 v72, v72, v76, s21
	v_and_b32_e32 v76, 0xffff0000, v75
	v_and_b32_e32 v77, 0xffff0000, v73
	v_and_b32_e32 v9, 0xffff0000, v74
	v_and_b32_e32 v11, 0xffff0000, v72
	v_mul_f32_e32 v76, v77, v76
	v_fmac_f32_e32 v76, v11, v9
	v_mov_b32_e32 v11, v129
	s_nop 0
	v_add_f32_dpp v9, v76, v76 quad_perm:[1,0,3,2] row_mask:0xf bank_mask:0xf bound_ctrl:1
	s_nop 1
	v_add_f32_dpp v9, v9, v9 quad_perm:[2,3,0,1] row_mask:0xf bank_mask:0xf bound_ctrl:1
	s_nop 1
	v_add_f32_dpp v9, v9, v9 row_half_mirror row_mask:0xf bank_mask:0xf bound_ctrl:1
	s_nop 1
	v_add_f32_dpp v9, v9, v9 row_mirror row_mask:0xf bank_mask:0xf bound_ctrl:1
	s_nop 1
	v_mov_b32_dpp v11, v9 row_bcast:15 row_mask:0xa bank_mask:0xf
	v_add_f32_e32 v9, v9, v11
	v_mov_b32_e32 v11, v129
	s_nop 1
	v_mov_b32_dpp v11, v9 row_bcast:31 row_mask:0xc bank_mask:0xf
	v_add_f32_e32 v9, v9, v11
	v_lshlrev_b32_e32 v11, 16, v206
	v_readlane_b32 s2, v9, 63
	v_lshlrev_b32_e32 v9, 16, v207
	v_mul_f32_e32 v9, 0x3e000000, v9
	v_mul_f32_e32 v76, v9, v11
	s_nop 1
	v_mov_b32_dpp v76, v76 quad_perm:[1,0,3,2] row_mask:0xf bank_mask:0xf bound_ctrl:1
	v_fmac_f32_e32 v76, v9, v11
	v_mov_b32_e32 v11, v129
	s_nop 0
	v_add_f32_dpp v9, v76, v76 quad_perm:[2,3,0,1] row_mask:0xf bank_mask:0xf bound_ctrl:1
	s_nop 1
	v_add_f32_dpp v9, v9, v9 row_half_mirror row_mask:0xf bank_mask:0xf bound_ctrl:1
	s_nop 1
	v_add_f32_dpp v9, v9, v9 row_mirror row_mask:0xf bank_mask:0xf bound_ctrl:1
	s_nop 1
	v_mov_b32_dpp v11, v9 row_bcast:15 row_mask:0xa bank_mask:0xf
	v_add_f32_e32 v9, v9, v11
	v_mov_b32_e32 v11, v129
	s_nop 1
	v_mov_b32_dpp v11, v9 row_bcast:31 row_mask:0xc bank_mask:0xf
	v_add_f32_e32 v9, v9, v11
	s_nop 0
	v_readlane_b32 s3, v9, 63
	s_and_saveexec_b64 s[0:1], s[40:41]
	s_cbranch_execz .LBB0_349
	v_mov_b32_e32 v9, s2
	global_store_dword v[70:71], v9, off
	v_mov_b32_e32 v9, s3
	global_store_dword v[70:71], v9, off offset:16
; __device__ __forceinline__ float bf2f(u16 v) { return __uint_as_float(((unsigned)v) << 16); }
; __device__ __forceinline__ float siluf_(float x) { return x / (1.f + __expf(-x)); }
; __device__ void phase_gdnprep(const P& p, int l, float* lds) {
;     ...
; #pragma unroll
;       for (int j = 0; j < 8; ++j) {
;         float xc = bf2f((u16)rc[g8 * 8 + j]), xl = bf2f((u16)rl[g8 * 8 + j]) * ml, xr = bf2f((u16)rr[g8 * 8 + j]) * mr;
;         x[g8 * 8 + j] = siluf_(xl * w0[j] + xc * w1[j] + xr * w2[j]);
;       }
;     }
;     ...
;     for (int hh = 0; hh < 4; ++hh) {
;       float qs = wave_sum_b(x[2 * hh] * x[2 * hh] + x[2 * hh + 1] * x[2 * hh + 1]);
;       float ks = wave_sum_b(x[8 + 2 * hh] * x[8 + 2 * hh] + x[8 + 2 * hh + 1] * x[8 + 2 * hh + 1]);
;       float qn = rsqrtf(qs + 1e-6f) * 0.08838834764831845f, kn = rsqrtf(ks + 1e-6f);
;       u16 q0b = f2bf(x[2 * hh] * qn), q1b = f2bf(x[2 * hh + 1] * qn), k0b = f2bf(x[8 + 2 * hh] * kn), k1b = f2bf(x[8 + 2 * hh + 1] * kn);
;       float kqd = wave_sum_b(bf2f(k0b) * bf2f(q0b) + bf2f(k1b) * bf2f(q1b));
;       float kql = wave_sum_b(bf2f((u16)glq[hh]) * 0.125f * bf2f((u16)glk[hh]));
;       if (lane == 0) { p.kqa[(size_t)row * 8 + hh] = kqd; p.kqa[(size_t)row * 8 + 4 + hh] = kql; }
;       dst[(2 * hh) * 64 + lane] = q0b; dst[(2 * hh + 1) * 64 + lane] = q1b;
;       dst[512 + (2 * hh) * 64 + lane] = k0b; dst[512 + (2 * hh + 1) * 64 + lane] = k1b;
;       dst[1024 + (2 * hh) * 64 + lane] = f2bf(x[16 + 2 * hh]); dst[1024 + (2 * hh + 1) * 64 + lane] = f2bf(x[16 + 2 * hh + 1]);
.LBB0_349:
	s_or_b64 exec, exec, s[0:1]
	v_mov_b32_e32 v11, v10
	v_lshlrev_b32_e32 v76, 16, v162
	v_lshlrev_b32_e32 v77, 16, v165
	v_lshlrev_b32_e32 v78, 16, v160
	v_lshlrev_b32_e32 v79, 16, v164
	v_mov_b32_e32 v9, v8
	v_pk_mul_f32 v[78:79], v[10:11], v[78:79]
	v_lshlrev_b32_e32 v80, 16, v159
	v_lshlrev_b32_e32 v81, 16, v163
	v_pk_mul_f32 v[66:67], v[66:67], v[76:77]
	v_pk_mul_f32 v[80:81], v[8:9], v[80:81]
	v_pk_fma_f32 v[64:65], v[78:79], v[64:65], v[66:67]
	s_nop 0
	v_pk_fma_f32 v[64:65], v[80:81], v[68:69], v[64:65]
	s_nop 0
	v_mul_f32_e32 v66, 0xbfb8aa3b, v64
	v_mul_f32_e32 v67, 0xbfb8aa3b, v65
	v_exp_f32_e32 v66, v66
	v_exp_f32_e32 v67, v67
	s_nop 0
	v_pk_add_f32 v[66:67], v[66:67], 1.0 op_sel_hi:[1,0]
	s_nop 0
	s_nop 0
	v_rcp_f32_e32 v68, v67
	s_nop 0
	v_mul_f32_e32 v65, v65, v68
	s_nop 0
	v_rcp_f32_e32 v67, v66
	s_nop 0
	v_mul_f32_e32 v64, v64, v67
	v_lshlrev_b32_e32 v66, 16, v190
	v_lshlrev_b32_e32 v67, 16, v193
	v_lshlrev_b32_e32 v68, 16, v167
	v_lshlrev_b32_e32 v69, 16, v192
	v_pk_mul_f32 v[68:69], v[10:11], v[68:69]
	v_lshlrev_b32_e32 v76, 16, v166
	v_lshlrev_b32_e32 v77, 16, v191
	v_pk_mul_f32 v[60:61], v[60:61], v[66:67]
	v_pk_mul_f32 v[76:77], v[8:9], v[76:77]
	v_pk_fma_f32 v[58:59], v[68:69], v[58:59], v[60:61]
	s_nop 0
	v_pk_fma_f32 v[58:59], v[76:77], v[62:63], v[58:59]
	s_nop 0
	v_mul_f32_e32 v60, 0xbfb8aa3b, v58
	v_mul_f32_e32 v61, 0xbfb8aa3b, v59
	v_exp_f32_e32 v60, v60
	v_exp_f32_e32 v61, v61
	s_nop 0
	v_pk_add_f32 v[60:61], v[60:61], 1.0 op_sel_hi:[1,0]
	s_nop 0
	s_nop 0
	v_rcp_f32_e32 v62, v61
	s_nop 0
	v_mul_f32_e32 v61, v59, v62
	s_nop 0
	v_rcp_f32_e32 v59, v60
	s_nop 0
	v_mul_f32_e32 v60, v58, v59
	v_lshlrev_b32_e32 v58, 16, v157
	v_lshlrev_b32_e32 v59, 16, v158
	v_mul_f32_e32 v59, v10, v59
	v_lshlrev_b32_e32 v62, 16, v156
	v_mul_f32_e32 v58, v212, v58
	v_mul_f32_e32 v62, v8, v62
	v_fmac_f32_e32 v58, v59, v210
	v_fmac_f32_e32 v58, v62, v213
	v_mul_f32_e32 v59, 0xbfb8aa3b, v58
	v_exp_f32_e32 v59, v59
	s_nop 0
	v_add_f32_e32 v59, 1.0, v59
	s_nop 0
	v_rcp_f32_e32 v62, v59
	s_nop 0
	v_mul_f32_e32 v62, v58, v62
	v_lshlrev_b32_e32 v58, 16, v152
	v_lshlrev_b32_e32 v59, 16, v153
	v_mul_f32_e32 v59, v10, v59
	v_lshlrev_b32_e32 v63, 16, v151
	v_mul_f32_e32 v58, v209, v58
	v_mul_f32_e32 v63, v8, v63
	v_fmac_f32_e32 v58, v59, v208
	v_fmac_f32_e32 v58, v63, v211
	v_mul_f32_e32 v59, 0xbfb8aa3b, v58
	v_exp_f32_e32 v59, v59
	s_nop 0
	v_add_f32_e32 v59, 1.0, v59
	s_nop 0
	v_bfe_u32 v66, v62, 16, 1
	v_rcp_f32_e32 v63, v59
	s_nop 0
	v_mul_f32_e32 v63, v58, v63
	v_lshl_add_u64 v[58:59], v[28:29], 0, v[26:27]
	v_add3_u32 v62, v62, v66, s21
	global_store_short_d16_hi v[58:59], v72, off
	global_store_short_d16_hi v[58:59], v73, off offset:128
	global_store_short_d16_hi v[58:59], v74, off offset:1024
	global_store_short_d16_hi v[58:59], v75, off offset:1152
	global_store_short_d16_hi v[58:59], v62, off offset:2048
	v_bfe_u32 v62, v63, 16, 1
	v_add3_u32 v62, v63, v62, s21
	global_store_short_d16_hi v[58:59], v62, off offset:2176
	v_pk_mul_f32 v[62:63], v[64:65], v[64:65]
	s_nop 0
	v_add_f32_e32 v62, v62, v63
	v_mov_b32_e32 v63, v129
	s_nop 0
	v_add_f32_dpp v62, v62, v62 quad_perm:[1,0,3,2] row_mask:0xf bank_mask:0xf bound_ctrl:1
	s_nop 1
	v_add_f32_dpp v62, v62, v62 quad_perm:[2,3,0,1] row_mask:0xf bank_mask:0xf bound_ctrl:1
	s_nop 1
	v_add_f32_dpp v62, v62, v62 row_half_mirror row_mask:0xf bank_mask:0xf bound_ctrl:1
	s_nop 1
	v_add_f32_dpp v62, v62, v62 row_mirror row_mask:0xf bank_mask:0xf bound_ctrl:1
	s_nop 1
	v_mov_b32_dpp v63, v62 row_bcast:15 row_mask:0xa bank_mask:0xf
	v_add_f32_e32 v62, v62, v63
	v_mov_b32_e32 v63, v129
	s_nop 1
	v_mov_b32_dpp v63, v62 row_bcast:31 row_mask:0xc bank_mask:0xf
	v_add_f32_e32 v62, v62, v63
	s_nop 0
	v_readlane_b32 s0, v62, 63
	v_pk_mul_f32 v[62:63], v[60:61], v[60:61]
	s_nop 0
	v_add_f32_e32 v62, v62, v63
	v_mov_b32_e32 v63, v129
	s_nop 0
	v_add_f32_dpp v62, v62, v62 quad_perm:[1,0,3,2] row_mask:0xf bank_mask:0xf bound_ctrl:1
	s_nop 1
	v_add_f32_dpp v62, v62, v62 quad_perm:[2,3,0,1] row_mask:0xf bank_mask:0xf bound_ctrl:1
	s_nop 1
	v_add_f32_dpp v62, v62, v62 row_half_mirror row_mask:0xf bank_mask:0xf bound_ctrl:1
	s_nop 1
	v_add_f32_dpp v62, v62, v62 row_mirror row_mask:0xf bank_mask:0xf bound_ctrl:1
	s_nop 1
	v_mov_b32_dpp v63, v62 row_bcast:15 row_mask:0xa bank_mask:0xf
	v_add_f32_e32 v62, v62, v63
	v_mov_b32_e32 v63, v129
	s_nop 1
	v_mov_b32_dpp v63, v62 row_bcast:31 row_mask:0xc bank_mask:0xf
	v_add_f32_e32 v62, v62, v63
	s_nop 0
	v_readlane_b32 s1, v62, 63
	v_add_f32_e32 v62, s0, v169
	s_mov_b32 s0, 0x800000
	v_cmp_gt_f32_e32 vcc, s0, v62
	v_mul_f32_e32 v63, 0x4b800000, v62
	s_nop 0
	v_cndmask_b32_e32 v62, v62, v63, vcc
	v_rsq_f32_e32 v62, v62
	s_nop 0
	v_mul_f32_e32 v63, 0x45800000, v62
	v_cndmask_b32_e32 v62, v62, v63, vcc
	v_mul_f32_e32 v63, 0x3db504f3, v62
	v_add_f32_e32 v62, s1, v169
	v_cmp_gt_f32_e32 vcc, s0, v62
	v_mul_f32_e32 v66, 0x4b800000, v62
	s_nop 0
	v_cndmask_b32_e32 v62, v62, v66, vcc
	v_rsq_f32_e32 v62, v62
	s_nop 0
	v_mul_f32_e32 v66, 0x45800000, v62
	v_cndmask_b32_e32 v66, v62, v66, vcc
	v_mul_f32_e32 v62, v64, v63
	v_bfe_u32 v64, v62, 16, 1
	v_mul_f32_e32 v63, v65, v63
	v_add3_u32 v62, v62, v64, s21
	v_bfe_u32 v64, v63, 16, 1
	v_mul_f32_e32 v60, v60, v66
	v_add3_u32 v63, v63, v64, s21
	v_bfe_u32 v64, v60, 16, 1
	v_mul_f32_e32 v61, v61, v66
	v_add3_u32 v60, v60, v64, s21
	v_bfe_u32 v64, v61, 16, 1
	v_add3_u32 v61, v61, v64, s21
	v_and_b32_e32 v66, 0xffff0000, v61
	v_and_b32_e32 v67, 0xffff0000, v63
	v_and_b32_e32 v64, 0xffff0000, v60
	v_and_b32_e32 v65, 0xffff0000, v62
	v_mul_f32_e32 v66, v67, v66
	v_fmac_f32_e32 v66, v65, v64
	v_mov_b32_e32 v65, v129
	s_nop 0
; __device__ __forceinline__ float bf2f(u16 v) { return __uint_as_float(((unsigned)v) << 16); }
; __device__ __forceinline__ float siluf_(float x) { return x / (1.f + __expf(-x)); }
; __device__ void phase_gdnprep(const P& p, int l, float* lds) {
;     ...
; #pragma unroll
;       for (int j = 0; j < 8; ++j) {
;         float xc = bf2f((u16)rc[g8 * 8 + j]), xl = bf2f((u16)rl[g8 * 8 + j]) * ml, xr = bf2f((u16)rr[g8 * 8 + j]) * mr;
;         x[g8 * 8 + j] = siluf_(xl * w0[j] + xc * w1[j] + xr * w2[j]);
;       }
;     }
;     ...
;     for (int hh = 0; hh < 4; ++hh) {
;       float qs = wave_sum_b(x[2 * hh] * x[2 * hh] + x[2 * hh + 1] * x[2 * hh + 1]);
;       float ks = wave_sum_b(x[8 + 2 * hh] * x[8 + 2 * hh] + x[8 + 2 * hh + 1] * x[8 + 2 * hh + 1]);
;       float qn = rsqrtf(qs + 1e-6f) * 0.08838834764831845f, kn = rsqrtf(ks + 1e-6f);
;       u16 q0b = f2bf(x[2 * hh] * qn), q1b = f2bf(x[2 * hh + 1] * qn), k0b = f2bf(x[8 + 2 * hh] * kn), k1b = f2bf(x[8 + 2 * hh + 1] * kn);
;       float kqd = wave_sum_b(bf2f(k0b) * bf2f(q0b) + bf2f(k1b) * bf2f(q1b));
;       float kql = wave_sum_b(bf2f((u16)glq[hh]) * 0.125f * bf2f((u16)glk[hh]));
;       if (lane == 0) { p.kqa[(size_t)row * 8 + hh] = kqd; p.kqa[(size_t)row * 8 + 4 + hh] = kql; }
;       dst[(2 * hh) * 64 + lane] = q0b; dst[(2 * hh + 1) * 64 + lane] = q1b;
;       dst[512 + (2 * hh) * 64 + lane] = k0b; dst[512 + (2 * hh + 1) * 64 + lane] = k1b;
;       dst[1024 + (2 * hh) * 64 + lane] = f2bf(x[16 + 2 * hh]); dst[1024 + (2 * hh + 1) * 64 + lane] = f2bf(x[16 + 2 * hh + 1]);
	v_add_f32_dpp v64, v66, v66 quad_perm:[1,0,3,2] row_mask:0xf bank_mask:0xf bound_ctrl:1
	s_nop 1
	v_add_f32_dpp v64, v64, v64 quad_perm:[2,3,0,1] row_mask:0xf bank_mask:0xf bound_ctrl:1
	s_nop 1
	v_add_f32_dpp v64, v64, v64 row_half_mirror row_mask:0xf bank_mask:0xf bound_ctrl:1
	s_nop 1
	v_add_f32_dpp v64, v64, v64 row_mirror row_mask:0xf bank_mask:0xf bound_ctrl:1
	s_nop 1
	v_mov_b32_dpp v65, v64 row_bcast:15 row_mask:0xa bank_mask:0xf
	v_add_f32_e32 v64, v64, v65
	v_mov_b32_e32 v65, v129
	s_nop 1
	v_mov_b32_dpp v65, v64 row_bcast:31 row_mask:0xc bank_mask:0xf
	v_add_f32_e32 v64, v64, v65
	v_lshlrev_b32_e32 v65, 16, v146
	v_readlane_b32 s2, v64, 63
	v_lshlrev_b32_e32 v64, 16, v147
	v_mul_f32_e32 v64, 0x3e000000, v64
	v_mul_f32_e32 v66, v64, v65
	s_nop 1
	v_mov_b32_dpp v66, v66 quad_perm:[1,0,3,2] row_mask:0xf bank_mask:0xf bound_ctrl:1
	v_fmac_f32_e32 v66, v64, v65
	v_mov_b32_e32 v65, v129
	s_nop 0
	v_add_f32_dpp v64, v66, v66 quad_perm:[2,3,0,1] row_mask:0xf bank_mask:0xf bound_ctrl:1
	s_nop 1
	v_add_f32_dpp v64, v64, v64 row_half_mirror row_mask:0xf bank_mask:0xf bound_ctrl:1
	s_nop 1
	v_add_f32_dpp v64, v64, v64 row_mirror row_mask:0xf bank_mask:0xf bound_ctrl:1
	s_nop 1
	v_mov_b32_dpp v65, v64 row_bcast:15 row_mask:0xa bank_mask:0xf
	v_add_f32_e32 v64, v64, v65
	v_mov_b32_e32 v65, v129
	s_nop 1
	v_mov_b32_dpp v65, v64 row_bcast:31 row_mask:0xc bank_mask:0xf
	v_add_f32_e32 v64, v64, v65
	s_nop 0
	v_readlane_b32 s3, v64, 63
	s_and_saveexec_b64 s[0:1], s[40:41]
	v_readlane_b32 s70, v238, 38
	v_readlane_b32 s71, v238, 39
	s_movk_i32 s33, 0x3600
	s_cbranch_execz .LBB0_351
	v_mov_b32_e32 v64, s2
	global_store_dword v[70:71], v64, off offset:4
	v_mov_b32_e32 v64, s3
	global_store_dword v[70:71], v64, off offset:20
.LBB0_351:
	s_or_b64 exec, exec, s[0:1]
	v_lshlrev_b32_e32 v64, 16, v136
	v_lshlrev_b32_e32 v65, 16, v139
	v_lshlrev_b32_e32 v66, 16, v135
	v_lshlrev_b32_e32 v67, 16, v138
	v_pk_mul_f32 v[66:67], v[10:11], v[66:67]
	v_lshlrev_b32_e32 v68, 16, v134
	v_lshlrev_b32_e32 v69, 16, v137
	v_pk_mul_f32 v[54:55], v[54:55], v[64:65]
	v_pk_mul_f32 v[68:69], v[8:9], v[68:69]
	v_pk_fma_f32 v[52:53], v[66:67], v[52:53], v[54:55]
	global_store_short_d16_hi v[58:59], v62, off offset:256
	global_store_short_d16_hi v[58:59], v63, off offset:384
	global_store_short_d16_hi v[58:59], v60, off offset:1280
	global_store_short_d16_hi v[58:59], v61, off offset:1408
	v_pk_fma_f32 v[52:53], v[68:69], v[56:57], v[52:53]
	s_nop 0
	v_mul_f32_e32 v54, 0xbfb8aa3b, v52
	v_mul_f32_e32 v55, 0xbfb8aa3b, v53
	v_exp_f32_e32 v54, v54
	v_exp_f32_e32 v55, v55
	s_nop 0
	v_pk_add_f32 v[54:55], v[54:55], 1.0 op_sel_hi:[1,0]
	s_nop 0
	s_nop 0
	v_rcp_f32_e32 v56, v55
	s_nop 0
	v_mul_f32_e32 v53, v53, v56
	s_nop 0
	v_rcp_f32_e32 v55, v54
	s_nop 0
	v_mul_f32_e32 v52, v52, v55
	v_lshlrev_b32_e32 v54, 16, v142
	v_lshlrev_b32_e32 v55, 16, v145
	v_lshlrev_b32_e32 v56, 16, v141
	v_lshlrev_b32_e32 v57, 16, v144
	v_pk_mul_f32 v[56:57], v[10:11], v[56:57]
	v_lshlrev_b32_e32 v64, 16, v140
	v_lshlrev_b32_e32 v65, 16, v143
	v_pk_mul_f32 v[48:49], v[48:49], v[54:55]
	v_pk_mul_f32 v[64:65], v[8:9], v[64:65]
	v_pk_fma_f32 v[46:47], v[56:57], v[46:47], v[48:49]
	s_nop 0
	v_pk_fma_f32 v[46:47], v[64:65], v[50:51], v[46:47]
	s_nop 0
	v_mul_f32_e32 v48, 0xbfb8aa3b, v46
	v_mul_f32_e32 v49, 0xbfb8aa3b, v47
	v_exp_f32_e32 v48, v48
	v_exp_f32_e32 v49, v49
	s_nop 0
	v_pk_add_f32 v[48:49], v[48:49], 1.0 op_sel_hi:[1,0]
	s_nop 0
	s_nop 0
	v_rcp_f32_e32 v50, v49
	s_nop 0
	v_mul_f32_e32 v47, v47, v50
	s_nop 0
	v_rcp_f32_e32 v49, v48
	s_nop 0
	v_mul_f32_e32 v46, v46, v49
	v_lshlrev_b32_e32 v48, 16, v126
	v_lshlrev_b32_e32 v49, 16, v127
	v_mul_f32_e32 v49, v10, v49
	v_lshlrev_b32_e32 v50, 16, v125
	v_mul_f32_e32 v48, v155, v48
	v_mul_f32_e32 v50, v8, v50
	v_fmac_f32_e32 v48, v49, v150
	v_fmac_f32_e32 v48, v50, v161
	v_mul_f32_e32 v49, 0xbfb8aa3b, v48
	v_exp_f32_e32 v49, v49
	s_nop 0
	v_add_f32_e32 v49, 1.0, v49
	s_nop 0
	v_rcp_f32_e32 v50, v49
	s_nop 0
	v_mul_f32_e32 v48, v48, v50
	v_lshlrev_b32_e32 v49, 16, v122
	v_lshlrev_b32_e32 v50, 16, v123
	v_mul_f32_e32 v50, v10, v50
	v_lshlrev_b32_e32 v51, 16, v121
	v_mul_f32_e32 v49, v149, v49
	v_mul_f32_e32 v51, v8, v51
	v_fmac_f32_e32 v49, v50, v148
	v_fmac_f32_e32 v49, v51, v154
	v_mul_f32_e32 v50, 0xbfb8aa3b, v49
	v_exp_f32_e32 v50, v50
	s_nop 0
	v_add_f32_e32 v50, 1.0, v50
	s_nop 0
	v_rcp_f32_e32 v51, v50
	s_nop 0
	v_mul_f32_e32 v49, v49, v51
	v_bfe_u32 v50, v48, 16, 1
	v_add3_u32 v48, v48, v50, s21
	global_store_short_d16_hi v[58:59], v48, off offset:2304
	v_bfe_u32 v48, v49, 16, 1
	v_add3_u32 v48, v49, v48, s21
	global_store_short_d16_hi v[58:59], v48, off offset:2432
	v_pk_mul_f32 v[48:49], v[52:53], v[52:53]
	s_nop 0
	v_add_f32_e32 v48, v48, v49
	v_mov_b32_e32 v49, v129
	s_nop 0
	v_add_f32_dpp v48, v48, v48 quad_perm:[1,0,3,2] row_mask:0xf bank_mask:0xf bound_ctrl:1
	s_nop 1
	v_add_f32_dpp v48, v48, v48 quad_perm:[2,3,0,1] row_mask:0xf bank_mask:0xf bound_ctrl:1
	s_nop 1
	v_add_f32_dpp v48, v48, v48 row_half_mirror row_mask:0xf bank_mask:0xf bound_ctrl:1
	s_nop 1
	v_add_f32_dpp v48, v48, v48 row_mirror row_mask:0xf bank_mask:0xf bound_ctrl:1
	s_nop 1
	v_mov_b32_dpp v49, v48 row_bcast:15 row_mask:0xa bank_mask:0xf
	v_add_f32_e32 v48, v48, v49
	v_mov_b32_e32 v49, v129
	s_nop 1
	v_mov_b32_dpp v49, v48 row_bcast:31 row_mask:0xc bank_mask:0xf
	v_add_f32_e32 v48, v48, v49
	s_nop 0
	v_readlane_b32 s0, v48, 63
	v_pk_mul_f32 v[48:49], v[46:47], v[46:47]
	s_nop 0
	v_add_f32_e32 v48, v48, v49
	v_mov_b32_e32 v49, v129
	s_nop 0
	v_add_f32_dpp v48, v48, v48 quad_perm:[1,0,3,2] row_mask:0xf bank_mask:0xf bound_ctrl:1
	s_nop 1
; __device__ __forceinline__ float bf2f(u16 v) { return __uint_as_float(((unsigned)v) << 16); }
; __device__ __forceinline__ float siluf_(float x) { return x / (1.f + __expf(-x)); }
; __device__ void phase_gdnprep(const P& p, int l, float* lds) {
;     ...
; #pragma unroll
;       for (int j = 0; j < 8; ++j) {
;         float xc = bf2f((u16)rc[g8 * 8 + j]), xl = bf2f((u16)rl[g8 * 8 + j]) * ml, xr = bf2f((u16)rr[g8 * 8 + j]) * mr;
;         x[g8 * 8 + j] = siluf_(xl * w0[j] + xc * w1[j] + xr * w2[j]);
;       }
;     }
;     ...
;     for (int hh = 0; hh < 4; ++hh) {
;       float qs = wave_sum_b(x[2 * hh] * x[2 * hh] + x[2 * hh + 1] * x[2 * hh + 1]);
;       float ks = wave_sum_b(x[8 + 2 * hh] * x[8 + 2 * hh] + x[8 + 2 * hh + 1] * x[8 + 2 * hh + 1]);
;       float qn = rsqrtf(qs + 1e-6f) * 0.08838834764831845f, kn = rsqrtf(ks + 1e-6f);
;       u16 q0b = f2bf(x[2 * hh] * qn), q1b = f2bf(x[2 * hh + 1] * qn), k0b = f2bf(x[8 + 2 * hh] * kn), k1b = f2bf(x[8 + 2 * hh + 1] * kn);
;       float kqd = wave_sum_b(bf2f(k0b) * bf2f(q0b) + bf2f(k1b) * bf2f(q1b));
;       float kql = wave_sum_b(bf2f((u16)glq[hh]) * 0.125f * bf2f((u16)glk[hh]));
;       if (lane == 0) { p.kqa[(size_t)row * 8 + hh] = kqd; p.kqa[(size_t)row * 8 + 4 + hh] = kql; }
;       dst[(2 * hh) * 64 + lane] = q0b; dst[(2 * hh + 1) * 64 + lane] = q1b;
;       dst[512 + (2 * hh) * 64 + lane] = k0b; dst[512 + (2 * hh + 1) * 64 + lane] = k1b;
;       dst[1024 + (2 * hh) * 64 + lane] = f2bf(x[16 + 2 * hh]); dst[1024 + (2 * hh + 1) * 64 + lane] = f2bf(x[16 + 2 * hh + 1]);
	v_add_f32_dpp v48, v48, v48 quad_perm:[2,3,0,1] row_mask:0xf bank_mask:0xf bound_ctrl:1
	s_nop 1
	v_add_f32_dpp v48, v48, v48 row_half_mirror row_mask:0xf bank_mask:0xf bound_ctrl:1
	s_nop 1
	v_add_f32_dpp v48, v48, v48 row_mirror row_mask:0xf bank_mask:0xf bound_ctrl:1
	s_nop 1
	v_mov_b32_dpp v49, v48 row_bcast:15 row_mask:0xa bank_mask:0xf
	v_add_f32_e32 v48, v48, v49
	v_mov_b32_e32 v49, v129
	s_nop 1
	v_mov_b32_dpp v49, v48 row_bcast:31 row_mask:0xc bank_mask:0xf
	v_add_f32_e32 v48, v48, v49
	s_nop 0
	v_readlane_b32 s1, v48, 63
	v_add_f32_e32 v48, s0, v169
	s_mov_b32 s0, 0x800000
	v_cmp_gt_f32_e32 vcc, s0, v48
	v_mul_f32_e32 v49, 0x4b800000, v48
	s_nop 0
	v_cndmask_b32_e32 v48, v48, v49, vcc
	v_rsq_f32_e32 v48, v48
	s_nop 0
	v_mul_f32_e32 v49, 0x45800000, v48
	v_cndmask_b32_e32 v48, v48, v49, vcc
	v_mul_f32_e32 v49, 0x3db504f3, v48
	v_add_f32_e32 v48, s1, v169
	v_cmp_gt_f32_e32 vcc, s0, v48
	v_mul_f32_e32 v50, 0x4b800000, v48
	s_nop 0
	v_cndmask_b32_e32 v48, v48, v50, vcc
	v_rsq_f32_e32 v48, v48
	s_nop 0
	v_mul_f32_e32 v50, 0x45800000, v48
	v_cndmask_b32_e32 v50, v48, v50, vcc
	v_mul_f32_e32 v48, v52, v49
	v_bfe_u32 v51, v48, 16, 1
	v_mul_f32_e32 v49, v53, v49
	v_mul_f32_e32 v47, v47, v50
	v_add3_u32 v48, v48, v51, s21
	v_bfe_u32 v51, v49, 16, 1
	v_mul_f32_e32 v46, v46, v50
	v_bfe_u32 v50, v47, 16, 1
	v_add3_u32 v49, v49, v51, s21
	v_bfe_u32 v51, v46, 16, 1
	v_add3_u32 v47, v47, v50, s21
	v_add3_u32 v46, v46, v51, s21
	v_and_b32_e32 v52, 0xffff0000, v47
	v_and_b32_e32 v53, 0xffff0000, v49
	v_and_b32_e32 v50, 0xffff0000, v46
	v_and_b32_e32 v51, 0xffff0000, v48
	v_mul_f32_e32 v52, v53, v52
	v_fmac_f32_e32 v52, v51, v50
	v_mov_b32_e32 v51, v129
	s_nop 0
	v_add_f32_dpp v50, v52, v52 quad_perm:[1,0,3,2] row_mask:0xf bank_mask:0xf bound_ctrl:1
	s_nop 1
	v_add_f32_dpp v50, v50, v50 quad_perm:[2,3,0,1] row_mask:0xf bank_mask:0xf bound_ctrl:1
	s_nop 1
	v_add_f32_dpp v50, v50, v50 row_half_mirror row_mask:0xf bank_mask:0xf bound_ctrl:1
	s_nop 1
	v_add_f32_dpp v50, v50, v50 row_mirror row_mask:0xf bank_mask:0xf bound_ctrl:1
	s_nop 1
	v_mov_b32_dpp v51, v50 row_bcast:15 row_mask:0xa bank_mask:0xf
	v_add_f32_e32 v50, v50, v51
	v_mov_b32_e32 v51, v129
	s_nop 1
	v_mov_b32_dpp v51, v50 row_bcast:31 row_mask:0xc bank_mask:0xf
	v_add_f32_e32 v50, v50, v51
	v_lshlrev_b32_e32 v51, 16, v115
	v_readlane_b32 s2, v50, 63
	v_lshlrev_b32_e32 v50, 16, v116
	v_mul_f32_e32 v50, 0x3e000000, v50
	v_mul_f32_e32 v52, v50, v51
	s_nop 1
	v_mov_b32_dpp v52, v52 quad_perm:[1,0,3,2] row_mask:0xf bank_mask:0xf bound_ctrl:1
	v_fmac_f32_e32 v52, v50, v51
	v_mov_b32_e32 v51, v129
	s_nop 0
	v_add_f32_dpp v50, v52, v52 quad_perm:[2,3,0,1] row_mask:0xf bank_mask:0xf bound_ctrl:1
	s_nop 1
	v_add_f32_dpp v50, v50, v50 row_half_mirror row_mask:0xf bank_mask:0xf bound_ctrl:1
	s_nop 1
	v_add_f32_dpp v50, v50, v50 row_mirror row_mask:0xf bank_mask:0xf bound_ctrl:1
	s_nop 1
	v_mov_b32_dpp v51, v50 row_bcast:15 row_mask:0xa bank_mask:0xf
	v_add_f32_e32 v50, v50, v51
	v_mov_b32_e32 v51, v129
	s_nop 1
	v_mov_b32_dpp v51, v50 row_bcast:31 row_mask:0xc bank_mask:0xf
	v_add_f32_e32 v50, v50, v51
	s_nop 0
	v_readlane_b32 s3, v50, 63
	s_and_saveexec_b64 s[0:1], s[40:41]
	s_cbranch_execz .LBB0_353
	v_mov_b32_e32 v50, s2
	global_store_dword v[70:71], v50, off offset:8
	v_mov_b32_e32 v50, s3
	global_store_dword v[70:71], v50, off offset:24
.LBB0_353:
	s_or_b64 exec, exec, s[0:1]
	v_lshlrev_b32_e32 v50, 16, v100
	v_lshlrev_b32_e32 v51, 16, v101
	v_lshlrev_b32_e32 v52, 16, v99
	v_lshlrev_b32_e32 v53, 16, v106
	v_pk_mul_f32 v[52:53], v[10:11], v[52:53]
	v_lshlrev_b32_e32 v54, 16, v98
	v_lshlrev_b32_e32 v55, 16, v107
	v_pk_mul_f32 v[42:43], v[42:43], v[50:51]
	v_pk_mul_f32 v[54:55], v[8:9], v[54:55]
	v_pk_fma_f32 v[40:41], v[52:53], v[40:41], v[42:43]
	global_store_short_d16_hi v[58:59], v48, off offset:512
	global_store_short_d16_hi v[58:59], v49, off offset:640
	global_store_short_d16_hi v[58:59], v46, off offset:1536
	global_store_short_d16_hi v[58:59], v47, off offset:1664
	v_pk_fma_f32 v[40:41], v[54:55], v[44:45], v[40:41]
	s_nop 0
	v_mul_f32_e32 v42, 0xbfb8aa3b, v40
	v_mul_f32_e32 v43, 0xbfb8aa3b, v41
	v_exp_f32_e32 v42, v42
	v_exp_f32_e32 v43, v43
	s_nop 0
	v_pk_add_f32 v[42:43], v[42:43], 1.0 op_sel_hi:[1,0]
	s_nop 0
	s_nop 0
	v_rcp_f32_e32 v44, v43
	s_nop 0
	v_mul_f32_e32 v41, v41, v44
	s_nop 0
	v_rcp_f32_e32 v43, v42
	s_nop 0
	v_mul_f32_e32 v40, v40, v43
	v_lshlrev_b32_e32 v42, 16, v104
	v_lshlrev_b32_e32 v43, 16, v105
	v_lshlrev_b32_e32 v44, 16, v103
	v_lshlrev_b32_e32 v45, 16, v108
	v_pk_mul_f32 v[44:45], v[10:11], v[44:45]
	v_lshlrev_b32_e32 v50, 16, v102
	v_lshlrev_b32_e32 v51, 16, v109
	v_pk_mul_f32 v[36:37], v[36:37], v[42:43]
	v_pk_mul_f32 v[50:51], v[8:9], v[50:51]
	v_pk_fma_f32 v[34:35], v[44:45], v[34:35], v[36:37]
	s_nop 0
	v_pk_fma_f32 v[34:35], v[50:51], v[38:39], v[34:35]
	s_nop 0
	v_mul_f32_e32 v9, 0xbfb8aa3b, v34
	v_exp_f32_e32 v36, v9
	v_mul_f32_e32 v9, 0xbfb8aa3b, v35
	v_exp_f32_e32 v37, v9
	s_nop 0
	v_pk_add_f32 v[36:37], v[36:37], 1.0 op_sel_hi:[1,0]
	s_nop 0
	s_nop 0
	v_rcp_f32_e32 v9, v37
	s_nop 0
	v_mul_f32_e32 v35, v35, v9
	s_nop 0
	v_rcp_f32_e32 v9, v36
	s_nop 0
	v_mul_f32_e32 v34, v34, v9
	v_lshlrev_b32_e32 v9, 16, v96
	v_lshlrev_b32_e32 v11, 16, v97
; __device__ __forceinline__ float bf2f(u16 v) { return __uint_as_float(((unsigned)v) << 16); }
; __device__ __forceinline__ float siluf_(float x) { return x / (1.f + __expf(-x)); }
; __device__ void phase_gdnprep(const P& p, int l, float* lds) {
;     ...
;         float xc = bf2f((u16)rc[g8 * 8 + j]), xl = bf2f((u16)rl[g8 * 8 + j]) * ml, xr = bf2f((u16)rr[g8 * 8 + j]) * mr;
;         x[g8 * 8 + j] = siluf_(xl * w0[j] + xc * w1[j] + xr * w2[j]);
;     ...
;     for (int hh = 0; hh < 4; ++hh) {
;       float qs = wave_sum_b(x[2 * hh] * x[2 * hh] + x[2 * hh + 1] * x[2 * hh + 1]);
;       float ks = wave_sum_b(x[8 + 2 * hh] * x[8 + 2 * hh] + x[8 + 2 * hh + 1] * x[8 + 2 * hh + 1]);
;       float qn = rsqrtf(qs + 1e-6f) * 0.08838834764831845f, kn = rsqrtf(ks + 1e-6f);
;       u16 q0b = f2bf(x[2 * hh] * qn), q1b = f2bf(x[2 * hh + 1] * qn), k0b = f2bf(x[8 + 2 * hh] * kn), k1b = f2bf(x[8 + 2 * hh + 1] * kn);
;       float kqd = wave_sum_b(bf2f(k0b) * bf2f(q0b) + bf2f(k1b) * bf2f(q1b));
;       float kql = wave_sum_b(bf2f((u16)glq[hh]) * 0.125f * bf2f((u16)glk[hh]));
;       if (lane == 0) { p.kqa[(size_t)row * 8 + hh] = kqd; p.kqa[(size_t)row * 8 + 4 + hh] = kql; }
;       dst[(2 * hh) * 64 + lane] = q0b; dst[(2 * hh + 1) * 64 + lane] = q1b;
;       dst[512 + (2 * hh) * 64 + lane] = k0b; dst[512 + (2 * hh + 1) * 64 + lane] = k1b;
;       dst[1024 + (2 * hh) * 64 + lane] = f2bf(x[16 + 2 * hh]); dst[1024 + (2 * hh + 1) * 64 + lane] = f2bf(x[16 + 2 * hh + 1]);
;     }
	v_mul_f32_e32 v11, v10, v11
	v_lshlrev_b32_e32 v36, 16, v95
	v_mul_f32_e32 v9, v124, v9
	v_mul_f32_e32 v36, v8, v36
	v_fmac_f32_e32 v9, v11, v119
	v_fmac_f32_e32 v9, v36, v128
	v_mul_f32_e32 v11, 0xbfb8aa3b, v9
	v_exp_f32_e32 v11, v11
	s_nop 0
	v_add_f32_e32 v11, 1.0, v11
	s_nop 0
	v_rcp_f32_e32 v36, v11
	s_nop 0
	v_mul_f32_e32 v9, v9, v36
	v_lshlrev_b32_e32 v11, 16, v93
	v_lshlrev_b32_e32 v36, 16, v94
	v_mul_f32_e32 v36, v10, v36
	v_lshlrev_b32_e32 v37, 16, v92
	v_mul_f32_e32 v11, v118, v11
	v_mul_f32_e32 v37, v8, v37
	v_fmac_f32_e32 v11, v36, v117
	v_fmac_f32_e32 v11, v37, v120
	v_mul_f32_e32 v36, 0xbfb8aa3b, v11
	v_exp_f32_e32 v36, v36
	s_nop 0
	v_add_f32_e32 v36, 1.0, v36
	s_nop 0
	v_rcp_f32_e32 v37, v36
	s_nop 0
	v_mul_f32_e32 v11, v11, v37
	v_bfe_u32 v36, v9, 16, 1
	v_add3_u32 v9, v9, v36, s21
	global_store_short_d16_hi v[58:59], v9, off offset:2560
	v_bfe_u32 v9, v11, 16, 1
	v_add3_u32 v9, v11, v9, s21
	v_pk_mul_f32 v[36:37], v[40:41], v[40:41]
	global_store_short_d16_hi v[58:59], v9, off offset:2688
	v_add_f32_e32 v9, v36, v37
	v_mov_b32_e32 v11, v129
	v_pk_mul_f32 v[36:37], v[34:35], v[34:35]
	v_add_f32_dpp v9, v9, v9 quad_perm:[1,0,3,2] row_mask:0xf bank_mask:0xf bound_ctrl:1
	s_nop 1
	v_add_f32_dpp v9, v9, v9 quad_perm:[2,3,0,1] row_mask:0xf bank_mask:0xf bound_ctrl:1
	s_nop 1
	v_add_f32_dpp v9, v9, v9 row_half_mirror row_mask:0xf bank_mask:0xf bound_ctrl:1
	s_nop 1
	v_add_f32_dpp v9, v9, v9 row_mirror row_mask:0xf bank_mask:0xf bound_ctrl:1
	s_nop 1
	v_mov_b32_dpp v11, v9 row_bcast:15 row_mask:0xa bank_mask:0xf
	v_add_f32_e32 v9, v9, v11
	v_mov_b32_e32 v11, v129
	s_nop 1
	v_mov_b32_dpp v11, v9 row_bcast:31 row_mask:0xc bank_mask:0xf
	v_add_f32_e32 v9, v9, v11
	v_mov_b32_e32 v11, v129
	v_readlane_b32 s0, v9, 63
	v_add_f32_e32 v9, v36, v37
	s_nop 1
	v_add_f32_dpp v9, v9, v9 quad_perm:[1,0,3,2] row_mask:0xf bank_mask:0xf bound_ctrl:1
	s_nop 1
	v_add_f32_dpp v9, v9, v9 quad_perm:[2,3,0,1] row_mask:0xf bank_mask:0xf bound_ctrl:1
	s_nop 1
	v_add_f32_dpp v9, v9, v9 row_half_mirror row_mask:0xf bank_mask:0xf bound_ctrl:1
	s_nop 1
	v_add_f32_dpp v9, v9, v9 row_mirror row_mask:0xf bank_mask:0xf bound_ctrl:1
	s_nop 1
	v_mov_b32_dpp v11, v9 row_bcast:15 row_mask:0xa bank_mask:0xf
	v_add_f32_e32 v9, v9, v11
	v_mov_b32_e32 v11, v129
	s_nop 1
	v_mov_b32_dpp v11, v9 row_bcast:31 row_mask:0xc bank_mask:0xf
	v_add_f32_e32 v9, v9, v11
	s_nop 0
	v_readlane_b32 s1, v9, 63
	v_add_f32_e32 v9, s0, v169
	s_mov_b32 s0, 0x800000
	v_cmp_gt_f32_e32 vcc, s0, v9
	v_mul_f32_e32 v11, 0x4b800000, v9
	s_nop 0
	v_cndmask_b32_e32 v9, v9, v11, vcc
	v_rsq_f32_e32 v9, v9
	s_nop 0
	v_mul_f32_e32 v11, 0x45800000, v9
	v_cndmask_b32_e32 v9, v9, v11, vcc
	v_mul_f32_e32 v11, 0x3db504f3, v9
	v_add_f32_e32 v9, s1, v169
	v_cmp_gt_f32_e32 vcc, s0, v9
	v_mul_f32_e32 v36, 0x4b800000, v9
	s_nop 0
	v_cndmask_b32_e32 v9, v9, v36, vcc
	v_rsq_f32_e32 v9, v9
	s_nop 0
	v_mul_f32_e32 v36, 0x45800000, v9
	v_cndmask_b32_e32 v36, v9, v36, vcc
	v_mul_f32_e32 v9, v40, v11
	v_bfe_u32 v37, v9, 16, 1
	v_mul_f32_e32 v11, v41, v11
	v_mul_f32_e32 v35, v35, v36
	v_add3_u32 v9, v9, v37, s21
	v_bfe_u32 v37, v11, 16, 1
	v_mul_f32_e32 v34, v34, v36
	v_bfe_u32 v36, v35, 16, 1
	v_add3_u32 v11, v11, v37, s21
	v_bfe_u32 v37, v34, 16, 1
	v_add3_u32 v35, v35, v36, s21
	v_add3_u32 v34, v34, v37, s21
	v_and_b32_e32 v38, 0xffff0000, v35
	v_and_b32_e32 v39, 0xffff0000, v11
	v_and_b32_e32 v36, 0xffff0000, v34
	v_and_b32_e32 v37, 0xffff0000, v9
	v_mul_f32_e32 v38, v39, v38
	v_fmac_f32_e32 v38, v37, v36
	v_mov_b32_e32 v37, v129
	s_nop 0
	v_add_f32_dpp v36, v38, v38 quad_perm:[1,0,3,2] row_mask:0xf bank_mask:0xf bound_ctrl:1
	s_nop 1
	v_add_f32_dpp v36, v36, v36 quad_perm:[2,3,0,1] row_mask:0xf bank_mask:0xf bound_ctrl:1
	s_nop 1
	v_add_f32_dpp v36, v36, v36 row_half_mirror row_mask:0xf bank_mask:0xf bound_ctrl:1
	s_nop 1
	v_add_f32_dpp v36, v36, v36 row_mirror row_mask:0xf bank_mask:0xf bound_ctrl:1
	s_nop 1
	v_mov_b32_dpp v37, v36 row_bcast:15 row_mask:0xa bank_mask:0xf
	v_add_f32_e32 v36, v36, v37
	v_mov_b32_e32 v37, v129
	s_nop 1
	v_mov_b32_dpp v37, v36 row_bcast:31 row_mask:0xc bank_mask:0xf
	v_add_f32_e32 v36, v36, v37
	v_lshlrev_b32_e32 v37, 16, v91
	v_readlane_b32 s2, v36, 63
	v_lshlrev_b32_e32 v36, 16, v90
	v_mul_f32_e32 v36, 0x3e000000, v36
	v_mul_f32_e32 v38, v36, v37
	s_nop 1
	v_mov_b32_dpp v38, v38 quad_perm:[1,0,3,2] row_mask:0xf bank_mask:0xf bound_ctrl:1
	v_fmac_f32_e32 v38, v36, v37
	v_mov_b32_e32 v37, v129
	s_nop 0
	v_add_f32_dpp v36, v38, v38 quad_perm:[2,3,0,1] row_mask:0xf bank_mask:0xf bound_ctrl:1
	s_nop 1
	v_add_f32_dpp v36, v36, v36 row_half_mirror row_mask:0xf bank_mask:0xf bound_ctrl:1
	s_nop 1
	v_add_f32_dpp v36, v36, v36 row_mirror row_mask:0xf bank_mask:0xf bound_ctrl:1
	s_nop 1
	v_mov_b32_dpp v37, v36 row_bcast:15 row_mask:0xa bank_mask:0xf
	v_add_f32_e32 v36, v36, v37
	v_mov_b32_e32 v37, v129
	s_nop 1
	v_mov_b32_dpp v37, v36 row_bcast:31 row_mask:0xc bank_mask:0xf
	v_add_f32_e32 v36, v36, v37
	s_nop 0
	v_readlane_b32 s3, v36, 63
	s_and_saveexec_b64 s[0:1], s[40:41]
	s_cbranch_execz .LBB0_344
	v_mov_b32_e32 v36, s2
	global_store_dword v[70:71], v36, off offset:12
	v_mov_b32_e32 v36, s3
	global_store_dword v[70:71], v36, off offset:28
	s_branch .LBB0_344

; __device__ __forceinline__ float siluf_(float x) { return x / (1.f + __expf(-x)); }
; __device__ void phase_mod(const P& p, float* lds) {
;     ...
;   for (int e = tid; e < 5 * D; e += NTHR) {
;     int cnd = e / D, k = e % D;
;     float v = cnd < 4 ? p.c[cnd * D + k] : p.c_ctx[k];
;     scond[e] = siluf_(v);
;   }
.LBB0_381:
	s_or_b64 exec, exec, s[36:37]
	global_load_dword v0, v[0:1], off
	s_movk_i32 s20, 0x25ff
	v_add_u32_e32 v4, 0x200, v3
	v_cmp_lt_i32_e32 vcc, s20, v3
	s_or_b64 s[2:3], vcc, s[2:3]
	s_waitcnt vmcnt(0)
	v_mul_f32_e32 v1, 0xbfb8aa3b, v0
	v_exp_f32_e32 v1, v1
	s_nop 0
	v_add_f32_e32 v1, 1.0, v1
	v_rcp_f32_e32 v3, v1
	s_nop 0
	v_mul_f32_e32 v0, v0, v3
	ds_write_b32 v2, v0
	v_add_u32_e32 v2, 0x800, v2
	v_mov_b32_e32 v3, v4
	s_andn2_b64 exec, exec, s[2:3]
	s_cbranch_execz .LBB0_386
